# v50 plus early A-quarter prefetch in all six GEMM unit loops: next unit As[1][1] staged at the epilogue entry (before the epilogue stores); second peeled first-iteration copy without that stage, first
# speedup vs baseline: 1.0089x; 1.0047x over previous
; #define PG8_STAGE(bufoff, gbase, voff) do { _Pragma("unroll") for (int _i = 0; _i < 2; ++_i) \
;         __builtin_amdgcn_global_load_lds((const unsigned*)((const char*)(gbase) + (voff)[_i]), (PG8_LAS unsigned*)(lds + (bufoff) + ldsw + _i * 8192), 16, 0, 0); } while (0)
; #define PG8_LDA(dst, b, h) do { _Pragma("unroll") for (int m = 0; m < 4; ++m) _Pragma("unroll") for (int k = 0; k < 2; ++k) dst[m][k] = *(const PG8_LAS bf16x8*)(lds + PG8_SA(b, h) + aoff + m * 2048 + k * 1024); } while (0)
; #define PG8_LDB(dst, b, h) do { _Pragma("unroll") for (int n = 0; n < 2; ++n) _Pragma("unroll") for (int k = 0; k < 2; ++k) dst[n][k] = *(const PG8_LAS bf16x8*)(lds + PG8_SB(b, h) + boff + n * 2048 + k * 1024); } while (0)
; #define PG8_WAIT_V(n) asm volatile("s_waitcnt vmcnt(" #n ")" ::: "memory")
; #define PG8_WAIT_L(n) asm volatile("s_waitcnt lgkmcnt(" #n ")" ::: "memory")
; #define PG8_BAR __builtin_amdgcn_s_barrier()
; template <class Epi, class Sched, bool ALIGN_EPI = false, bool SP2 = false>
; __device__ __forceinline__ void gemm_phase(PG8_LAS unsigned char* lds, const Gemm g, const Sched& S, const Epi& E, const int wv  ) {
;     ...
;         const bool has_next = S.next(ui + 1, nxt);
;         const char* nA = has_next ? (const char*)g.A + (size_t)nxt.pm * tstep : cA; const char* nB = has_next ? (const char*)g.Bt + (size_t)nxt.pn * tstep : cB;
;         for (int t = 0; t < nt; t += 2) {
;             const bool last = (t == nt - 2);
;             const char* a1 = cA + (size_t)(t + 1) * kstep;
;             const char* a2 = last ? nA : cA + (size_t)(t + 2) * kstep; const char* b2 = last ? nB : cB + (size_t)(t + 2) * kstep;
;             const char* a3 = a2 + kstep; const char* b3 = b2 + kstep;
;             if (last && has_next) S.a_ready(nxt);
;             if constexpr (SP2) {
;             PG8_LDB(B0, 0, 0); PG8_LDB(B1, 0, 1); PG8_SCHED; PG8_LDA(At, 0, 0); PG8_STAGE(PG8_SA(1, 1), a1 + hstep, voffA);
;             PG8_WAIT_V(8); PG8_WAIT_L(0); PG8_BAR; PG8_MMA(0, 0, At, B0); PG8_MMA(0, 1, At, B1); PG8_BAR; PG8_SCHED;
;     ...
; #pragma unroll
;         for (int a = 0; a < 2; ++a)
; #pragma unroll
;             for (int b = 0; b < 2; ++b)
; #pragma unroll
;                 for (int m = 0; m < 4; ++m)
; #pragma unroll
;                     for (int n = 0; n < 2; ++n) acc[a][b][m][n] = (f32x4){0.f, 0.f, 0.f, 0.f};
;         cur = nxt; cA = nA; cB = nB; ++ui;
.LBB0_259:
	s_ashr_i32 s53, s52, 31
	s_lshl_b64 s[2:3], s[52:53], 19
	s_add_u32 s54, s36, s2
	s_addc_u32 s55, s37, s3
	s_and_b64 s[2:3], s[10:11], exec
	s_cselect_b32 s2, s55, s1
	s_cselect_b32 s3, s54, s0
	s_ashr_i32 s51, s50, 31
	s_lshl_b64 s[14:15], s[50:51], 19
	s_add_u32 s56, s38, s14
	s_addc_u32 s57, s39, s15
	s_and_b64 s[14:15], s[10:11], exec
	s_cselect_b32 s17, s57, s13
	s_cselect_b32 s18, s56, s12
	s_add_u32 s0, s0, 0x40080
	s_addc_u32 s1, s1, 0
	s_add_u32 s19, s12, 0x100
	v_mov_b32_e32 v0, 0
	s_addc_u32 s33, s13, 0
	s_mov_b32 s34, -2
	v_mov_b32_e32 v1, v0
	v_mov_b32_e32 v2, v0
	v_mov_b32_e32 v3, v0
	v_mov_b32_e32 v4, v0
	v_mov_b32_e32 v5, v0
	v_mov_b32_e32 v6, v0
	v_mov_b32_e32 v7, v0
	v_mov_b32_e32 v16, v0
	v_mov_b32_e32 v17, v0
	v_mov_b32_e32 v18, v0
	v_mov_b32_e32 v19, v0
	v_mov_b32_e32 v20, v0
	v_mov_b32_e32 v21, v0
	v_mov_b32_e32 v22, v0
	v_mov_b32_e32 v23, v0
	v_mov_b32_e32 v32, v0
	v_mov_b32_e32 v33, v0
	v_mov_b32_e32 v34, v0
	v_mov_b32_e32 v35, v0
	v_mov_b32_e32 v36, v0
	v_mov_b32_e32 v37, v0
	v_mov_b32_e32 v38, v0
	v_mov_b32_e32 v39, v0
	v_mov_b32_e32 v64, v0
	v_mov_b32_e32 v65, v0
	v_mov_b32_e32 v66, v0
	v_mov_b32_e32 v67, v0
	v_mov_b32_e32 v68, v0
	v_mov_b32_e32 v69, v0
	v_mov_b32_e32 v70, v0
	v_mov_b32_e32 v71, v0
	v_mov_b32_e32 v8, v0
	v_mov_b32_e32 v9, v0
	v_mov_b32_e32 v10, v0
	v_mov_b32_e32 v11, v0
	v_mov_b32_e32 v12, v0
	v_mov_b32_e32 v13, v0
	v_mov_b32_e32 v14, v0
	v_mov_b32_e32 v15, v0
	v_mov_b32_e32 v24, v0
	v_mov_b32_e32 v25, v0
	v_mov_b32_e32 v26, v0
	v_mov_b32_e32 v27, v0
	v_mov_b32_e32 v28, v0
	v_mov_b32_e32 v29, v0
	v_mov_b32_e32 v30, v0
	v_mov_b32_e32 v31, v0
	v_mov_b32_e32 v40, v0
	v_mov_b32_e32 v41, v0
	v_mov_b32_e32 v42, v0
	v_mov_b32_e32 v43, v0
	v_mov_b32_e32 v44, v0
	v_mov_b32_e32 v45, v0
	v_mov_b32_e32 v46, v0
	v_mov_b32_e32 v47, v0
	v_mov_b32_e32 v72, v0
	v_mov_b32_e32 v73, v0
	v_mov_b32_e32 v74, v0
	v_mov_b32_e32 v75, v0
	v_mov_b32_e32 v80, v0
	v_mov_b32_e32 v81, v0
	v_mov_b32_e32 v82, v0
	v_mov_b32_e32 v83, v0
	v_mov_b32_e32 v104, v0
	v_mov_b32_e32 v105, v0
	v_mov_b32_e32 v106, v0
	v_mov_b32_e32 v107, v0
	v_mov_b32_e32 v108, v0
	v_mov_b32_e32 v109, v0
	v_mov_b32_e32 v110, v0
	v_mov_b32_e32 v111, v0
	v_mov_b32_e32 v136, v0
	v_mov_b32_e32 v137, v0
	v_mov_b32_e32 v138, v0
	v_mov_b32_e32 v139, v0
	v_mov_b32_e32 v140, v0
	v_mov_b32_e32 v141, v0
	v_mov_b32_e32 v142, v0
	v_mov_b32_e32 v143, v0
	v_mov_b32_e32 v160, v0
	v_mov_b32_e32 v161, v0
	v_mov_b32_e32 v162, v0
	v_mov_b32_e32 v163, v0
	v_mov_b32_e32 v164, v0
	v_mov_b32_e32 v165, v0
	v_mov_b32_e32 v166, v0
	v_mov_b32_e32 v167, v0
	v_mov_b32_e32 v176, v0
	v_mov_b32_e32 v177, v0
	v_mov_b32_e32 v178, v0
	v_mov_b32_e32 v179, v0
	v_mov_b32_e32 v180, v0
	v_mov_b32_e32 v181, v0
	v_mov_b32_e32 v182, v0
	v_mov_b32_e32 v183, v0
	v_mov_b32_e32 v112, v0
	v_mov_b32_e32 v113, v0
	v_mov_b32_e32 v114, v0
	v_mov_b32_e32 v115, v0
	v_mov_b32_e32 v116, v0
	v_mov_b32_e32 v117, v0
	v_mov_b32_e32 v118, v0
	v_mov_b32_e32 v119, v0
	v_mov_b32_e32 v148, v0
	v_mov_b32_e32 v149, v0
	v_mov_b32_e32 v150, v0
	v_mov_b32_e32 v151, v0
	v_mov_b32_e32 v156, v0
	v_mov_b32_e32 v157, v0
	v_mov_b32_e32 v158, v0
	v_mov_b32_e32 v159, v0
	v_mov_b32_e32 v168, v0
	v_mov_b32_e32 v169, v0
	v_mov_b32_e32 v170, v0
	v_mov_b32_e32 v171, v0
	v_mov_b32_e32 v172, v0
	v_mov_b32_e32 v173, v0
	v_mov_b32_e32 v174, v0
	v_mov_b32_e32 v175, v0
	v_mov_b32_e32 v184, v0
	v_mov_b32_e32 v185, v0
	v_mov_b32_e32 v186, v0
	v_mov_b32_e32 v187, v0
	v_mov_b32_e32 v188, v0
	v_mov_b32_e32 v189, v0
	v_mov_b32_e32 v190, v0
	v_mov_b32_e32 v191, v0
	s_cmp_eq_u32 s63, 1
	s_cbranch_scc1 .LBB0_260
	ds_read_b128 v[48:51], v243
	ds_read_b128 v[52:55], v243 offset:1024
	ds_read_b128 v[56:59], v243 offset:2048
	ds_read_b128 v[60:63], v243 offset:3072
	ds_read_b128 v[76:79], v244
	ds_read_b128 v[84:87], v244 offset:1024
	ds_read_b128 v[88:91], v244 offset:2048
	ds_read_b128 v[92:95], v244 offset:3072
	s_add_u32 s12, s0, 0xfffc0080
	s_addc_u32 s13, s1, -1
	s_cmp_eq_u32 s34, 12
	s_cselect_b32 s15, s2, s13
	s_cselect_b32 s14, s3, s12
	s_cselect_b32 s13, s17, s33
	s_cselect_b32 s12, s18, s19
	ds_read_b128 v[96:99], v245
	ds_read_b128 v[100:103], v245 offset:1024
	ds_read_b128 v[120:123], v245 offset:2048
	ds_read_b128 v[124:127], v245 offset:3072
	ds_read_b128 v[128:131], v245 offset:4096
	ds_read_b128 v[132:135], v245 offset:5120
	ds_read_b128 v[144:147], v245 offset:6144
	ds_read_b128 v[152:155], v245 offset:7168
	s_waitcnt vmcnt(24)
	s_waitcnt lgkmcnt(0)
	s_barrier
	s_setprio 1
	s_waitcnt lgkmcnt(0)
	v_mfma_f32_16x16x32_bf16 v[188:191], v[48:51], v[96:99], v[188:191]
	v_mfma_f32_16x16x32_bf16 v[184:187], v[56:59], v[96:99], v[184:187]
	v_mfma_f32_16x16x32_bf16 v[172:175], v[48:51], v[120:123], v[172:175]
	v_mfma_f32_16x16x32_bf16 v[168:171], v[56:59], v[120:123], v[168:171]
	v_mfma_f32_16x16x32_bf16 v[156:159], v[48:51], v[128:131], v[156:159]
	v_mfma_f32_16x16x32_bf16 v[148:151], v[56:59], v[128:131], v[148:151]
	v_mfma_f32_16x16x32_bf16 v[116:119], v[48:51], v[144:147], v[116:119]
	v_mfma_f32_16x16x32_bf16 v[112:115], v[56:59], v[144:147], v[112:115]
	v_mfma_f32_16x16x32_bf16 v[188:191], v[52:55], v[100:103], v[188:191]
	v_mfma_f32_16x16x32_bf16 v[184:187], v[60:63], v[100:103], v[184:187]
	v_mfma_f32_16x16x32_bf16 v[172:175], v[52:55], v[124:127], v[172:175]
	v_mfma_f32_16x16x32_bf16 v[168:171], v[60:63], v[124:127], v[168:171]
	v_mfma_f32_16x16x32_bf16 v[156:159], v[52:55], v[132:135], v[156:159]
	v_mfma_f32_16x16x32_bf16 v[148:151], v[60:63], v[132:135], v[148:151]
	v_mfma_f32_16x16x32_bf16 v[116:119], v[52:55], v[152:155], v[116:119]
	v_mfma_f32_16x16x32_bf16 v[112:115], v[60:63], v[152:155], v[112:115]
	s_setprio 0
	s_setprio 1
	v_mfma_f32_16x16x32_bf16 v[180:183], v[76:79], v[96:99], v[180:183]
	v_mfma_f32_16x16x32_bf16 v[96:99], v[88:91], v[96:99], v[176:179]
	v_mfma_f32_16x16x32_bf16 v[180:183], v[84:87], v[100:103], v[180:183]
	v_mfma_f32_16x16x32_bf16 v[96:99], v[92:95], v[100:103], v[96:99]
	v_mfma_f32_16x16x32_bf16 v[100:103], v[76:79], v[120:123], v[164:167]
	v_mfma_f32_16x16x32_bf16 v[120:123], v[88:91], v[120:123], v[160:163]
	v_mfma_f32_16x16x32_bf16 v[108:111], v[76:79], v[144:147], v[108:111]
	v_mfma_f32_16x16x32_bf16 v[104:107], v[88:91], v[144:147], v[104:107]
	v_mfma_f32_16x16x32_bf16 v[100:103], v[84:87], v[124:127], v[100:103]
	v_mfma_f32_16x16x32_bf16 v[120:123], v[92:95], v[124:127], v[120:123]
	v_mfma_f32_16x16x32_bf16 v[124:127], v[76:79], v[128:131], v[140:143]
	v_mfma_f32_16x16x32_bf16 v[128:131], v[88:91], v[128:131], v[136:139]
	v_mfma_f32_16x16x32_bf16 v[108:111], v[84:87], v[152:155], v[108:111]
	v_mfma_f32_16x16x32_bf16 v[104:107], v[92:95], v[152:155], v[104:107]
	v_mfma_f32_16x16x32_bf16 v[124:127], v[84:87], v[132:135], v[124:127]
	v_mfma_f32_16x16x32_bf16 v[128:131], v[92:95], v[132:135], v[128:131]
	s_setprio 0
	s_barrier
; #define PG8_STAGE(bufoff, gbase, voff) do { _Pragma("unroll") for (int _i = 0; _i < 2; ++_i) \
;         __builtin_amdgcn_global_load_lds((const unsigned*)((const char*)(gbase) + (voff)[_i]), (PG8_LAS unsigned*)(lds + (bufoff) + ldsw + _i * 8192), 16, 0, 0); } while (0)
; #define PG8_LDA(dst, b, h) do { _Pragma("unroll") for (int m = 0; m < 4; ++m) _Pragma("unroll") for (int k = 0; k < 2; ++k) dst[m][k] = *(const PG8_LAS bf16x8*)(lds + PG8_SA(b, h) + aoff + m * 2048 + k * 1024); } while (0)
; #define PG8_LDB(dst, b, h) do { _Pragma("unroll") for (int n = 0; n < 2; ++n) _Pragma("unroll") for (int k = 0; k < 2; ++k) dst[n][k] = *(const PG8_LAS bf16x8*)(lds + PG8_SB(b, h) + boff + n * 2048 + k * 1024); } while (0)
; #define PG8_MMA(ai, bj, At, Bt) do { __builtin_amdgcn_s_setprio(1); _Pragma("unroll") for (int m = 0; m < 4; ++m) _Pragma("unroll") for (int n = 0; n < 2; ++n) _Pragma("unroll") for (int k = 0; k < 2; ++k) \
;         acc[ai][bj][m][n] = __builtin_amdgcn_mfma_f32_16x16x32_bf16(Bt[n][k], At[m][k], acc[ai][bj][m][n], 0, 0, 0); __builtin_amdgcn_s_setprio(0); } while (0)
; #define PG8_WAIT_V(n) asm volatile("s_waitcnt vmcnt(" #n ")" ::: "memory")
; #define PG8_WAIT_L(n) asm volatile("s_waitcnt lgkmcnt(" #n ")" ::: "memory")
; #define PG8_BAR __builtin_amdgcn_s_barrier()
; #define PG8_SCHED __builtin_amdgcn_sched_barrier(0)
; template <class Epi, class Sched, bool ALIGN_EPI = false, bool SP2 = false>
; __device__ __forceinline__ void gemm_phase(PG8_LAS unsigned char* lds, const Gemm g, const Sched& S, const Epi& E, const int wv  ) {
;     ...
;             PG8_LDB(B0, 0, 0); PG8_LDB(B1, 0, 1); PG8_SCHED; PG8_LDA(At, 0, 0); PG8_STAGE(PG8_SA(1, 1), a1 + hstep, voffA);
;             PG8_WAIT_V(8); PG8_WAIT_L(0); PG8_BAR; PG8_MMA(0, 0, At, B0); PG8_MMA(0, 1, At, B1); PG8_BAR; PG8_SCHED;
;             PG8_LDA(At, 0, 1); PG8_STAGE(PG8_SB(0, 0), b2, voffB); PG8_STAGE(PG8_SB(0, 1), b2 + hstep, voffB); PG8_STAGE(PG8_SA(0, 0), a2, voffA);
;             PG8_WAIT_V(8); PG8_WAIT_L(0); PG8_BAR; PG8_MMA(1, 0, At, B0); PG8_MMA(1, 1, At, B1); PG8_BAR; PG8_SCHED;
;             PG8_LDB(B0, 1, 0); PG8_LDB(B1, 1, 1); PG8_SCHED; PG8_LDA(At, 1, 0); PG8_STAGE(PG8_SA(0, 1), a2 + hstep, voffA);
	s_add_i32 s49, s78, s21
	v_lshl_add_u64 v[222:223], s[12:13], 0, v[194:195]
	s_mov_b32 m0, s49
	ds_read_b128 v[132:135], v245 offset:16384
	ds_read_b128 v[136:139], v245 offset:17408
	ds_read_b128 v[140:143], v245 offset:18432
	ds_read_b128 v[144:147], v245 offset:19456
	ds_read_b128 v[152:155], v245 offset:20480
	ds_read_b128 v[160:163], v245 offset:21504
	ds_read_b128 v[164:167], v245 offset:22528
	ds_read_b128 v[176:179], v245 offset:23552
	global_load_lds_dwordx4 v[222:223], off
	s_add_i32 m0, s49, 0x2000
	s_add_u32 s58, s12, 0x40000
	v_lshl_add_u64 v[224:225], s[12:13], 0, v[198:199]
	s_addc_u32 s59, s13, 0
	s_add_i32 s49, s79, s21
	global_load_lds_dwordx4 v[224:225], off
	v_lshl_add_u64 v[208:209], s[58:59], 0, v[194:195]
	s_mov_b32 m0, s49
	v_lshl_add_u64 v[226:227], s[14:15], 0, v[192:193]
	global_load_lds_dwordx4 v[208:209], off
	v_lshl_add_u64 v[208:209], s[58:59], 0, v[198:199]
	s_add_i32 m0, s49, 0x2000
	v_lshl_add_u64 v[228:229], s[14:15], 0, v[196:197]
	global_load_lds_dwordx4 v[208:209], off
	s_mov_b32 m0, s25
	s_nop 0
	global_load_lds_dwordx4 v[226:227], off
	s_mov_b32 m0, s40
	s_nop 0
	global_load_lds_dwordx4 v[228:229], off
	s_waitcnt vmcnt(24)
	s_waitcnt lgkmcnt(0)
	s_barrier
	s_setprio 1
	s_waitcnt lgkmcnt(0)
	v_mfma_f32_16x16x32_bf16 v[80:83], v[48:51], v[132:135], v[80:83]
	v_mfma_f32_16x16x32_bf16 v[72:75], v[56:59], v[132:135], v[72:75]
	v_mfma_f32_16x16x32_bf16 v[44:47], v[48:51], v[140:143], v[44:47]
	v_mfma_f32_16x16x32_bf16 v[40:43], v[56:59], v[140:143], v[40:43]
	v_mfma_f32_16x16x32_bf16 v[28:31], v[48:51], v[152:155], v[28:31]
	v_mfma_f32_16x16x32_bf16 v[24:27], v[56:59], v[152:155], v[24:27]
	v_mfma_f32_16x16x32_bf16 v[12:15], v[48:51], v[164:167], v[12:15]
	v_mfma_f32_16x16x32_bf16 v[8:11], v[56:59], v[164:167], v[8:11]
	v_mfma_f32_16x16x32_bf16 v[80:83], v[52:55], v[136:139], v[80:83]
	v_mfma_f32_16x16x32_bf16 v[72:75], v[60:63], v[136:139], v[72:75]
	v_mfma_f32_16x16x32_bf16 v[44:47], v[52:55], v[144:147], v[44:47]
	v_mfma_f32_16x16x32_bf16 v[40:43], v[60:63], v[144:147], v[40:43]
	v_mfma_f32_16x16x32_bf16 v[28:31], v[52:55], v[160:163], v[28:31]
	v_mfma_f32_16x16x32_bf16 v[24:27], v[60:63], v[160:163], v[24:27]
	v_mfma_f32_16x16x32_bf16 v[12:15], v[52:55], v[176:179], v[12:15]
	v_mfma_f32_16x16x32_bf16 v[8:11], v[60:63], v[176:179], v[8:11]
	s_setprio 0
	s_setprio 1
	v_mfma_f32_16x16x32_bf16 v[36:39], v[76:79], v[140:143], v[36:39]
	v_mfma_f32_16x16x32_bf16 v[32:35], v[88:91], v[140:143], v[32:35]
	v_mfma_f32_16x16x32_bf16 v[20:23], v[76:79], v[152:155], v[20:23]
	v_mfma_f32_16x16x32_bf16 v[16:19], v[88:91], v[152:155], v[16:19]
	v_mfma_f32_16x16x32_bf16 v[4:7], v[76:79], v[164:167], v[4:7]
	v_mfma_f32_16x16x32_bf16 v[0:3], v[88:91], v[164:167], v[0:3]
	v_mfma_f32_16x16x32_bf16 v[48:51], v[76:79], v[132:135], v[68:71]
	v_mfma_f32_16x16x32_bf16 v[52:55], v[88:91], v[132:135], v[64:67]
	v_mfma_f32_16x16x32_bf16 v[36:39], v[84:87], v[144:147], v[36:39]
	v_mfma_f32_16x16x32_bf16 v[32:35], v[92:95], v[144:147], v[32:35]
	v_mfma_f32_16x16x32_bf16 v[20:23], v[84:87], v[160:163], v[20:23]
	v_mfma_f32_16x16x32_bf16 v[16:19], v[92:95], v[160:163], v[16:19]
	v_mfma_f32_16x16x32_bf16 v[4:7], v[84:87], v[176:179], v[4:7]
	v_mfma_f32_16x16x32_bf16 v[0:3], v[92:95], v[176:179], v[0:3]
	v_mfma_f32_16x16x32_bf16 v[48:51], v[84:87], v[136:139], v[48:51]
	v_mfma_f32_16x16x32_bf16 v[52:55], v[92:95], v[136:139], v[52:55]
	s_setprio 0
	s_barrier
	s_add_i32 s49, 0, 0x18000
	s_add_i32 s51, 0, 0x1c000
	v_add_u32_e32 v68, s49, v234
	v_add_u32_e32 v92, s51, v234
	ds_read_b128 v[56:59], v68
	ds_read_b128 v[60:63], v68 offset:1024
	ds_read_b128 v[64:67], v68 offset:2048
	ds_read_b128 v[68:71], v68 offset:3072
	ds_read_b128 v[76:79], v92
	ds_read_b128 v[84:87], v92 offset:1024
	ds_read_b128 v[88:91], v92 offset:2048
	ds_read_b128 v[92:95], v92 offset:3072
	s_add_u32 s14, s14, 0x40000
	s_addc_u32 s15, s15, 0
	s_mov_b32 m0, s41
	v_lshl_add_u64 v[160:161], s[14:15], 0, v[192:193]
	ds_read_b128 v[132:135], v245 offset:32768
	ds_read_b128 v[136:139], v245 offset:33792
	ds_read_b128 v[140:143], v245 offset:34816
	ds_read_b128 v[144:147], v245 offset:35840
	ds_read_b128 v[152:155], v245 offset:36864
	ds_read_b128 v[208:211], v245 offset:37888
	ds_read_b128 v[214:217], v245 offset:38912
	ds_read_b128 v[218:221], v245 offset:39936
	global_load_lds_dwordx4 v[160:161], off
	v_lshl_add_u64 v[160:161], s[14:15], 0, v[196:197]
	s_mov_b32 m0, s62
	s_nop 0
	global_load_lds_dwordx4 v[160:161], off
	s_waitcnt vmcnt(24)
	s_waitcnt lgkmcnt(0)
	s_barrier
; #define PG8_STAGE(bufoff, gbase, voff) do { _Pragma("unroll") for (int _i = 0; _i < 2; ++_i) \
;         __builtin_amdgcn_global_load_lds((const unsigned*)((const char*)(gbase) + (voff)[_i]), (PG8_LAS unsigned*)(lds + (bufoff) + ldsw + _i * 8192), 16, 0, 0); } while (0)
; #define PG8_LDA(dst, b, h) do { _Pragma("unroll") for (int m = 0; m < 4; ++m) _Pragma("unroll") for (int k = 0; k < 2; ++k) dst[m][k] = *(const PG8_LAS bf16x8*)(lds + PG8_SA(b, h) + aoff + m * 2048 + k * 1024); } while (0)
; #define PG8_LDB(dst, b, h) do { _Pragma("unroll") for (int n = 0; n < 2; ++n) _Pragma("unroll") for (int k = 0; k < 2; ++k) dst[n][k] = *(const PG8_LAS bf16x8*)(lds + PG8_SB(b, h) + boff + n * 2048 + k * 1024); } while (0)
; #define PG8_MMA(ai, bj, At, Bt) do { __builtin_amdgcn_s_setprio(1); _Pragma("unroll") for (int m = 0; m < 4; ++m) _Pragma("unroll") for (int n = 0; n < 2; ++n) _Pragma("unroll") for (int k = 0; k < 2; ++k) \
;         acc[ai][bj][m][n] = __builtin_amdgcn_mfma_f32_16x16x32_bf16(Bt[n][k], At[m][k], acc[ai][bj][m][n], 0, 0, 0); __builtin_amdgcn_s_setprio(0); } while (0)
; #define PG8_WAIT_V(n) asm volatile("s_waitcnt vmcnt(" #n ")" ::: "memory")
; #define PG8_WAIT_L(n) asm volatile("s_waitcnt lgkmcnt(" #n ")" ::: "memory")
; #define PG8_BAR __builtin_amdgcn_s_barrier()
; #define PG8_SCHED __builtin_amdgcn_sched_barrier(0)
; template <class Epi, class Sched, bool ALIGN_EPI = false, bool SP2 = false>
; __device__ __forceinline__ void gemm_phase(PG8_LAS unsigned char* lds, const Gemm g, const Sched& S, const Epi& E, const int wv  ) {
;     ...
;             PG8_LDB(B0, 1, 0); PG8_LDB(B1, 1, 1); PG8_SCHED; PG8_LDA(At, 1, 0); PG8_STAGE(PG8_SA(0, 1), a2 + hstep, voffA);
;             PG8_WAIT_V(8); PG8_WAIT_L(0); PG8_BAR; PG8_MMA(0, 0, At, B0); PG8_MMA(0, 1, At, B1); PG8_BAR; PG8_SCHED;
;             PG8_LDA(At, 1, 1); PG8_STAGE(PG8_SB(1, 0), b3, voffB); PG8_STAGE(PG8_SB(1, 1), b3 + hstep, voffB); PG8_STAGE(PG8_SA(1, 0), a3, voffA);
;             PG8_WAIT_V(8); PG8_WAIT_L(0); PG8_BAR; PG8_MMA(1, 0, At, B0); PG8_MMA(1, 1, At, B1); PG8_BAR; PG8_SCHED;
	s_setprio 1
	s_waitcnt lgkmcnt(0)
	v_mfma_f32_16x16x32_bf16 v[160:163], v[56:59], v[132:135], v[188:191]
	v_mfma_f32_16x16x32_bf16 v[188:191], v[60:63], v[136:139], v[160:163]
	v_mfma_f32_16x16x32_bf16 v[160:163], v[64:67], v[132:135], v[184:187]
	v_mfma_f32_16x16x32_bf16 v[184:187], v[68:71], v[136:139], v[160:163]
	v_mfma_f32_16x16x32_bf16 v[160:163], v[56:59], v[140:143], v[172:175]
	v_mfma_f32_16x16x32_bf16 v[172:175], v[60:63], v[144:147], v[160:163]
	v_mfma_f32_16x16x32_bf16 v[160:163], v[64:67], v[140:143], v[168:171]
	v_mfma_f32_16x16x32_bf16 v[156:159], v[56:59], v[152:155], v[156:159]
	v_mfma_f32_16x16x32_bf16 v[148:151], v[64:67], v[152:155], v[148:151]
	v_mfma_f32_16x16x32_bf16 v[116:119], v[56:59], v[214:217], v[116:119]
	v_mfma_f32_16x16x32_bf16 v[112:115], v[64:67], v[214:217], v[112:115]
	v_mfma_f32_16x16x32_bf16 v[168:171], v[68:71], v[144:147], v[160:163]
	v_mfma_f32_16x16x32_bf16 v[156:159], v[60:63], v[208:211], v[156:159]
	v_mfma_f32_16x16x32_bf16 v[148:151], v[68:71], v[208:211], v[148:151]
	v_mfma_f32_16x16x32_bf16 v[116:119], v[60:63], v[218:221], v[116:119]
	v_mfma_f32_16x16x32_bf16 v[112:115], v[68:71], v[218:221], v[112:115]
	s_setprio 0
	s_setprio 1
	v_mfma_f32_16x16x32_bf16 v[96:99], v[88:91], v[132:135], v[96:99]
	v_mfma_f32_16x16x32_bf16 v[176:179], v[92:95], v[136:139], v[96:99]
	v_mfma_f32_16x16x32_bf16 v[96:99], v[76:79], v[140:143], v[100:103]
	v_mfma_f32_16x16x32_bf16 v[160:163], v[76:79], v[132:135], v[180:183]
	v_mfma_f32_16x16x32_bf16 v[164:167], v[84:87], v[144:147], v[96:99]
	v_mfma_f32_16x16x32_bf16 v[96:99], v[88:91], v[140:143], v[120:123]
	v_mfma_f32_16x16x32_bf16 v[180:183], v[84:87], v[136:139], v[160:163]
	v_mfma_f32_16x16x32_bf16 v[160:163], v[92:95], v[144:147], v[96:99]
	v_mfma_f32_16x16x32_bf16 v[96:99], v[76:79], v[152:155], v[124:127]
	v_mfma_f32_16x16x32_bf16 v[140:143], v[84:87], v[208:211], v[96:99]
	v_mfma_f32_16x16x32_bf16 v[96:99], v[88:91], v[152:155], v[128:131]
	v_mfma_f32_16x16x32_bf16 v[136:139], v[92:95], v[208:211], v[96:99]
	v_mfma_f32_16x16x32_bf16 v[96:99], v[76:79], v[214:217], v[108:111]
	v_mfma_f32_16x16x32_bf16 v[108:111], v[84:87], v[218:221], v[96:99]
	v_mfma_f32_16x16x32_bf16 v[96:99], v[88:91], v[214:217], v[104:107]
	v_mfma_f32_16x16x32_bf16 v[104:107], v[92:95], v[218:221], v[96:99]
	s_setprio 0
	s_barrier
	s_add_i32 s14, s49, s21
	v_lshl_add_u64 v[208:209], v[222:223], 0, s[30:31]
	s_mov_b32 m0, s14
	s_nop 1
	ds_read_b128 v[96:99], v245 offset:49152
	ds_read_b128 v[100:103], v245 offset:50176
	ds_read_b128 v[120:123], v245 offset:51200
	ds_read_b128 v[124:127], v245 offset:52224
	ds_read_b128 v[128:131], v245 offset:53248
	ds_read_b128 v[132:135], v245 offset:54272
	ds_read_b128 v[144:147], v245 offset:55296
	ds_read_b128 v[152:155], v245 offset:56320
	global_load_lds_dwordx4 v[208:209], off
	s_add_i32 m0, s14, 0x2000
	s_add_u32 s12, s12, 0x40080
	v_lshl_add_u64 v[208:209], v[224:225], 0, s[30:31]
	s_addc_u32 s13, s13, 0
	s_add_i32 s14, s51, s21
	global_load_lds_dwordx4 v[208:209], off
	v_lshl_add_u64 v[208:209], s[12:13], 0, v[194:195]
	s_mov_b32 m0, s14
	s_nop 0
	global_load_lds_dwordx4 v[208:209], off
	v_lshl_add_u64 v[208:209], s[12:13], 0, v[198:199]
	s_add_i32 m0, s14, 0x2000
	s_nop 0
	global_load_lds_dwordx4 v[208:209], off
	v_lshl_add_u64 v[208:209], v[226:227], 0, s[30:31]
	s_mov_b32 m0, s67
	s_nop 0
	global_load_lds_dwordx4 v[208:209], off
	v_lshl_add_u64 v[208:209], v[228:229], 0, s[30:31]
	s_mov_b32 m0, s76
	s_nop 0
	global_load_lds_dwordx4 v[208:209], off
	s_waitcnt vmcnt(8)
	s_waitcnt lgkmcnt(0)
	s_barrier
	s_setprio 1
	s_waitcnt lgkmcnt(0)
	v_mfma_f32_16x16x32_bf16 v[80:83], v[56:59], v[96:99], v[80:83]
	v_mfma_f32_16x16x32_bf16 v[72:75], v[64:67], v[96:99], v[72:75]
	v_mfma_f32_16x16x32_bf16 v[44:47], v[56:59], v[120:123], v[44:47]
	v_mfma_f32_16x16x32_bf16 v[40:43], v[64:67], v[120:123], v[40:43]
	v_mfma_f32_16x16x32_bf16 v[28:31], v[56:59], v[128:131], v[28:31]
	v_mfma_f32_16x16x32_bf16 v[24:27], v[64:67], v[128:131], v[24:27]
	v_mfma_f32_16x16x32_bf16 v[12:15], v[56:59], v[144:147], v[12:15]
	v_mfma_f32_16x16x32_bf16 v[8:11], v[64:67], v[144:147], v[8:11]
	v_mfma_f32_16x16x32_bf16 v[80:83], v[60:63], v[100:103], v[80:83]
	v_mfma_f32_16x16x32_bf16 v[72:75], v[68:71], v[100:103], v[72:75]
	v_mfma_f32_16x16x32_bf16 v[44:47], v[60:63], v[124:127], v[44:47]
	v_mfma_f32_16x16x32_bf16 v[40:43], v[68:71], v[124:127], v[40:43]
	v_mfma_f32_16x16x32_bf16 v[28:31], v[60:63], v[132:135], v[28:31]
	v_mfma_f32_16x16x32_bf16 v[24:27], v[68:71], v[132:135], v[24:27]
	v_mfma_f32_16x16x32_bf16 v[12:15], v[60:63], v[152:155], v[12:15]
	v_mfma_f32_16x16x32_bf16 v[8:11], v[68:71], v[152:155], v[8:11]
	s_setprio 0
	s_setprio 1
	v_mfma_f32_16x16x32_bf16 v[48:51], v[76:79], v[96:99], v[48:51]
	v_mfma_f32_16x16x32_bf16 v[68:71], v[84:87], v[100:103], v[48:51]
	v_mfma_f32_16x16x32_bf16 v[48:51], v[88:91], v[96:99], v[52:55]
	v_mfma_f32_16x16x32_bf16 v[36:39], v[76:79], v[120:123], v[36:39]
	v_mfma_f32_16x16x32_bf16 v[32:35], v[88:91], v[120:123], v[32:35]
	v_mfma_f32_16x16x32_bf16 v[20:23], v[76:79], v[128:131], v[20:23]
	v_mfma_f32_16x16x32_bf16 v[16:19], v[88:91], v[128:131], v[16:19]
	v_mfma_f32_16x16x32_bf16 v[4:7], v[76:79], v[144:147], v[4:7]
	v_mfma_f32_16x16x32_bf16 v[0:3], v[88:91], v[144:147], v[0:3]
	v_mfma_f32_16x16x32_bf16 v[64:67], v[92:95], v[100:103], v[48:51]
	v_mfma_f32_16x16x32_bf16 v[36:39], v[84:87], v[124:127], v[36:39]
	v_mfma_f32_16x16x32_bf16 v[32:35], v[92:95], v[124:127], v[32:35]
	v_mfma_f32_16x16x32_bf16 v[20:23], v[84:87], v[132:135], v[20:23]
	v_mfma_f32_16x16x32_bf16 v[16:19], v[92:95], v[132:135], v[16:19]
	v_mfma_f32_16x16x32_bf16 v[4:7], v[84:87], v[152:155], v[4:7]
	v_mfma_f32_16x16x32_bf16 v[0:3], v[92:95], v[152:155], v[0:3]
	s_setprio 0
	s_barrier
	s_add_i32 s34, s34, 2
	s_add_u32 s0, s0, 0x100
	s_addc_u32 s1, s1, 0
	s_add_u32 s19, s19, 0x100
	s_addc_u32 s33, s33, 0
	s_cmp_gt_u32 s34, 13

; #define PG8_STAGE(bufoff, gbase, voff) do { _Pragma("unroll") for (int _i = 0; _i < 2; ++_i) \
;         __builtin_amdgcn_global_load_lds((const unsigned*)((const char*)(gbase) + (voff)[_i]), (PG8_LAS unsigned*)(lds + (bufoff) + ldsw + _i * 8192), 16, 0, 0); } while (0)
; #define PG8_LDA(dst, b, h) do { _Pragma("unroll") for (int m = 0; m < 4; ++m) _Pragma("unroll") for (int k = 0; k < 2; ++k) dst[m][k] = *(const PG8_LAS bf16x8*)(lds + PG8_SA(b, h) + aoff + m * 2048 + k * 1024); } while (0)
; #define PG8_LDB(dst, b, h) do { _Pragma("unroll") for (int n = 0; n < 2; ++n) _Pragma("unroll") for (int k = 0; k < 2; ++k) dst[n][k] = *(const PG8_LAS bf16x8*)(lds + PG8_SB(b, h) + boff + n * 2048 + k * 1024); } while (0)
; #define PG8_MMA(ai, bj, At, Bt) do { __builtin_amdgcn_s_setprio(1); _Pragma("unroll") for (int m = 0; m < 4; ++m) _Pragma("unroll") for (int n = 0; n < 2; ++n) _Pragma("unroll") for (int k = 0; k < 2; ++k) \
;         acc[ai][bj][m][n] = __builtin_amdgcn_mfma_f32_16x16x32_bf16(Bt[n][k], At[m][k], acc[ai][bj][m][n], 0, 0, 0); __builtin_amdgcn_s_setprio(0); } while (0)
; #define PG8_WAIT_V(n) asm volatile("s_waitcnt vmcnt(" #n ")" ::: "memory")
; #define PG8_WAIT_L(n) asm volatile("s_waitcnt lgkmcnt(" #n ")" ::: "memory")
;     __device__ __forceinline__ void operator()(const f32x4 (&acc)[2][2][4][2], const Unit& u, int wr, int wc, int fr, int fq) const {
;     ...
;         if (tab) { const int n = pml[8]; for (int j = 0; j < n; ++j) if (pml[j] == u.pm) slot = j; }
; template <class Epi, class Sched, bool ALIGN_EPI = false, bool SP2 = false>
; __device__ __forceinline__ void gemm_phase(PG8_LAS unsigned char* lds, const Gemm g, const Sched& S, const Epi& E, const int wv  ) {
;     ...
;             const char* a2 = last ? nA : cA + (size_t)(t + 2) * kstep; const char* b2 = last ? nB : cB + (size_t)(t + 2) * kstep;
;             const char* a3 = a2 + kstep; const char* b3 = b2 + kstep;
;             if (last && has_next) S.a_ready(nxt);
;             if constexpr (SP2) {
;             PG8_LDB(B0, 0, 0); PG8_LDB(B1, 0, 1); PG8_SCHED; PG8_LDA(At, 0, 0); PG8_STAGE(PG8_SA(1, 1), a1 + hstep, voffA);
;             PG8_WAIT_V(8); PG8_WAIT_L(0); PG8_BAR; PG8_MMA(0, 0, At, B0); PG8_MMA(0, 1, At, B1); PG8_BAR; PG8_SCHED;
;             PG8_LDA(At, 0, 1); PG8_STAGE(PG8_SB(0, 0), b2, voffB); PG8_STAGE(PG8_SB(0, 1), b2 + hstep, voffB); PG8_STAGE(PG8_SA(0, 0), a2, voffA);
.LBB0_263:
	s_add_u32 s60, s3, 0x40080
	s_addc_u32 s61, s2, 0
	v_lshl_add_u64 v[208:209], s[60:61], 0, v[200:201]
	s_add_i32 m0, s25, 0xc000
	s_nop 0
	global_load_lds_dwordx4 v[208:209], off
	v_lshl_add_u64 v[208:209], s[60:61], 0, v[202:203]
	s_add_i32 m0, s25, 0xe000
	s_nop 0
	global_load_lds_dwordx4 v[208:209], off
	v_mov_b32_e32 v48, s80
	ds_read_b32 v48, v48
	s_waitcnt lgkmcnt(0)
	v_cmp_gt_i32_e32 vcc, 1, v48
	v_readfirstlane_b32 s2, v48
	s_cbranch_vccnz .LBB0_269
	s_cmp_eq_u32 s2, 1
	s_cbranch_scc1 .LBB0_270
	s_add_i32 s0, s2, -2
	s_lshr_b32 s3, s0, 1
	s_add_i32 s3, s3, 1
	s_cmp_lt_u32 s0, 14
	s_cbranch_scc1 .LBB0_271
	s_mov_b32 s34, 0
	s_and_b32 s12, s3, -8
	s_mov_b32 s1, 1
	v_bfrev_b32_e32 v48, 1
	s_mov_b32 s13, s81
	v_bfrev_b32_e32 v49, 1
	s_mov_b32 s0, s34

; #define PG8_STAGE(bufoff, gbase, voff) do { _Pragma("unroll") for (int _i = 0; _i < 2; ++_i) \
;         __builtin_amdgcn_global_load_lds((const unsigned*)((const char*)(gbase) + (voff)[_i]), (PG8_LAS unsigned*)(lds + (bufoff) + ldsw + _i * 8192), 16, 0, 0); } while (0)
; #define PG8_LDA(dst, b, h) do { _Pragma("unroll") for (int m = 0; m < 4; ++m) _Pragma("unroll") for (int k = 0; k < 2; ++k) dst[m][k] = *(const PG8_LAS bf16x8*)(lds + PG8_SA(b, h) + aoff + m * 2048 + k * 1024); } while (0)
; #define PG8_LDB(dst, b, h) do { _Pragma("unroll") for (int n = 0; n < 2; ++n) _Pragma("unroll") for (int k = 0; k < 2; ++k) dst[n][k] = *(const PG8_LAS bf16x8*)(lds + PG8_SB(b, h) + boff + n * 2048 + k * 1024); } while (0)
; #define PG8_MMA(ai, bj, At, Bt) do { __builtin_amdgcn_s_setprio(1); _Pragma("unroll") for (int m = 0; m < 4; ++m) _Pragma("unroll") for (int n = 0; n < 2; ++n) _Pragma("unroll") for (int k = 0; k < 2; ++k) \
;         acc[ai][bj][m][n] = __builtin_amdgcn_mfma_f32_16x16x32_bf16(Bt[n][k], At[m][k], acc[ai][bj][m][n], 0, 0, 0); __builtin_amdgcn_s_setprio(0); } while (0)
; template <class Epi, class Sched, bool ALIGN_EPI = false, bool SP2 = false>
; __device__ __forceinline__ void gemm_phase(PG8_LAS unsigned char* lds, const Gemm g, const Sched& S, const Epi& E, const int wv  ) {
;     ...
;         const bool has_next = S.next(ui + 1, nxt);
;         const char* nA = has_next ? (const char*)g.A + (size_t)nxt.pm * tstep : cA; const char* nB = has_next ? (const char*)g.Bt + (size_t)nxt.pn * tstep : cB;
;         for (int t = 0; t < nt; t += 2) {
;             const bool last = (t == nt - 2);
;             const char* a1 = cA + (size_t)(t + 1) * kstep;
;             const char* a2 = last ? nA : cA + (size_t)(t + 2) * kstep; const char* b2 = last ? nB : cB + (size_t)(t + 2) * kstep;
;             const char* a3 = a2 + kstep; const char* b3 = b2 + kstep;
;             if (last && has_next) S.a_ready(nxt);
;             if constexpr (SP2) {
;             PG8_LDB(B0, 0, 0); PG8_LDB(B1, 0, 1); PG8_SCHED; PG8_LDA(At, 0, 0); PG8_STAGE(PG8_SA(1, 1), a1 + hstep, voffA);
;             PG8_WAIT_V(8); PG8_WAIT_L(0); PG8_BAR; PG8_MMA(0, 0, At, B0); PG8_MMA(0, 1, At, B1); PG8_BAR; PG8_SCHED;
;             PG8_LDA(At, 0, 1); PG8_STAGE(PG8_SB(0, 0), b2, voffB); PG8_STAGE(PG8_SB(0, 1), b2 + hstep, voffB); PG8_STAGE(PG8_SA(0, 0), a2, voffA);
.LBB0_915:
	s_ashr_i32 s25, s24, 31
	s_lshl_b64 s[26:27], s[24:25], 19
	s_add_u32 s26, s2, s26
	s_addc_u32 s27, s3, s27
	s_and_b64 s[28:29], s[6:7], exec
	s_cselect_b32 s25, s27, s35
	s_cselect_b32 s31, s26, s34
	s_ashr_i32 s23, s22, 31
	s_lshl_b64 s[28:29], s[22:23], 19
	s_add_u32 s28, s20, s28
	s_addc_u32 s29, s21, s29
	s_and_b64 s[38:39], s[6:7], exec
	s_cselect_b32 s23, s29, s37
	s_cselect_b32 s52, s28, s36
	s_add_u32 s34, s34, 0x40080
	s_addc_u32 s35, s35, 0
	s_add_u32 s53, s36, 0x100
	s_addc_u32 s54, s37, 0
	s_mov_b32 s55, -2
	s_waitcnt lgkmcnt(0)
	s_cmp_eq_u32 s51, 1
	s_cbranch_scc1 .LpeelA_916
	ds_read_b128 v[128:131], v191
	ds_read_b128 v[132:135], v191 offset:1024
	ds_read_b128 v[136:139], v191 offset:2048
	ds_read_b128 v[140:143], v191 offset:3072
	ds_read_b128 v[144:147], v192
	ds_read_b128 v[148:151], v192 offset:1024
	ds_read_b128 v[168:171], v192 offset:2048
	ds_read_b128 v[172:175], v192 offset:3072
	s_add_u32 s36, s34, 0xfffc0080
	s_addc_u32 s37, s35, -1
	s_cmp_eq_u32 s55, 12
	s_cselect_b32 s39, s25, s37
	s_cselect_b32 s38, s31, s36
	s_cselect_b32 s37, s23, s54
	s_cselect_b32 s36, s52, s53
	ds_read_b128 v[176:179], v193
	ds_read_b128 v[180:183], v193 offset:1024
	ds_read_b128 v[194:197], v193 offset:2048
	ds_read_b128 v[198:201], v193 offset:3072
	ds_read_b128 v[202:205], v193 offset:4096
	ds_read_b128 v[206:209], v193 offset:5120
	ds_read_b128 v[214:217], v193 offset:6144
	ds_read_b128 v[218:221], v193 offset:7168
	s_waitcnt vmcnt(24)
	s_waitcnt lgkmcnt(0)
	s_barrier
	s_setprio 1
	s_waitcnt lgkmcnt(0)
	v_mfma_f32_16x16x32_bf16 v[124:127], v[128:131], v[176:179], 0
	v_mfma_f32_16x16x32_bf16 v[120:123], v[136:139], v[176:179], 0
	v_mfma_f32_16x16x32_bf16 v[108:111], v[128:131], v[194:197], 0
	v_mfma_f32_16x16x32_bf16 v[104:107], v[136:139], v[194:197], 0
	v_mfma_f32_16x16x32_bf16 v[92:95], v[128:131], v[202:205], 0
	v_mfma_f32_16x16x32_bf16 v[88:91], v[136:139], v[202:205], 0
	v_mfma_f32_16x16x32_bf16 v[76:79], v[128:131], v[214:217], 0
	v_mfma_f32_16x16x32_bf16 v[72:75], v[136:139], v[214:217], 0
	v_mfma_f32_16x16x32_bf16 v[124:127], v[132:135], v[180:183], v[124:127]
	v_mfma_f32_16x16x32_bf16 v[120:123], v[140:143], v[180:183], v[120:123]
	v_mfma_f32_16x16x32_bf16 v[108:111], v[132:135], v[198:201], v[108:111]
	v_mfma_f32_16x16x32_bf16 v[104:107], v[140:143], v[198:201], v[104:107]
	v_mfma_f32_16x16x32_bf16 v[92:95], v[132:135], v[206:209], v[92:95]
	v_mfma_f32_16x16x32_bf16 v[88:91], v[140:143], v[206:209], v[88:91]
	v_mfma_f32_16x16x32_bf16 v[76:79], v[132:135], v[218:221], v[76:79]
	v_mfma_f32_16x16x32_bf16 v[72:75], v[140:143], v[218:221], v[72:75]
	s_setprio 0
	s_setprio 1
	v_mfma_f32_16x16x32_bf16 v[116:119], v[144:147], v[176:179], 0
	v_mfma_f32_16x16x32_bf16 v[112:115], v[168:171], v[176:179], 0
	v_mfma_f32_16x16x32_bf16 v[100:103], v[144:147], v[194:197], 0
	v_mfma_f32_16x16x32_bf16 v[96:99], v[168:171], v[194:197], 0
	v_mfma_f32_16x16x32_bf16 v[84:87], v[144:147], v[202:205], 0
	v_mfma_f32_16x16x32_bf16 v[80:83], v[168:171], v[202:205], 0
	v_mfma_f32_16x16x32_bf16 v[68:71], v[144:147], v[214:217], 0
	v_mfma_f32_16x16x32_bf16 v[64:67], v[168:171], v[214:217], 0
	v_mfma_f32_16x16x32_bf16 v[116:119], v[148:151], v[180:183], v[116:119]
	v_mfma_f32_16x16x32_bf16 v[112:115], v[172:175], v[180:183], v[112:115]
	v_mfma_f32_16x16x32_bf16 v[100:103], v[148:151], v[198:201], v[100:103]
	v_mfma_f32_16x16x32_bf16 v[96:99], v[172:175], v[198:201], v[96:99]
	v_mfma_f32_16x16x32_bf16 v[84:87], v[148:151], v[206:209], v[84:87]
	v_mfma_f32_16x16x32_bf16 v[80:83], v[172:175], v[206:209], v[80:83]
	v_mfma_f32_16x16x32_bf16 v[68:71], v[148:151], v[218:221], v[68:71]
	v_mfma_f32_16x16x32_bf16 v[64:67], v[172:175], v[218:221], v[64:67]
	s_setprio 0
	s_barrier
	s_add_i32 s56, s49, s33
	v_lshl_add_u64 v[184:185], s[36:37], 0, v[154:155]
	s_mov_b32 m0, s56
	ds_read_b128 v[176:179], v193 offset:16384
	ds_read_b128 v[180:183], v193 offset:17408
	ds_read_b128 v[194:197], v193 offset:18432
	ds_read_b128 v[198:201], v193 offset:19456
	ds_read_b128 v[202:205], v193 offset:20480
	ds_read_b128 v[206:209], v193 offset:21504
	ds_read_b128 v[214:217], v193 offset:22528
	ds_read_b128 v[218:221], v193 offset:23552
	global_load_lds_dwordx4 v[184:185], off
	s_add_i32 m0, s56, 0x2000
	s_add_u32 s56, s36, 0x40000
	v_lshl_add_u64 v[210:211], s[36:37], 0, v[158:159]
	s_addc_u32 s57, s37, 0
	s_add_i32 s58, s50, s33
	global_load_lds_dwordx4 v[210:211], off
	v_lshl_add_u64 v[222:223], s[56:57], 0, v[154:155]
	s_mov_b32 m0, s58
	v_lshl_add_u64 v[224:225], s[38:39], 0, v[156:157]
	global_load_lds_dwordx4 v[222:223], off
	v_lshl_add_u64 v[222:223], s[56:57], 0, v[158:159]
	s_add_i32 m0, s58, 0x2000
	s_nop 0
	global_load_lds_dwordx4 v[222:223], off
	v_lshl_add_u64 v[222:223], s[38:39], 0, v[152:153]
	s_mov_b32 m0, s40
	s_nop 0
	global_load_lds_dwordx4 v[222:223], off
	s_mov_b32 m0, s41
	s_nop 0
	global_load_lds_dwordx4 v[224:225], off
	s_waitcnt vmcnt(24)
	s_waitcnt lgkmcnt(0)
	s_barrier
; #define PG8_STAGE(bufoff, gbase, voff) do { _Pragma("unroll") for (int _i = 0; _i < 2; ++_i) \
;         __builtin_amdgcn_global_load_lds((const unsigned*)((const char*)(gbase) + (voff)[_i]), (PG8_LAS unsigned*)(lds + (bufoff) + ldsw + _i * 8192), 16, 0, 0); } while (0)
; #define PG8_LDA(dst, b, h) do { _Pragma("unroll") for (int m = 0; m < 4; ++m) _Pragma("unroll") for (int k = 0; k < 2; ++k) dst[m][k] = *(const PG8_LAS bf16x8*)(lds + PG8_SA(b, h) + aoff + m * 2048 + k * 1024); } while (0)
; #define PG8_LDB(dst, b, h) do { _Pragma("unroll") for (int n = 0; n < 2; ++n) _Pragma("unroll") for (int k = 0; k < 2; ++k) dst[n][k] = *(const PG8_LAS bf16x8*)(lds + PG8_SB(b, h) + boff + n * 2048 + k * 1024); } while (0)
; #define PG8_MMA(ai, bj, At, Bt) do { __builtin_amdgcn_s_setprio(1); _Pragma("unroll") for (int m = 0; m < 4; ++m) _Pragma("unroll") for (int n = 0; n < 2; ++n) _Pragma("unroll") for (int k = 0; k < 2; ++k) \
;         acc[ai][bj][m][n] = __builtin_amdgcn_mfma_f32_16x16x32_bf16(Bt[n][k], At[m][k], acc[ai][bj][m][n], 0, 0, 0); __builtin_amdgcn_s_setprio(0); } while (0)
; #define PG8_BAR __builtin_amdgcn_s_barrier()
; template <class Epi, class Sched, bool ALIGN_EPI = false, bool SP2 = false>
; __device__ __forceinline__ void gemm_phase(PG8_LAS unsigned char* lds, const Gemm g, const Sched& S, const Epi& E, const int wv  ) {
;     ...
;             PG8_LDB(B0, 0, 0); PG8_LDB(B1, 0, 1); PG8_SCHED; PG8_LDA(At, 0, 0); PG8_STAGE(PG8_SA(1, 1), a1 + hstep, voffA);
;             PG8_WAIT_V(8); PG8_WAIT_L(0); PG8_BAR; PG8_MMA(0, 0, At, B0); PG8_MMA(0, 1, At, B1); PG8_BAR; PG8_SCHED;
;             PG8_LDA(At, 0, 1); PG8_STAGE(PG8_SB(0, 0), b2, voffB); PG8_STAGE(PG8_SB(0, 1), b2 + hstep, voffB); PG8_STAGE(PG8_SA(0, 0), a2, voffA);
;             PG8_WAIT_V(8); PG8_WAIT_L(0); PG8_BAR; PG8_MMA(1, 0, At, B0); PG8_MMA(1, 1, At, B1); PG8_BAR; PG8_SCHED;
;             PG8_LDB(B0, 1, 0); PG8_LDB(B1, 1, 1); PG8_SCHED; PG8_LDA(At, 1, 0); PG8_STAGE(PG8_SA(0, 1), a2 + hstep, voffA);
;             PG8_WAIT_V(8); PG8_WAIT_L(0); PG8_BAR; PG8_MMA(0, 0, At, B0); PG8_MMA(0, 1, At, B1); PG8_BAR; PG8_SCHED;
;             PG8_LDA(At, 1, 1); PG8_STAGE(PG8_SB(1, 0), b3, voffB); PG8_STAGE(PG8_SB(1, 1), b3 + hstep, voffB); PG8_STAGE(PG8_SA(1, 0), a3, voffA);
;             PG8_WAIT_V(8); PG8_WAIT_L(0); PG8_BAR; PG8_MMA(1, 0, At, B0); PG8_MMA(1, 1, At, B1); PG8_BAR; PG8_SCHED;
	s_setprio 1
	s_waitcnt lgkmcnt(0)
	v_mfma_f32_16x16x32_bf16 v[60:63], v[128:131], v[176:179], 0
	v_mfma_f32_16x16x32_bf16 v[56:59], v[136:139], v[176:179], 0
	v_mfma_f32_16x16x32_bf16 v[44:47], v[128:131], v[194:197], 0
	v_mfma_f32_16x16x32_bf16 v[40:43], v[136:139], v[194:197], 0
	v_mfma_f32_16x16x32_bf16 v[28:31], v[128:131], v[202:205], 0
	v_mfma_f32_16x16x32_bf16 v[24:27], v[136:139], v[202:205], 0
	v_mfma_f32_16x16x32_bf16 v[12:15], v[128:131], v[214:217], 0
	v_mfma_f32_16x16x32_bf16 v[8:11], v[136:139], v[214:217], 0
	v_mfma_f32_16x16x32_bf16 v[60:63], v[132:135], v[180:183], v[60:63]
	v_mfma_f32_16x16x32_bf16 v[56:59], v[140:143], v[180:183], v[56:59]
	v_mfma_f32_16x16x32_bf16 v[44:47], v[132:135], v[198:201], v[44:47]
	v_mfma_f32_16x16x32_bf16 v[40:43], v[140:143], v[198:201], v[40:43]
	v_mfma_f32_16x16x32_bf16 v[28:31], v[132:135], v[206:209], v[28:31]
	v_mfma_f32_16x16x32_bf16 v[24:27], v[140:143], v[206:209], v[24:27]
	v_mfma_f32_16x16x32_bf16 v[12:15], v[132:135], v[218:221], v[12:15]
	v_mfma_f32_16x16x32_bf16 v[8:11], v[140:143], v[218:221], v[8:11]
	s_setprio 0
	s_setprio 1
	v_mfma_f32_16x16x32_bf16 v[52:55], v[144:147], v[176:179], 0
	v_mfma_f32_16x16x32_bf16 v[48:51], v[168:171], v[176:179], 0
	v_mfma_f32_16x16x32_bf16 v[36:39], v[144:147], v[194:197], 0
	v_mfma_f32_16x16x32_bf16 v[32:35], v[168:171], v[194:197], 0
	v_mfma_f32_16x16x32_bf16 v[20:23], v[144:147], v[202:205], 0
	v_mfma_f32_16x16x32_bf16 v[16:19], v[168:171], v[202:205], 0
	v_mfma_f32_16x16x32_bf16 v[4:7], v[144:147], v[214:217], 0
	v_mfma_f32_16x16x32_bf16 v[0:3], v[168:171], v[214:217], 0
	v_mfma_f32_16x16x32_bf16 v[52:55], v[148:151], v[180:183], v[52:55]
	v_mfma_f32_16x16x32_bf16 v[48:51], v[172:175], v[180:183], v[48:51]
	v_mfma_f32_16x16x32_bf16 v[36:39], v[148:151], v[198:201], v[36:39]
	v_mfma_f32_16x16x32_bf16 v[32:35], v[172:175], v[198:201], v[32:35]
	v_mfma_f32_16x16x32_bf16 v[20:23], v[148:151], v[206:209], v[20:23]
	v_mfma_f32_16x16x32_bf16 v[16:19], v[172:175], v[206:209], v[16:19]
	v_mfma_f32_16x16x32_bf16 v[4:7], v[148:151], v[218:221], v[4:7]
	v_mfma_f32_16x16x32_bf16 v[0:3], v[172:175], v[218:221], v[0:3]
	s_setprio 0
	s_barrier
	s_add_i32 s56, 0, 0x18000
	s_add_i32 s57, 0, 0x1c000
	v_add_u32_e32 v140, s56, v189
	v_add_u32_e32 v172, s57, v189
	ds_read_b128 v[128:131], v140
	ds_read_b128 v[132:135], v140 offset:1024
	ds_read_b128 v[136:139], v140 offset:2048
	ds_read_b128 v[140:143], v140 offset:3072
	ds_read_b128 v[144:147], v172
	ds_read_b128 v[148:151], v172 offset:1024
	ds_read_b128 v[168:171], v172 offset:2048
	ds_read_b128 v[172:175], v172 offset:3072
	s_add_u32 s38, s38, 0x40000
	s_addc_u32 s39, s39, 0
	s_mov_b32 m0, s42
	v_lshl_add_u64 v[226:227], s[38:39], 0, v[152:153]
	ds_read_b128 v[176:179], v193 offset:32768
	ds_read_b128 v[180:183], v193 offset:33792
	ds_read_b128 v[194:197], v193 offset:34816
	ds_read_b128 v[198:201], v193 offset:35840
	ds_read_b128 v[202:205], v193 offset:36864
	ds_read_b128 v[206:209], v193 offset:37888
	ds_read_b128 v[214:217], v193 offset:38912
	ds_read_b128 v[218:221], v193 offset:39936
	global_load_lds_dwordx4 v[226:227], off
	v_lshl_add_u64 v[226:227], s[38:39], 0, v[156:157]
	s_mov_b32 m0, s43
	s_nop 0
	global_load_lds_dwordx4 v[226:227], off
	s_waitcnt vmcnt(24)
	s_waitcnt lgkmcnt(0)
	s_barrier
	s_setprio 1
	s_waitcnt lgkmcnt(0)
	v_mfma_f32_16x16x32_bf16 v[124:127], v[128:131], v[176:179], v[124:127]
	v_mfma_f32_16x16x32_bf16 v[120:123], v[136:139], v[176:179], v[120:123]
	v_mfma_f32_16x16x32_bf16 v[108:111], v[128:131], v[194:197], v[108:111]
	v_mfma_f32_16x16x32_bf16 v[104:107], v[136:139], v[194:197], v[104:107]
	v_mfma_f32_16x16x32_bf16 v[92:95], v[128:131], v[202:205], v[92:95]
	v_mfma_f32_16x16x32_bf16 v[88:91], v[136:139], v[202:205], v[88:91]
	v_mfma_f32_16x16x32_bf16 v[76:79], v[128:131], v[214:217], v[76:79]
	v_mfma_f32_16x16x32_bf16 v[72:75], v[136:139], v[214:217], v[72:75]
	v_mfma_f32_16x16x32_bf16 v[124:127], v[132:135], v[180:183], v[124:127]
	v_mfma_f32_16x16x32_bf16 v[120:123], v[140:143], v[180:183], v[120:123]
	v_mfma_f32_16x16x32_bf16 v[108:111], v[132:135], v[198:201], v[108:111]
	v_mfma_f32_16x16x32_bf16 v[104:107], v[140:143], v[198:201], v[104:107]
	v_mfma_f32_16x16x32_bf16 v[92:95], v[132:135], v[206:209], v[92:95]
	v_mfma_f32_16x16x32_bf16 v[88:91], v[140:143], v[206:209], v[88:91]
	v_mfma_f32_16x16x32_bf16 v[76:79], v[132:135], v[218:221], v[76:79]
	v_mfma_f32_16x16x32_bf16 v[72:75], v[140:143], v[218:221], v[72:75]
	s_setprio 0
	s_setprio 1
	v_mfma_f32_16x16x32_bf16 v[116:119], v[144:147], v[176:179], v[116:119]
	v_mfma_f32_16x16x32_bf16 v[112:115], v[168:171], v[176:179], v[112:115]
	v_mfma_f32_16x16x32_bf16 v[100:103], v[144:147], v[194:197], v[100:103]
	v_mfma_f32_16x16x32_bf16 v[96:99], v[168:171], v[194:197], v[96:99]
	v_mfma_f32_16x16x32_bf16 v[84:87], v[144:147], v[202:205], v[84:87]
	v_mfma_f32_16x16x32_bf16 v[80:83], v[168:171], v[202:205], v[80:83]
	v_mfma_f32_16x16x32_bf16 v[68:71], v[144:147], v[214:217], v[68:71]
	v_mfma_f32_16x16x32_bf16 v[64:67], v[168:171], v[214:217], v[64:67]
	v_mfma_f32_16x16x32_bf16 v[116:119], v[148:151], v[180:183], v[116:119]
	v_mfma_f32_16x16x32_bf16 v[112:115], v[172:175], v[180:183], v[112:115]
	v_mfma_f32_16x16x32_bf16 v[100:103], v[148:151], v[198:201], v[100:103]
	v_mfma_f32_16x16x32_bf16 v[96:99], v[172:175], v[198:201], v[96:99]
	v_mfma_f32_16x16x32_bf16 v[84:87], v[148:151], v[206:209], v[84:87]
	v_mfma_f32_16x16x32_bf16 v[80:83], v[172:175], v[206:209], v[80:83]
	v_mfma_f32_16x16x32_bf16 v[68:71], v[148:151], v[218:221], v[68:71]
	v_mfma_f32_16x16x32_bf16 v[64:67], v[172:175], v[218:221], v[64:67]
	s_setprio 0
	s_barrier
; #define PG8_STAGE(bufoff, gbase, voff) do { _Pragma("unroll") for (int _i = 0; _i < 2; ++_i) \
;         __builtin_amdgcn_global_load_lds((const unsigned*)((const char*)(gbase) + (voff)[_i]), (PG8_LAS unsigned*)(lds + (bufoff) + ldsw + _i * 8192), 16, 0, 0); } while (0)
; #define PG8_LDA(dst, b, h) do { _Pragma("unroll") for (int m = 0; m < 4; ++m) _Pragma("unroll") for (int k = 0; k < 2; ++k) dst[m][k] = *(const PG8_LAS bf16x8*)(lds + PG8_SA(b, h) + aoff + m * 2048 + k * 1024); } while (0)
; #define PG8_LDB(dst, b, h) do { _Pragma("unroll") for (int n = 0; n < 2; ++n) _Pragma("unroll") for (int k = 0; k < 2; ++k) dst[n][k] = *(const PG8_LAS bf16x8*)(lds + PG8_SB(b, h) + boff + n * 2048 + k * 1024); } while (0)
; #define PG8_WAIT_V(n) asm volatile("s_waitcnt vmcnt(" #n ")" ::: "memory")
; #define PG8_BAR __builtin_amdgcn_s_barrier()
; template <class Epi, class Sched, bool ALIGN_EPI = false, bool SP2 = false>
; __device__ __forceinline__ void gemm_phase(PG8_LAS unsigned char* lds, const Gemm g, const Sched& S, const Epi& E, const int wv  ) {
;     ...
;         for (int t = 0; t < nt; t += 2) {
;             const bool last = (t == nt - 2);
;             const char* a1 = cA + (size_t)(t + 1) * kstep;
;             const char* a2 = last ? nA : cA + (size_t)(t + 2) * kstep; const char* b2 = last ? nB : cB + (size_t)(t + 2) * kstep;
;     ...
;             PG8_LDB(B0, 0, 0); PG8_LDB(B1, 0, 1); PG8_SCHED; PG8_LDA(At, 0, 0); PG8_STAGE(PG8_SA(1, 1), a1 + hstep, voffA);
;             PG8_WAIT_V(8); PG8_WAIT_L(0); PG8_BAR; PG8_MMA(0, 0, At, B0); PG8_MMA(0, 1, At, B1); PG8_BAR; PG8_SCHED;
;             PG8_LDA(At, 0, 1); PG8_STAGE(PG8_SB(0, 0), b2, voffB); PG8_STAGE(PG8_SB(0, 1), b2 + hstep, voffB); PG8_STAGE(PG8_SA(0, 0), a2, voffA);
;             PG8_WAIT_V(8); PG8_WAIT_L(0); PG8_BAR; PG8_MMA(1, 0, At, B0); PG8_MMA(1, 1, At, B1); PG8_BAR; PG8_SCHED;
;             PG8_LDB(B0, 1, 0); PG8_LDB(B1, 1, 1); PG8_SCHED; PG8_LDA(At, 1, 0); PG8_STAGE(PG8_SA(0, 1), a2 + hstep, voffA);
;             PG8_WAIT_V(8); PG8_WAIT_L(0); PG8_BAR; PG8_MMA(0, 0, At, B0); PG8_MMA(0, 1, At, B1); PG8_BAR; PG8_SCHED;
;             PG8_LDA(At, 1, 1); PG8_STAGE(PG8_SB(1, 0), b3, voffB); PG8_STAGE(PG8_SB(1, 1), b3 + hstep, voffB); PG8_STAGE(PG8_SA(1, 0), a3, voffA);
;             PG8_WAIT_V(8); PG8_WAIT_L(0); PG8_BAR; PG8_MMA(1, 0, At, B0); PG8_MMA(1, 1, At, B1); PG8_BAR; PG8_SCHED;
	s_add_i32 s38, s56, s33
	v_lshl_add_u64 v[184:185], v[184:185], 0, s[16:17]
	s_mov_b32 m0, s38
	ds_read_b128 v[176:179], v193 offset:49152
	ds_read_b128 v[180:183], v193 offset:50176
	ds_read_b128 v[194:197], v193 offset:51200
	ds_read_b128 v[198:201], v193 offset:52224
	ds_read_b128 v[202:205], v193 offset:53248
	ds_read_b128 v[206:209], v193 offset:54272
	ds_read_b128 v[214:217], v193 offset:55296
	ds_read_b128 v[218:221], v193 offset:56320
	global_load_lds_dwordx4 v[184:185], off
	s_add_i32 m0, s38, 0x2000
	s_add_u32 s36, s36, 0x40080
	v_lshl_add_u64 v[184:185], v[210:211], 0, s[16:17]
	s_addc_u32 s37, s37, 0
	s_add_i32 s38, s57, s33
	global_load_lds_dwordx4 v[184:185], off
	v_lshl_add_u64 v[184:185], s[36:37], 0, v[154:155]
	s_mov_b32 m0, s38
	s_nop 0
	global_load_lds_dwordx4 v[184:185], off
	v_lshl_add_u64 v[184:185], s[36:37], 0, v[158:159]
	s_add_i32 m0, s38, 0x2000
	s_nop 0
	global_load_lds_dwordx4 v[184:185], off
	v_lshl_add_u64 v[184:185], v[222:223], 0, s[16:17]
	s_mov_b32 m0, s47
	s_nop 0
	global_load_lds_dwordx4 v[184:185], off
	v_lshl_add_u64 v[184:185], v[224:225], 0, s[16:17]
	s_mov_b32 m0, s48
	s_nop 0
	global_load_lds_dwordx4 v[184:185], off
	s_waitcnt vmcnt(8)
	s_waitcnt lgkmcnt(0)
	s_barrier
	s_setprio 1
	s_waitcnt lgkmcnt(0)
	v_mfma_f32_16x16x32_bf16 v[60:63], v[128:131], v[176:179], v[60:63]
	v_mfma_f32_16x16x32_bf16 v[56:59], v[136:139], v[176:179], v[56:59]
	v_mfma_f32_16x16x32_bf16 v[44:47], v[128:131], v[194:197], v[44:47]
	v_mfma_f32_16x16x32_bf16 v[40:43], v[136:139], v[194:197], v[40:43]
	v_mfma_f32_16x16x32_bf16 v[28:31], v[128:131], v[202:205], v[28:31]
	v_mfma_f32_16x16x32_bf16 v[24:27], v[136:139], v[202:205], v[24:27]
	v_mfma_f32_16x16x32_bf16 v[12:15], v[128:131], v[214:217], v[12:15]
	v_mfma_f32_16x16x32_bf16 v[8:11], v[136:139], v[214:217], v[8:11]
	v_mfma_f32_16x16x32_bf16 v[60:63], v[132:135], v[180:183], v[60:63]
	v_mfma_f32_16x16x32_bf16 v[56:59], v[140:143], v[180:183], v[56:59]
	v_mfma_f32_16x16x32_bf16 v[44:47], v[132:135], v[198:201], v[44:47]
	v_mfma_f32_16x16x32_bf16 v[40:43], v[140:143], v[198:201], v[40:43]
	v_mfma_f32_16x16x32_bf16 v[28:31], v[132:135], v[206:209], v[28:31]
	v_mfma_f32_16x16x32_bf16 v[24:27], v[140:143], v[206:209], v[24:27]
	v_mfma_f32_16x16x32_bf16 v[12:15], v[132:135], v[218:221], v[12:15]
	v_mfma_f32_16x16x32_bf16 v[8:11], v[140:143], v[218:221], v[8:11]
	s_setprio 0
	s_setprio 1
	v_mfma_f32_16x16x32_bf16 v[52:55], v[144:147], v[176:179], v[52:55]
	v_mfma_f32_16x16x32_bf16 v[48:51], v[168:171], v[176:179], v[48:51]
	v_mfma_f32_16x16x32_bf16 v[36:39], v[144:147], v[194:197], v[36:39]
	v_mfma_f32_16x16x32_bf16 v[32:35], v[168:171], v[194:197], v[32:35]
	v_mfma_f32_16x16x32_bf16 v[20:23], v[144:147], v[202:205], v[20:23]
	v_mfma_f32_16x16x32_bf16 v[16:19], v[168:171], v[202:205], v[16:19]
	v_mfma_f32_16x16x32_bf16 v[4:7], v[144:147], v[214:217], v[4:7]
	v_mfma_f32_16x16x32_bf16 v[0:3], v[168:171], v[214:217], v[0:3]
	v_mfma_f32_16x16x32_bf16 v[52:55], v[148:151], v[180:183], v[52:55]
	v_mfma_f32_16x16x32_bf16 v[48:51], v[172:175], v[180:183], v[48:51]
	v_mfma_f32_16x16x32_bf16 v[36:39], v[148:151], v[198:201], v[36:39]
	v_mfma_f32_16x16x32_bf16 v[32:35], v[172:175], v[198:201], v[32:35]
	v_mfma_f32_16x16x32_bf16 v[20:23], v[148:151], v[206:209], v[20:23]
	v_mfma_f32_16x16x32_bf16 v[16:19], v[172:175], v[206:209], v[16:19]
	v_mfma_f32_16x16x32_bf16 v[4:7], v[148:151], v[218:221], v[4:7]
	v_mfma_f32_16x16x32_bf16 v[0:3], v[172:175], v[218:221], v[0:3]
	s_setprio 0
	s_barrier
	s_add_i32 s55, s55, 2
	s_add_u32 s34, s34, 0x100
	s_addc_u32 s35, s35, 0
	s_add_u32 s53, s53, 0x100
	s_addc_u32 s54, s54, 0
	s_cmp_gt_u32 s55, 13
	s_branch .LBB0_916
.LpeelA_916:
	ds_read_b128 v[128:131], v191
	ds_read_b128 v[132:135], v191 offset:1024
	ds_read_b128 v[136:139], v191 offset:2048
	ds_read_b128 v[140:143], v191 offset:3072
	ds_read_b128 v[144:147], v192
	ds_read_b128 v[148:151], v192 offset:1024
	ds_read_b128 v[168:171], v192 offset:2048
	ds_read_b128 v[172:175], v192 offset:3072
	s_add_u32 s36, s34, 0xfffc0080
	s_addc_u32 s37, s35, -1
	s_cmp_eq_u32 s55, 12
	s_cselect_b32 s39, s25, s37
	s_cselect_b32 s38, s31, s36
	s_cselect_b32 s37, s23, s54
	s_cselect_b32 s36, s52, s53
	v_lshl_add_u64 v[184:185], s[34:35], 0, v[160:161]
	s_add_i32 m0, s40, 0xc000
	ds_read_b128 v[176:179], v193
	ds_read_b128 v[180:183], v193 offset:1024
	ds_read_b128 v[194:197], v193 offset:2048
	ds_read_b128 v[198:201], v193 offset:3072
	ds_read_b128 v[202:205], v193 offset:4096
	ds_read_b128 v[206:209], v193 offset:5120
	ds_read_b128 v[214:217], v193 offset:6144
	ds_read_b128 v[218:221], v193 offset:7168
	global_load_lds_dwordx4 v[184:185], off
	v_lshl_add_u64 v[184:185], s[34:35], 0, v[162:163]
	s_add_i32 m0, s40, 0xe000
	s_nop 0
	global_load_lds_dwordx4 v[184:185], off
	s_waitcnt vmcnt(8)
	s_waitcnt lgkmcnt(0)
	s_barrier
; #define PG8_STAGE(bufoff, gbase, voff) do { _Pragma("unroll") for (int _i = 0; _i < 2; ++_i) \
;         __builtin_amdgcn_global_load_lds((const unsigned*)((const char*)(gbase) + (voff)[_i]), (PG8_LAS unsigned*)(lds + (bufoff) + ldsw + _i * 8192), 16, 0, 0); } while (0)
; #define PG8_LDA(dst, b, h) do { _Pragma("unroll") for (int m = 0; m < 4; ++m) _Pragma("unroll") for (int k = 0; k < 2; ++k) dst[m][k] = *(const PG8_LAS bf16x8*)(lds + PG8_SA(b, h) + aoff + m * 2048 + k * 1024); } while (0)
; #define PG8_LDB(dst, b, h) do { _Pragma("unroll") for (int n = 0; n < 2; ++n) _Pragma("unroll") for (int k = 0; k < 2; ++k) dst[n][k] = *(const PG8_LAS bf16x8*)(lds + PG8_SB(b, h) + boff + n * 2048 + k * 1024); } while (0)
; #define PG8_MMA(ai, bj, At, Bt) do { __builtin_amdgcn_s_setprio(1); _Pragma("unroll") for (int m = 0; m < 4; ++m) _Pragma("unroll") for (int n = 0; n < 2; ++n) _Pragma("unroll") for (int k = 0; k < 2; ++k) \
;         acc[ai][bj][m][n] = __builtin_amdgcn_mfma_f32_16x16x32_bf16(Bt[n][k], At[m][k], acc[ai][bj][m][n], 0, 0, 0); __builtin_amdgcn_s_setprio(0); } while (0)
; #define PG8_BAR __builtin_amdgcn_s_barrier()
; template <class Epi, class Sched, bool ALIGN_EPI = false, bool SP2 = false>
; __device__ __forceinline__ void gemm_phase(PG8_LAS unsigned char* lds, const Gemm g, const Sched& S, const Epi& E, const int wv  ) {
;     ...
;             PG8_LDB(B0, 0, 0); PG8_LDB(B1, 0, 1); PG8_SCHED; PG8_LDA(At, 0, 0); PG8_STAGE(PG8_SA(1, 1), a1 + hstep, voffA);
;             PG8_WAIT_V(8); PG8_WAIT_L(0); PG8_BAR; PG8_MMA(0, 0, At, B0); PG8_MMA(0, 1, At, B1); PG8_BAR; PG8_SCHED;
;             PG8_LDA(At, 0, 1); PG8_STAGE(PG8_SB(0, 0), b2, voffB); PG8_STAGE(PG8_SB(0, 1), b2 + hstep, voffB); PG8_STAGE(PG8_SA(0, 0), a2, voffA);
;             PG8_WAIT_V(8); PG8_WAIT_L(0); PG8_BAR; PG8_MMA(1, 0, At, B0); PG8_MMA(1, 1, At, B1); PG8_BAR; PG8_SCHED;
;             PG8_LDB(B0, 1, 0); PG8_LDB(B1, 1, 1); PG8_SCHED; PG8_LDA(At, 1, 0); PG8_STAGE(PG8_SA(0, 1), a2 + hstep, voffA);
;             PG8_WAIT_V(8); PG8_WAIT_L(0); PG8_BAR; PG8_MMA(0, 0, At, B0); PG8_MMA(0, 1, At, B1); PG8_BAR; PG8_SCHED;
;             PG8_LDA(At, 1, 1); PG8_STAGE(PG8_SB(1, 0), b3, voffB); PG8_STAGE(PG8_SB(1, 1), b3 + hstep, voffB); PG8_STAGE(PG8_SA(1, 0), a3, voffA);
;             PG8_WAIT_V(8); PG8_WAIT_L(0); PG8_BAR; PG8_MMA(1, 0, At, B0); PG8_MMA(1, 1, At, B1); PG8_BAR; PG8_SCHED;
	s_setprio 1
	s_waitcnt lgkmcnt(0)
	v_mfma_f32_16x16x32_bf16 v[124:127], v[128:131], v[176:179], 0
	v_mfma_f32_16x16x32_bf16 v[120:123], v[136:139], v[176:179], 0
	v_mfma_f32_16x16x32_bf16 v[108:111], v[128:131], v[194:197], 0
	v_mfma_f32_16x16x32_bf16 v[104:107], v[136:139], v[194:197], 0
	v_mfma_f32_16x16x32_bf16 v[92:95], v[128:131], v[202:205], 0
	v_mfma_f32_16x16x32_bf16 v[88:91], v[136:139], v[202:205], 0
	v_mfma_f32_16x16x32_bf16 v[76:79], v[128:131], v[214:217], 0
	v_mfma_f32_16x16x32_bf16 v[72:75], v[136:139], v[214:217], 0
	v_mfma_f32_16x16x32_bf16 v[124:127], v[132:135], v[180:183], v[124:127]
	v_mfma_f32_16x16x32_bf16 v[120:123], v[140:143], v[180:183], v[120:123]
	v_mfma_f32_16x16x32_bf16 v[108:111], v[132:135], v[198:201], v[108:111]
	v_mfma_f32_16x16x32_bf16 v[104:107], v[140:143], v[198:201], v[104:107]
	v_mfma_f32_16x16x32_bf16 v[92:95], v[132:135], v[206:209], v[92:95]
	v_mfma_f32_16x16x32_bf16 v[88:91], v[140:143], v[206:209], v[88:91]
	v_mfma_f32_16x16x32_bf16 v[76:79], v[132:135], v[218:221], v[76:79]
	v_mfma_f32_16x16x32_bf16 v[72:75], v[140:143], v[218:221], v[72:75]
	s_setprio 0
	s_setprio 1
	v_mfma_f32_16x16x32_bf16 v[116:119], v[144:147], v[176:179], 0
	v_mfma_f32_16x16x32_bf16 v[112:115], v[168:171], v[176:179], 0
	v_mfma_f32_16x16x32_bf16 v[100:103], v[144:147], v[194:197], 0
	v_mfma_f32_16x16x32_bf16 v[96:99], v[168:171], v[194:197], 0
	v_mfma_f32_16x16x32_bf16 v[84:87], v[144:147], v[202:205], 0
	v_mfma_f32_16x16x32_bf16 v[80:83], v[168:171], v[202:205], 0
	v_mfma_f32_16x16x32_bf16 v[68:71], v[144:147], v[214:217], 0
	v_mfma_f32_16x16x32_bf16 v[64:67], v[168:171], v[214:217], 0
	v_mfma_f32_16x16x32_bf16 v[116:119], v[148:151], v[180:183], v[116:119]
	v_mfma_f32_16x16x32_bf16 v[112:115], v[172:175], v[180:183], v[112:115]
	v_mfma_f32_16x16x32_bf16 v[100:103], v[148:151], v[198:201], v[100:103]
	v_mfma_f32_16x16x32_bf16 v[96:99], v[172:175], v[198:201], v[96:99]
	v_mfma_f32_16x16x32_bf16 v[84:87], v[148:151], v[206:209], v[84:87]
	v_mfma_f32_16x16x32_bf16 v[80:83], v[172:175], v[206:209], v[80:83]
	v_mfma_f32_16x16x32_bf16 v[68:71], v[148:151], v[218:221], v[68:71]
	v_mfma_f32_16x16x32_bf16 v[64:67], v[172:175], v[218:221], v[64:67]
	s_setprio 0
	s_barrier
	s_add_i32 s56, s49, s33
	v_lshl_add_u64 v[184:185], s[36:37], 0, v[154:155]
	s_mov_b32 m0, s56
	ds_read_b128 v[176:179], v193 offset:16384
	ds_read_b128 v[180:183], v193 offset:17408
	ds_read_b128 v[194:197], v193 offset:18432
	ds_read_b128 v[198:201], v193 offset:19456
	ds_read_b128 v[202:205], v193 offset:20480
	ds_read_b128 v[206:209], v193 offset:21504
	ds_read_b128 v[214:217], v193 offset:22528
	ds_read_b128 v[218:221], v193 offset:23552
	global_load_lds_dwordx4 v[184:185], off
	s_add_i32 m0, s56, 0x2000
	s_add_u32 s56, s36, 0x40000
	v_lshl_add_u64 v[210:211], s[36:37], 0, v[158:159]
	s_addc_u32 s57, s37, 0
	s_add_i32 s58, s50, s33
	global_load_lds_dwordx4 v[210:211], off
	v_lshl_add_u64 v[222:223], s[56:57], 0, v[154:155]
	s_mov_b32 m0, s58
	v_lshl_add_u64 v[224:225], s[38:39], 0, v[156:157]
	global_load_lds_dwordx4 v[222:223], off
	v_lshl_add_u64 v[222:223], s[56:57], 0, v[158:159]
	s_add_i32 m0, s58, 0x2000
	s_nop 0
	global_load_lds_dwordx4 v[222:223], off
	v_lshl_add_u64 v[222:223], s[38:39], 0, v[152:153]
	s_mov_b32 m0, s40
	s_nop 0
	global_load_lds_dwordx4 v[222:223], off
	s_mov_b32 m0, s41
	s_nop 0
	global_load_lds_dwordx4 v[224:225], off
	s_waitcnt vmcnt(8)
	s_waitcnt lgkmcnt(0)
	s_barrier
	s_setprio 1
	s_waitcnt lgkmcnt(0)
	v_mfma_f32_16x16x32_bf16 v[60:63], v[128:131], v[176:179], 0
	v_mfma_f32_16x16x32_bf16 v[56:59], v[136:139], v[176:179], 0
	v_mfma_f32_16x16x32_bf16 v[44:47], v[128:131], v[194:197], 0
	v_mfma_f32_16x16x32_bf16 v[40:43], v[136:139], v[194:197], 0
	v_mfma_f32_16x16x32_bf16 v[28:31], v[128:131], v[202:205], 0
	v_mfma_f32_16x16x32_bf16 v[24:27], v[136:139], v[202:205], 0
	v_mfma_f32_16x16x32_bf16 v[12:15], v[128:131], v[214:217], 0
	v_mfma_f32_16x16x32_bf16 v[8:11], v[136:139], v[214:217], 0
	v_mfma_f32_16x16x32_bf16 v[60:63], v[132:135], v[180:183], v[60:63]
	v_mfma_f32_16x16x32_bf16 v[56:59], v[140:143], v[180:183], v[56:59]
	v_mfma_f32_16x16x32_bf16 v[44:47], v[132:135], v[198:201], v[44:47]
	v_mfma_f32_16x16x32_bf16 v[40:43], v[140:143], v[198:201], v[40:43]
	v_mfma_f32_16x16x32_bf16 v[28:31], v[132:135], v[206:209], v[28:31]
	v_mfma_f32_16x16x32_bf16 v[24:27], v[140:143], v[206:209], v[24:27]
	v_mfma_f32_16x16x32_bf16 v[12:15], v[132:135], v[218:221], v[12:15]
	v_mfma_f32_16x16x32_bf16 v[8:11], v[140:143], v[218:221], v[8:11]
	s_setprio 0
	s_setprio 1
	v_mfma_f32_16x16x32_bf16 v[52:55], v[144:147], v[176:179], 0
	v_mfma_f32_16x16x32_bf16 v[48:51], v[168:171], v[176:179], 0
	v_mfma_f32_16x16x32_bf16 v[36:39], v[144:147], v[194:197], 0
	v_mfma_f32_16x16x32_bf16 v[32:35], v[168:171], v[194:197], 0
	v_mfma_f32_16x16x32_bf16 v[20:23], v[144:147], v[202:205], 0
	v_mfma_f32_16x16x32_bf16 v[16:19], v[168:171], v[202:205], 0
	v_mfma_f32_16x16x32_bf16 v[4:7], v[144:147], v[214:217], 0
	v_mfma_f32_16x16x32_bf16 v[0:3], v[168:171], v[214:217], 0
	v_mfma_f32_16x16x32_bf16 v[52:55], v[148:151], v[180:183], v[52:55]
	v_mfma_f32_16x16x32_bf16 v[48:51], v[172:175], v[180:183], v[48:51]
	v_mfma_f32_16x16x32_bf16 v[36:39], v[148:151], v[198:201], v[36:39]
	v_mfma_f32_16x16x32_bf16 v[32:35], v[172:175], v[198:201], v[32:35]
	v_mfma_f32_16x16x32_bf16 v[20:23], v[148:151], v[206:209], v[20:23]
	v_mfma_f32_16x16x32_bf16 v[16:19], v[172:175], v[206:209], v[16:19]
	v_mfma_f32_16x16x32_bf16 v[4:7], v[148:151], v[218:221], v[4:7]
	v_mfma_f32_16x16x32_bf16 v[0:3], v[172:175], v[218:221], v[0:3]
	s_setprio 0
	s_barrier
; #define PG8_STAGE(bufoff, gbase, voff) do { _Pragma("unroll") for (int _i = 0; _i < 2; ++_i) \
;         __builtin_amdgcn_global_load_lds((const unsigned*)((const char*)(gbase) + (voff)[_i]), (PG8_LAS unsigned*)(lds + (bufoff) + ldsw + _i * 8192), 16, 0, 0); } while (0)
; #define PG8_LDA(dst, b, h) do { _Pragma("unroll") for (int m = 0; m < 4; ++m) _Pragma("unroll") for (int k = 0; k < 2; ++k) dst[m][k] = *(const PG8_LAS bf16x8*)(lds + PG8_SA(b, h) + aoff + m * 2048 + k * 1024); } while (0)
; #define PG8_LDB(dst, b, h) do { _Pragma("unroll") for (int n = 0; n < 2; ++n) _Pragma("unroll") for (int k = 0; k < 2; ++k) dst[n][k] = *(const PG8_LAS bf16x8*)(lds + PG8_SB(b, h) + boff + n * 2048 + k * 1024); } while (0)
; #define PG8_MMA(ai, bj, At, Bt) do { __builtin_amdgcn_s_setprio(1); _Pragma("unroll") for (int m = 0; m < 4; ++m) _Pragma("unroll") for (int n = 0; n < 2; ++n) _Pragma("unroll") for (int k = 0; k < 2; ++k) \
;         acc[ai][bj][m][n] = __builtin_amdgcn_mfma_f32_16x16x32_bf16(Bt[n][k], At[m][k], acc[ai][bj][m][n], 0, 0, 0); __builtin_amdgcn_s_setprio(0); } while (0)
; #define PG8_BAR __builtin_amdgcn_s_barrier()
; template <class Epi, class Sched, bool ALIGN_EPI = false, bool SP2 = false>
; __device__ __forceinline__ void gemm_phase(PG8_LAS unsigned char* lds, const Gemm g, const Sched& S, const Epi& E, const int wv  ) {
;     ...
;             PG8_LDB(B0, 0, 0); PG8_LDB(B1, 0, 1); PG8_SCHED; PG8_LDA(At, 0, 0); PG8_STAGE(PG8_SA(1, 1), a1 + hstep, voffA);
;             PG8_WAIT_V(8); PG8_WAIT_L(0); PG8_BAR; PG8_MMA(0, 0, At, B0); PG8_MMA(0, 1, At, B1); PG8_BAR; PG8_SCHED;
;             PG8_LDA(At, 0, 1); PG8_STAGE(PG8_SB(0, 0), b2, voffB); PG8_STAGE(PG8_SB(0, 1), b2 + hstep, voffB); PG8_STAGE(PG8_SA(0, 0), a2, voffA);
;             PG8_WAIT_V(8); PG8_WAIT_L(0); PG8_BAR; PG8_MMA(1, 0, At, B0); PG8_MMA(1, 1, At, B1); PG8_BAR; PG8_SCHED;
;             PG8_LDB(B0, 1, 0); PG8_LDB(B1, 1, 1); PG8_SCHED; PG8_LDA(At, 1, 0); PG8_STAGE(PG8_SA(0, 1), a2 + hstep, voffA);
;             PG8_WAIT_V(8); PG8_WAIT_L(0); PG8_BAR; PG8_MMA(0, 0, At, B0); PG8_MMA(0, 1, At, B1); PG8_BAR; PG8_SCHED;
;             PG8_LDA(At, 1, 1); PG8_STAGE(PG8_SB(1, 0), b3, voffB); PG8_STAGE(PG8_SB(1, 1), b3 + hstep, voffB); PG8_STAGE(PG8_SA(1, 0), a3, voffA);
;             PG8_WAIT_V(8); PG8_WAIT_L(0); PG8_BAR; PG8_MMA(1, 0, At, B0); PG8_MMA(1, 1, At, B1); PG8_BAR; PG8_SCHED;
	s_add_i32 s56, 0, 0x18000
	s_add_i32 s57, 0, 0x1c000
	v_add_u32_e32 v140, s56, v189
	v_add_u32_e32 v172, s57, v189
	ds_read_b128 v[128:131], v140
	ds_read_b128 v[132:135], v140 offset:1024
	ds_read_b128 v[136:139], v140 offset:2048
	ds_read_b128 v[140:143], v140 offset:3072
	ds_read_b128 v[144:147], v172
	ds_read_b128 v[148:151], v172 offset:1024
	ds_read_b128 v[168:171], v172 offset:2048
	ds_read_b128 v[172:175], v172 offset:3072
	s_add_u32 s38, s38, 0x40000
	s_addc_u32 s39, s39, 0
	s_mov_b32 m0, s42
	v_lshl_add_u64 v[226:227], s[38:39], 0, v[152:153]
	ds_read_b128 v[176:179], v193 offset:32768
	ds_read_b128 v[180:183], v193 offset:33792
	ds_read_b128 v[194:197], v193 offset:34816
	ds_read_b128 v[198:201], v193 offset:35840
	ds_read_b128 v[202:205], v193 offset:36864
	ds_read_b128 v[206:209], v193 offset:37888
	ds_read_b128 v[214:217], v193 offset:38912
	ds_read_b128 v[218:221], v193 offset:39936
	global_load_lds_dwordx4 v[226:227], off
	v_lshl_add_u64 v[226:227], s[38:39], 0, v[156:157]
	s_mov_b32 m0, s43
	s_nop 0
	global_load_lds_dwordx4 v[226:227], off
	s_waitcnt vmcnt(8)
	s_waitcnt lgkmcnt(0)
	s_barrier
	s_setprio 1
	s_waitcnt lgkmcnt(0)
	v_mfma_f32_16x16x32_bf16 v[124:127], v[128:131], v[176:179], v[124:127]
	v_mfma_f32_16x16x32_bf16 v[120:123], v[136:139], v[176:179], v[120:123]
	v_mfma_f32_16x16x32_bf16 v[108:111], v[128:131], v[194:197], v[108:111]
	v_mfma_f32_16x16x32_bf16 v[104:107], v[136:139], v[194:197], v[104:107]
	v_mfma_f32_16x16x32_bf16 v[92:95], v[128:131], v[202:205], v[92:95]
	v_mfma_f32_16x16x32_bf16 v[88:91], v[136:139], v[202:205], v[88:91]
	v_mfma_f32_16x16x32_bf16 v[76:79], v[128:131], v[214:217], v[76:79]
	v_mfma_f32_16x16x32_bf16 v[72:75], v[136:139], v[214:217], v[72:75]
	v_mfma_f32_16x16x32_bf16 v[124:127], v[132:135], v[180:183], v[124:127]
	v_mfma_f32_16x16x32_bf16 v[120:123], v[140:143], v[180:183], v[120:123]
	v_mfma_f32_16x16x32_bf16 v[108:111], v[132:135], v[198:201], v[108:111]
	v_mfma_f32_16x16x32_bf16 v[104:107], v[140:143], v[198:201], v[104:107]
	v_mfma_f32_16x16x32_bf16 v[92:95], v[132:135], v[206:209], v[92:95]
	v_mfma_f32_16x16x32_bf16 v[88:91], v[140:143], v[206:209], v[88:91]
	v_mfma_f32_16x16x32_bf16 v[76:79], v[132:135], v[218:221], v[76:79]
	v_mfma_f32_16x16x32_bf16 v[72:75], v[140:143], v[218:221], v[72:75]
	s_setprio 0
	s_setprio 1
	v_mfma_f32_16x16x32_bf16 v[116:119], v[144:147], v[176:179], v[116:119]
	v_mfma_f32_16x16x32_bf16 v[112:115], v[168:171], v[176:179], v[112:115]
	v_mfma_f32_16x16x32_bf16 v[100:103], v[144:147], v[194:197], v[100:103]
	v_mfma_f32_16x16x32_bf16 v[96:99], v[168:171], v[194:197], v[96:99]
	v_mfma_f32_16x16x32_bf16 v[84:87], v[144:147], v[202:205], v[84:87]
	v_mfma_f32_16x16x32_bf16 v[80:83], v[168:171], v[202:205], v[80:83]
	v_mfma_f32_16x16x32_bf16 v[68:71], v[144:147], v[214:217], v[68:71]
	v_mfma_f32_16x16x32_bf16 v[64:67], v[168:171], v[214:217], v[64:67]
	v_mfma_f32_16x16x32_bf16 v[116:119], v[148:151], v[180:183], v[116:119]
	v_mfma_f32_16x16x32_bf16 v[112:115], v[172:175], v[180:183], v[112:115]
	v_mfma_f32_16x16x32_bf16 v[100:103], v[148:151], v[198:201], v[100:103]
	v_mfma_f32_16x16x32_bf16 v[96:99], v[172:175], v[198:201], v[96:99]
	v_mfma_f32_16x16x32_bf16 v[84:87], v[148:151], v[206:209], v[84:87]
	v_mfma_f32_16x16x32_bf16 v[80:83], v[172:175], v[206:209], v[80:83]
	v_mfma_f32_16x16x32_bf16 v[68:71], v[148:151], v[218:221], v[68:71]
	v_mfma_f32_16x16x32_bf16 v[64:67], v[172:175], v[218:221], v[64:67]
	s_setprio 0
	s_barrier
; #define PG8_STAGE(bufoff, gbase, voff) do { _Pragma("unroll") for (int _i = 0; _i < 2; ++_i) \
;         __builtin_amdgcn_global_load_lds((const unsigned*)((const char*)(gbase) + (voff)[_i]), (PG8_LAS unsigned*)(lds + (bufoff) + ldsw + _i * 8192), 16, 0, 0); } while (0)
; #define PG8_LDA(dst, b, h) do { _Pragma("unroll") for (int m = 0; m < 4; ++m) _Pragma("unroll") for (int k = 0; k < 2; ++k) dst[m][k] = *(const PG8_LAS bf16x8*)(lds + PG8_SA(b, h) + aoff + m * 2048 + k * 1024); } while (0)
; #define PG8_LDB(dst, b, h) do { _Pragma("unroll") for (int n = 0; n < 2; ++n) _Pragma("unroll") for (int k = 0; k < 2; ++k) dst[n][k] = *(const PG8_LAS bf16x8*)(lds + PG8_SB(b, h) + boff + n * 2048 + k * 1024); } while (0)
; #define PG8_MMA(ai, bj, At, Bt) do { __builtin_amdgcn_s_setprio(1); _Pragma("unroll") for (int m = 0; m < 4; ++m) _Pragma("unroll") for (int n = 0; n < 2; ++n) _Pragma("unroll") for (int k = 0; k < 2; ++k) \
;         acc[ai][bj][m][n] = __builtin_amdgcn_mfma_f32_16x16x32_bf16(Bt[n][k], At[m][k], acc[ai][bj][m][n], 0, 0, 0); __builtin_amdgcn_s_setprio(0); } while (0)
; #define PG8_BAR __builtin_amdgcn_s_barrier()
; template <class Epi, class Sched, bool ALIGN_EPI = false, bool SP2 = false>
; __device__ __forceinline__ void gemm_phase(PG8_LAS unsigned char* lds, const Gemm g, const Sched& S, const Epi& E, const int wv  ) {
;     ...
;             PG8_LDB(B0, 0, 0); PG8_LDB(B1, 0, 1); PG8_SCHED; PG8_LDA(At, 0, 0); PG8_STAGE(PG8_SA(1, 1), a1 + hstep, voffA);
;             PG8_WAIT_V(8); PG8_WAIT_L(0); PG8_BAR; PG8_MMA(0, 0, At, B0); PG8_MMA(0, 1, At, B1); PG8_BAR; PG8_SCHED;
;             PG8_LDA(At, 0, 1); PG8_STAGE(PG8_SB(0, 0), b2, voffB); PG8_STAGE(PG8_SB(0, 1), b2 + hstep, voffB); PG8_STAGE(PG8_SA(0, 0), a2, voffA);
;             PG8_WAIT_V(8); PG8_WAIT_L(0); PG8_BAR; PG8_MMA(1, 0, At, B0); PG8_MMA(1, 1, At, B1); PG8_BAR; PG8_SCHED;
;             PG8_LDB(B0, 1, 0); PG8_LDB(B1, 1, 1); PG8_SCHED; PG8_LDA(At, 1, 0); PG8_STAGE(PG8_SA(0, 1), a2 + hstep, voffA);
;             PG8_WAIT_V(8); PG8_WAIT_L(0); PG8_BAR; PG8_MMA(0, 0, At, B0); PG8_MMA(0, 1, At, B1); PG8_BAR; PG8_SCHED;
;             PG8_LDA(At, 1, 1); PG8_STAGE(PG8_SB(1, 0), b3, voffB); PG8_STAGE(PG8_SB(1, 1), b3 + hstep, voffB); PG8_STAGE(PG8_SA(1, 0), a3, voffA);
;             PG8_WAIT_V(8); PG8_WAIT_L(0); PG8_BAR; PG8_MMA(1, 0, At, B0); PG8_MMA(1, 1, At, B1); PG8_BAR; PG8_SCHED;
	s_add_i32 s38, s56, s33
	v_lshl_add_u64 v[184:185], v[184:185], 0, s[16:17]
	s_mov_b32 m0, s38
	ds_read_b128 v[176:179], v193 offset:49152
	ds_read_b128 v[180:183], v193 offset:50176
	ds_read_b128 v[194:197], v193 offset:51200
	ds_read_b128 v[198:201], v193 offset:52224
	ds_read_b128 v[202:205], v193 offset:53248
	ds_read_b128 v[206:209], v193 offset:54272
	ds_read_b128 v[214:217], v193 offset:55296
	ds_read_b128 v[218:221], v193 offset:56320
	global_load_lds_dwordx4 v[184:185], off
	s_add_i32 m0, s38, 0x2000
	s_add_u32 s36, s36, 0x40080
	v_lshl_add_u64 v[184:185], v[210:211], 0, s[16:17]
	s_addc_u32 s37, s37, 0
	s_add_i32 s38, s57, s33
	global_load_lds_dwordx4 v[184:185], off
	v_lshl_add_u64 v[184:185], s[36:37], 0, v[154:155]
	s_mov_b32 m0, s38
	s_nop 0
	global_load_lds_dwordx4 v[184:185], off
	v_lshl_add_u64 v[184:185], s[36:37], 0, v[158:159]
	s_add_i32 m0, s38, 0x2000
	s_nop 0
	global_load_lds_dwordx4 v[184:185], off
	v_lshl_add_u64 v[184:185], v[222:223], 0, s[16:17]
	s_mov_b32 m0, s47
	s_nop 0
	global_load_lds_dwordx4 v[184:185], off
	v_lshl_add_u64 v[184:185], v[224:225], 0, s[16:17]
	s_mov_b32 m0, s48
	s_nop 0
	global_load_lds_dwordx4 v[184:185], off
	s_waitcnt vmcnt(8)
	s_waitcnt lgkmcnt(0)
	s_barrier
	s_setprio 1
	s_waitcnt lgkmcnt(0)
	v_mfma_f32_16x16x32_bf16 v[60:63], v[128:131], v[176:179], v[60:63]
	v_mfma_f32_16x16x32_bf16 v[56:59], v[136:139], v[176:179], v[56:59]
	v_mfma_f32_16x16x32_bf16 v[44:47], v[128:131], v[194:197], v[44:47]
	v_mfma_f32_16x16x32_bf16 v[40:43], v[136:139], v[194:197], v[40:43]
	v_mfma_f32_16x16x32_bf16 v[28:31], v[128:131], v[202:205], v[28:31]
	v_mfma_f32_16x16x32_bf16 v[24:27], v[136:139], v[202:205], v[24:27]
	v_mfma_f32_16x16x32_bf16 v[12:15], v[128:131], v[214:217], v[12:15]
	v_mfma_f32_16x16x32_bf16 v[8:11], v[136:139], v[214:217], v[8:11]
	v_mfma_f32_16x16x32_bf16 v[60:63], v[132:135], v[180:183], v[60:63]
	v_mfma_f32_16x16x32_bf16 v[56:59], v[140:143], v[180:183], v[56:59]
	v_mfma_f32_16x16x32_bf16 v[44:47], v[132:135], v[198:201], v[44:47]
	v_mfma_f32_16x16x32_bf16 v[40:43], v[140:143], v[198:201], v[40:43]
	v_mfma_f32_16x16x32_bf16 v[28:31], v[132:135], v[206:209], v[28:31]
	v_mfma_f32_16x16x32_bf16 v[24:27], v[140:143], v[206:209], v[24:27]
	v_mfma_f32_16x16x32_bf16 v[12:15], v[132:135], v[218:221], v[12:15]
	v_mfma_f32_16x16x32_bf16 v[8:11], v[140:143], v[218:221], v[8:11]
	s_setprio 0
	s_setprio 1
	v_mfma_f32_16x16x32_bf16 v[52:55], v[144:147], v[176:179], v[52:55]
	v_mfma_f32_16x16x32_bf16 v[48:51], v[168:171], v[176:179], v[48:51]
	v_mfma_f32_16x16x32_bf16 v[36:39], v[144:147], v[194:197], v[36:39]
	v_mfma_f32_16x16x32_bf16 v[32:35], v[168:171], v[194:197], v[32:35]
	v_mfma_f32_16x16x32_bf16 v[20:23], v[144:147], v[202:205], v[20:23]
	v_mfma_f32_16x16x32_bf16 v[16:19], v[168:171], v[202:205], v[16:19]
	v_mfma_f32_16x16x32_bf16 v[4:7], v[144:147], v[214:217], v[4:7]
	v_mfma_f32_16x16x32_bf16 v[0:3], v[168:171], v[214:217], v[0:3]
	v_mfma_f32_16x16x32_bf16 v[52:55], v[148:151], v[180:183], v[52:55]
	v_mfma_f32_16x16x32_bf16 v[48:51], v[172:175], v[180:183], v[48:51]
	v_mfma_f32_16x16x32_bf16 v[36:39], v[148:151], v[198:201], v[36:39]
	v_mfma_f32_16x16x32_bf16 v[32:35], v[172:175], v[198:201], v[32:35]
	v_mfma_f32_16x16x32_bf16 v[20:23], v[148:151], v[206:209], v[20:23]
	v_mfma_f32_16x16x32_bf16 v[16:19], v[172:175], v[206:209], v[16:19]
	v_mfma_f32_16x16x32_bf16 v[4:7], v[148:151], v[218:221], v[4:7]
	v_mfma_f32_16x16x32_bf16 v[0:3], v[172:175], v[218:221], v[0:3]
	s_setprio 0
	s_barrier
	s_add_i32 s55, s55, 2
	s_add_u32 s34, s34, 0x100
	s_addc_u32 s35, s35, 0
	s_add_u32 s53, s53, 0x100
	s_addc_u32 s54, s54, 0
	s_cmp_gt_u32 s55, 13

; __device__ __forceinline__ unsigned cvt_pk_bf16(float lo, float hi) { unsigned r; asm volatile("v_cvt_pk_bf16_f32 %0, %1, %2" : "=v"(r) : "v"(lo), "v"(hi)); return r; }
;     __device__ __forceinline__ void operator()(const f32x4 (&acc)[2][2][4][2], const Unit& u, int wr, int wc, int fr, int fq) const {
;     ...
;                 for (int bj = 0; bj < 2; ++bj) { const size_t off = (size_t)(row0 + ai * HALF + m * 16) * 1024 + col0 + bj * HALF;
;                     if (BASE_BF16) bw[m][bj] = *(const u32x4*)((const bf16_t*)base + off);
;                     else { bf[m][bj][0] = *(const f32x4*)((const float*)base + off); bf[m][bj][1] = *(const f32x4*)((const float*)base + off + 4); } }
; #pragma unroll
;             for (int m = 0; m < 4; ++m) {
;                 const int row = row0 + ai * HALF + m * 16; const size_t off = (size_t)row * 1024 + col0;
;                 float ss = 0.f;
; #pragma unroll
;                 for (int bj = 0; bj < 2; ++bj) {
;                     f32x4 b0, b1;
;                     if (BASE_BF16) { const u32x4 w = bw[m][bj];
;                         b0 = (f32x4){__builtin_bit_cast(float, w.x << 16), __builtin_bit_cast(float, w.x & 0xffff0000u), __builtin_bit_cast(float, w.y << 16), __builtin_bit_cast(float, w.y & 0xffff0000u)};
;                         b1 = (f32x4){__builtin_bit_cast(float, w.z << 16), __builtin_bit_cast(float, w.z & 0xffff0000u), __builtin_bit_cast(float, w.w << 16), __builtin_bit_cast(float, w.w & 0xffff0000u)}; }
;                     else { b0 = bf[m][bj][0]; b1 = bf[m][bj][1]; }
;                     const f32x4 v0 = acc[ai][bj][m][0] + b0, v1 = acc[ai][bj][m][1] + b1;
;                     ss += (v0[0] * v0[0] + v0[1] * v0[1]) + (v0[2] * v0[2] + v0[3] * v0[3]) + (v1[0] * v1[0] + v1[1] * v1[1]) + (v1[2] * v1[2] + v1[3] * v1[3]);
;                     if (OUT_BF16) { u32x4 w; w.x = cvt_pk_bf16(v0[0], v0[1]); w.y = cvt_pk_bf16(v0[2], v0[3]); w.z = cvt_pk_bf16(v1[0], v1[1]); w.w = cvt_pk_bf16(v1[2], v1[3]);
;                         *(u32x4*)((bf16_t*)out + off + bj * HALF) = w; }
;                     else { *(f32x4*)((float*)out + off + bj * HALF) = v0; *(f32x4*)((float*)out + off + bj * HALF + 4) = v1; }
;                 }
;                 ss += __shfl_xor(ss, 16); ss += __shfl_xor(ss, 32);
;                 if (fq == 0) sspart[(size_t)row * 16 + u.pn * 4 + wc] = ss;
.LBB0_919:
	s_add_u32 s60, s31, 0x40080
	s_addc_u32 s61, s25, 0
	v_lshl_add_u64 v[184:185], s[60:61], 0, v[160:161]
	s_add_i32 m0, s40, 0xc000
	s_nop 0
	global_load_lds_dwordx4 v[184:185], off
	v_lshl_add_u64 v[184:185], s[60:61], 0, v[162:163]
	s_add_i32 m0, s40, 0xe000
	s_nop 0
	global_load_lds_dwordx4 v[184:185], off
	v_lshl_or_b32 v168, s8, 8, v190
	v_lshl_add_u32 v172, s30, 8, v188
	v_ashrrev_i32_e32 v169, 31, v168
	v_lshlrev_b64 v[202:203], 1, v[168:169]
	v_ashrrev_i32_e32 v173, 31, v172
	v_lshl_add_u64 v[170:171], s[12:13], 0, v[202:203]
	v_lshlrev_b64 v[204:205], 11, v[172:173]
	v_lshl_add_u64 v[128:129], v[170:171], 0, v[204:205]
	global_load_dwordx4 v[194:197], v[128:129], off
	global_load_dwordx4 v[198:201], v[128:129], off offset:256
	v_or_b32_e32 v182, 16, v172
	v_or_b32_e32 v178, 32, v172
	v_or_b32_e32 v174, 48, v172
	v_ashrrev_i32_e32 v183, 31, v182
	v_ashrrev_i32_e32 v179, 31, v178
	v_ashrrev_i32_e32 v175, 31, v174
	v_lshlrev_b64 v[184:185], 11, v[182:183]
	v_lshlrev_b64 v[180:181], 11, v[178:179]
	v_lshlrev_b64 v[176:177], 11, v[174:175]
	v_lshl_add_u64 v[128:129], v[170:171], 0, v[184:185]
	v_lshl_add_u64 v[130:131], v[170:171], 0, v[180:181]
	v_lshl_add_u64 v[206:207], v[170:171], 0, v[176:177]
	global_load_dwordx4 v[148:151], v[128:129], off
	global_load_dwordx4 v[144:147], v[128:129], off offset:256
	global_load_dwordx4 v[140:143], v[130:131], off
	global_load_dwordx4 v[136:139], v[130:131], off offset:256
	global_load_dwordx4 v[132:135], v[206:207], off
	s_nop 0
	global_load_dwordx4 v[128:131], v[206:207], off offset:256
	s_lshl_b32 s30, s8, 2
	s_ashr_i32 s31, s30, 31
	s_waitcnt vmcnt(0)
	v_lshlrev_b32_e32 v206, 16, v194
	v_and_b32_e32 v207, 0xffff0000, v194
	v_lshlrev_b32_e32 v194, 16, v195
	v_and_b32_e32 v195, 0xffff0000, v195
	v_lshlrev_b32_e32 v208, 16, v196
	v_and_b32_e32 v209, 0xffff0000, v196
	v_lshlrev_b32_e32 v196, 16, v197
	v_and_b32_e32 v197, 0xffff0000, v197
	v_lshlrev_b32_e32 v210, 16, v198
	v_and_b32_e32 v211, 0xffff0000, v198
	v_lshlrev_b32_e32 v198, 16, v199
	v_and_b32_e32 v199, 0xffff0000, v199
	v_lshlrev_b32_e32 v214, 16, v200
	v_and_b32_e32 v215, 0xffff0000, v200
	v_lshlrev_b32_e32 v200, 16, v201
	v_and_b32_e32 v201, 0xffff0000, v201
	v_pk_add_f32 v[126:127], v[126:127], v[194:195]
	v_pk_add_f32 v[124:125], v[124:125], v[206:207]
	v_pk_add_f32 v[122:123], v[122:123], v[196:197]
	v_pk_add_f32 v[120:121], v[120:121], v[208:209]
	v_pk_add_f32 v[118:119], v[118:119], v[198:199]
	v_pk_add_f32 v[116:117], v[116:117], v[210:211]
	v_pk_add_f32 v[194:195], v[114:115], v[200:201]
	v_pk_add_f32 v[196:197], v[112:113], v[214:215]
	v_mul_f32_e32 v198, v125, v125
	v_mul_f32_e32 v199, v127, v127
	v_mul_f32_e32 v200, v121, v121
	v_mul_f32_e32 v201, v123, v123
	v_cvt_pk_bf16_f32 v112, v124, v125
	v_cvt_pk_bf16_f32 v113, v126, v127
	v_cvt_pk_bf16_f32 v114, v120, v121
	v_cvt_pk_bf16_f32 v115, v122, v123
	v_mul_f32_e32 v121, v117, v117
	v_mul_f32_e32 v123, v119, v119
	v_mul_f32_e32 v125, v197, v197
	v_fmac_f32_e32 v198, v124, v124
	v_fmac_f32_e32 v199, v126, v126
	v_fmac_f32_e32 v121, v116, v116
	v_fmac_f32_e32 v123, v118, v118
	v_mul_f32_e32 v127, v195, v195
	v_fmac_f32_e32 v200, v120, v120
	v_fmac_f32_e32 v125, v196, v196
	v_add_f32_e32 v120, v198, v199
	v_add_f32_e32 v121, v121, v123
	v_fmac_f32_e32 v201, v122, v122
	v_fmac_f32_e32 v127, v194, v194
	v_add_f32_e32 v120, v200, v120
	v_add_f32_e32 v121, v125, v121
	v_add_f32_e32 v120, v201, v120
	v_add_f32_e32 v121, v127, v121
	v_add_f32_e32 v122, v120, v121
	ds_bpermute_b32 v123, v186, v122
	v_lshl_add_u64 v[120:121], s[12:13], 0, v[204:205]
	v_lshl_add_u64 v[120:121], v[120:121], 0, v[202:203]
	ds_bpermute_b32 v240, v253, v112
	ds_bpermute_b32 v241, v253, v113
	ds_bpermute_b32 v242, v253, v114
	ds_bpermute_b32 v243, v253, v115
	v_lshl_add_u64 v[236:237], v[120:121], 0, v[250:251]
	s_waitcnt lgkmcnt(4)
	s_nop 0
	v_add_f32_e32 v112, v122, v123
	ds_bpermute_b32 v113, v187, v112
	v_cvt_pk_bf16_f32 v114, v116, v117
	v_cvt_pk_bf16_f32 v115, v118, v119
	v_cvt_pk_bf16_f32 v116, v196, v197
	v_cvt_pk_bf16_f32 v117, v194, v195
	ds_bpermute_b32 v244, v253, v114
	ds_bpermute_b32 v245, v253, v115
	ds_bpermute_b32 v246, v253, v116
	ds_bpermute_b32 v247, v253, v117
	v_lshl_add_u64 v[238:239], v[120:121], 0, v[250:251]
	s_waitcnt lgkmcnt(4)
	global_store_dwordx4 v[236:237], v[240:243], off
	s_and_saveexec_b64 s[34:35], s[4:5]
	s_cbranch_execz .LBB0_921
	v_lshlrev_b64 v[114:115], 6, v[172:173]
	v_lshl_add_u64 v[114:115], s[14:15], 0, v[114:115]
	v_lshl_add_u64 v[114:115], s[30:31], 2, v[114:115]
	s_lshl_b32 s8, s46, 2
	v_lshl_add_u64 v[114:115], v[114:115], 0, s[8:9]
	s_waitcnt lgkmcnt(4)
	v_add_f32_e32 v112, v112, v113
	global_store_dword v[114:115], v112, off

; #define PG8_STAGE(bufoff, gbase, voff) do { _Pragma("unroll") for (int _i = 0; _i < 2; ++_i) \
;         __builtin_amdgcn_global_load_lds((const unsigned*)((const char*)(gbase) + (voff)[_i]), (PG8_LAS unsigned*)(lds + (bufoff) + ldsw + _i * 8192), 16, 0, 0); } while (0)
; #define PG8_LDA(dst, b, h) do { _Pragma("unroll") for (int m = 0; m < 4; ++m) _Pragma("unroll") for (int k = 0; k < 2; ++k) dst[m][k] = *(const PG8_LAS bf16x8*)(lds + PG8_SA(b, h) + aoff + m * 2048 + k * 1024); } while (0)
; #define PG8_LDB(dst, b, h) do { _Pragma("unroll") for (int n = 0; n < 2; ++n) _Pragma("unroll") for (int k = 0; k < 2; ++k) dst[n][k] = *(const PG8_LAS bf16x8*)(lds + PG8_SB(b, h) + boff + n * 2048 + k * 1024); } while (0)
; #define PG8_WAIT_V(n) asm volatile("s_waitcnt vmcnt(" #n ")" ::: "memory")
; #define PG8_WAIT_L(n) asm volatile("s_waitcnt lgkmcnt(" #n ")" ::: "memory")
; #define PG8_BAR __builtin_amdgcn_s_barrier()
; #define PG8_SCHED __builtin_amdgcn_sched_barrier(0)
; template <class Epi, class Sched, bool ALIGN_EPI = false, bool SP2 = false>
; __device__ __forceinline__ void gemm_phase(PG8_LAS unsigned char* lds, const Gemm g, const Sched& S, const Epi& E, const int wv  ) {
;     ...
;         const bool has_next = S.next(ui + 1, nxt);
;         const char* nA = has_next ? (const char*)g.A + (size_t)nxt.pm * tstep : cA; const char* nB = has_next ? (const char*)g.Bt + (size_t)nxt.pn * tstep : cB;
;         for (int t = 0; t < nt; t += 2) {
;             const bool last = (t == nt - 2);
;             const char* a1 = cA + (size_t)(t + 1) * kstep;
;             const char* a2 = last ? nA : cA + (size_t)(t + 2) * kstep; const char* b2 = last ? nB : cB + (size_t)(t + 2) * kstep;
;             const char* a3 = a2 + kstep; const char* b3 = b2 + kstep;
;             if (last && has_next) S.a_ready(nxt);
;             if constexpr (SP2) {
;             PG8_LDB(B0, 0, 0); PG8_LDB(B1, 0, 1); PG8_SCHED; PG8_LDA(At, 0, 0); PG8_STAGE(PG8_SA(1, 1), a1 + hstep, voffA);
;             PG8_WAIT_V(8); PG8_WAIT_L(0); PG8_BAR; PG8_MMA(0, 0, At, B0); PG8_MMA(0, 1, At, B1); PG8_BAR; PG8_SCHED;
;             PG8_LDA(At, 0, 1); PG8_STAGE(PG8_SB(0, 0), b2, voffB); PG8_STAGE(PG8_SB(0, 1), b2 + hstep, voffB); PG8_STAGE(PG8_SA(0, 0), a2, voffA);
;             PG8_WAIT_V(8); PG8_WAIT_L(0); PG8_BAR; PG8_MMA(1, 0, At, B0); PG8_MMA(1, 1, At, B1); PG8_BAR; PG8_SCHED;
.LBB0_1035:
	s_ashr_i32 s29, s28, 31
	s_lshl_b64 s[30:31], s[28:29], 19
	s_add_u32 s30, s21, s30
	s_addc_u32 s31, s33, s31
	s_and_b64 s[34:35], s[4:5], exec
	s_cselect_b32 s7, s31, s1
	s_cselect_b32 s9, s30, s0
	s_ashr_i32 s27, s26, 31
	s_lshl_b64 s[34:35], s[26:27], 19
	s_add_u32 s34, s42, s34
	s_addc_u32 s35, s43, s35
	s_and_b64 s[40:41], s[4:5], exec
	s_cselect_b32 s18, s35, s39
	s_cselect_b32 s25, s34, s38
	s_add_u32 s0, s0, 0x40080
	s_addc_u32 s1, s1, 0
	s_add_u32 s27, s38, 0x100
	s_addc_u32 s29, s39, 0
	s_mov_b32 s56, -2
	s_cmp_eq_u32 s48, 1
	s_cbranch_scc1 .LpeelA_1036
	ds_read_b128 v[144:147], v152
	ds_read_b128 v[158:161], v152 offset:1024
	ds_read_b128 v[162:165], v152 offset:2048
	ds_read_b128 v[166:169], v152 offset:3072
	ds_read_b128 v[170:173], v153
	ds_read_b128 v[174:177], v153 offset:1024
	ds_read_b128 v[178:181], v153 offset:2048
	ds_read_b128 v[182:185], v153 offset:3072
	s_add_u32 s38, s0, 0xfffc0080
	s_addc_u32 s39, s1, -1
	s_cmp_eq_u32 s56, 12
	s_cselect_b32 s41, s7, s39
	s_cselect_b32 s40, s9, s38
	s_cselect_b32 s39, s18, s29
	s_cselect_b32 s38, s25, s27
	ds_read_b128 v[186:189], v154
	ds_read_b128 v[190:193], v154 offset:1024
	ds_read_b128 v[194:197], v154 offset:2048
	ds_read_b128 v[198:201], v154 offset:3072
	ds_read_b128 v[202:205], v154 offset:4096
	ds_read_b128 v[206:209], v154 offset:5120
	ds_read_b128 v[214:217], v154 offset:6144
	ds_read_b128 v[218:221], v154 offset:7168
	s_waitcnt vmcnt(24)
	s_waitcnt lgkmcnt(0)
	s_barrier
	s_setprio 1
	s_waitcnt lgkmcnt(0)
	v_mfma_f32_16x16x32_bf16 v[124:127], v[144:147], v[186:189], 0
	v_mfma_f32_16x16x32_bf16 v[120:123], v[162:165], v[186:189], 0
	v_mfma_f32_16x16x32_bf16 v[108:111], v[144:147], v[194:197], 0
	v_mfma_f32_16x16x32_bf16 v[104:107], v[162:165], v[194:197], 0
	v_mfma_f32_16x16x32_bf16 v[92:95], v[144:147], v[202:205], 0
	v_mfma_f32_16x16x32_bf16 v[88:91], v[162:165], v[202:205], 0
	v_mfma_f32_16x16x32_bf16 v[76:79], v[144:147], v[214:217], 0
	v_mfma_f32_16x16x32_bf16 v[72:75], v[162:165], v[214:217], 0
	v_mfma_f32_16x16x32_bf16 v[124:127], v[158:161], v[190:193], v[124:127]
	v_mfma_f32_16x16x32_bf16 v[120:123], v[166:169], v[190:193], v[120:123]
	v_mfma_f32_16x16x32_bf16 v[108:111], v[158:161], v[198:201], v[108:111]
	v_mfma_f32_16x16x32_bf16 v[104:107], v[166:169], v[198:201], v[104:107]
	v_mfma_f32_16x16x32_bf16 v[92:95], v[158:161], v[206:209], v[92:95]
	v_mfma_f32_16x16x32_bf16 v[88:91], v[166:169], v[206:209], v[88:91]
	v_mfma_f32_16x16x32_bf16 v[76:79], v[158:161], v[218:221], v[76:79]
	v_mfma_f32_16x16x32_bf16 v[72:75], v[166:169], v[218:221], v[72:75]
	s_setprio 0
	s_setprio 1
	v_mfma_f32_16x16x32_bf16 v[116:119], v[170:173], v[186:189], 0
	v_mfma_f32_16x16x32_bf16 v[112:115], v[178:181], v[186:189], 0
	v_mfma_f32_16x16x32_bf16 v[100:103], v[170:173], v[194:197], 0
	v_mfma_f32_16x16x32_bf16 v[96:99], v[178:181], v[194:197], 0
	v_mfma_f32_16x16x32_bf16 v[84:87], v[170:173], v[202:205], 0
	v_mfma_f32_16x16x32_bf16 v[80:83], v[178:181], v[202:205], 0
	v_mfma_f32_16x16x32_bf16 v[68:71], v[170:173], v[214:217], 0
	v_mfma_f32_16x16x32_bf16 v[64:67], v[178:181], v[214:217], 0
	v_mfma_f32_16x16x32_bf16 v[116:119], v[174:177], v[190:193], v[116:119]
	v_mfma_f32_16x16x32_bf16 v[112:115], v[182:185], v[190:193], v[112:115]
	v_mfma_f32_16x16x32_bf16 v[100:103], v[174:177], v[198:201], v[100:103]
	v_mfma_f32_16x16x32_bf16 v[96:99], v[182:185], v[198:201], v[96:99]
	v_mfma_f32_16x16x32_bf16 v[84:87], v[174:177], v[206:209], v[84:87]
	v_mfma_f32_16x16x32_bf16 v[80:83], v[182:185], v[206:209], v[80:83]
	v_mfma_f32_16x16x32_bf16 v[68:71], v[174:177], v[218:221], v[68:71]
	v_mfma_f32_16x16x32_bf16 v[64:67], v[182:185], v[218:221], v[64:67]
	s_setprio 0
	s_barrier
	s_add_i32 s57, s51, s20
	v_lshl_add_u64 v[210:211], s[38:39], 0, v[130:131]
	s_mov_b32 m0, s57
	ds_read_b128 v[186:189], v154 offset:16384
	ds_read_b128 v[190:193], v154 offset:17408
	ds_read_b128 v[194:197], v154 offset:18432
	ds_read_b128 v[198:201], v154 offset:19456
	ds_read_b128 v[202:205], v154 offset:20480
	ds_read_b128 v[206:209], v154 offset:21504
	ds_read_b128 v[214:217], v154 offset:22528
	ds_read_b128 v[218:221], v154 offset:23552
	global_load_lds_dwordx4 v[210:211], off
	s_add_i32 m0, s57, 0x2000
	s_add_u32 s58, s38, 0x40000
	v_lshl_add_u64 v[222:223], s[38:39], 0, v[134:135]
	s_addc_u32 s59, s39, 0
	s_add_i32 s57, s52, s20
	global_load_lds_dwordx4 v[222:223], off
	v_lshl_add_u64 v[224:225], s[58:59], 0, v[130:131]
	s_mov_b32 m0, s57
	v_lshl_add_u64 v[226:227], s[40:41], 0, v[132:133]
	global_load_lds_dwordx4 v[224:225], off
	v_lshl_add_u64 v[224:225], s[58:59], 0, v[134:135]
	s_add_i32 m0, s57, 0x2000
	s_nop 0
	global_load_lds_dwordx4 v[224:225], off
	v_lshl_add_u64 v[224:225], s[40:41], 0, v[128:129]
	s_mov_b32 m0, s44
	s_nop 0
	global_load_lds_dwordx4 v[224:225], off
	s_mov_b32 m0, s45
	s_nop 0
	global_load_lds_dwordx4 v[226:227], off
	s_waitcnt vmcnt(24)
	s_waitcnt lgkmcnt(0)
	s_barrier
; #define PG8_STAGE(bufoff, gbase, voff) do { _Pragma("unroll") for (int _i = 0; _i < 2; ++_i) \
;         __builtin_amdgcn_global_load_lds((const unsigned*)((const char*)(gbase) + (voff)[_i]), (PG8_LAS unsigned*)(lds + (bufoff) + ldsw + _i * 8192), 16, 0, 0); } while (0)
; #define PG8_LDA(dst, b, h) do { _Pragma("unroll") for (int m = 0; m < 4; ++m) _Pragma("unroll") for (int k = 0; k < 2; ++k) dst[m][k] = *(const PG8_LAS bf16x8*)(lds + PG8_SA(b, h) + aoff + m * 2048 + k * 1024); } while (0)
; #define PG8_LDB(dst, b, h) do { _Pragma("unroll") for (int n = 0; n < 2; ++n) _Pragma("unroll") for (int k = 0; k < 2; ++k) dst[n][k] = *(const PG8_LAS bf16x8*)(lds + PG8_SB(b, h) + boff + n * 2048 + k * 1024); } while (0)
; #define PG8_MMA(ai, bj, At, Bt) do { __builtin_amdgcn_s_setprio(1); _Pragma("unroll") for (int m = 0; m < 4; ++m) _Pragma("unroll") for (int n = 0; n < 2; ++n) _Pragma("unroll") for (int k = 0; k < 2; ++k) \
;         acc[ai][bj][m][n] = __builtin_amdgcn_mfma_f32_16x16x32_bf16(Bt[n][k], At[m][k], acc[ai][bj][m][n], 0, 0, 0); __builtin_amdgcn_s_setprio(0); } while (0)
; #define PG8_BAR __builtin_amdgcn_s_barrier()
; template <class Epi, class Sched, bool ALIGN_EPI = false, bool SP2 = false>
; __device__ __forceinline__ void gemm_phase(PG8_LAS unsigned char* lds, const Gemm g, const Sched& S, const Epi& E, const int wv  ) {
;     ...
;             PG8_LDB(B0, 0, 0); PG8_LDB(B1, 0, 1); PG8_SCHED; PG8_LDA(At, 0, 0); PG8_STAGE(PG8_SA(1, 1), a1 + hstep, voffA);
;             PG8_WAIT_V(8); PG8_WAIT_L(0); PG8_BAR; PG8_MMA(0, 0, At, B0); PG8_MMA(0, 1, At, B1); PG8_BAR; PG8_SCHED;
;             PG8_LDA(At, 0, 1); PG8_STAGE(PG8_SB(0, 0), b2, voffB); PG8_STAGE(PG8_SB(0, 1), b2 + hstep, voffB); PG8_STAGE(PG8_SA(0, 0), a2, voffA);
;             PG8_WAIT_V(8); PG8_WAIT_L(0); PG8_BAR; PG8_MMA(1, 0, At, B0); PG8_MMA(1, 1, At, B1); PG8_BAR; PG8_SCHED;
;             PG8_LDB(B0, 1, 0); PG8_LDB(B1, 1, 1); PG8_SCHED; PG8_LDA(At, 1, 0); PG8_STAGE(PG8_SA(0, 1), a2 + hstep, voffA);
;             PG8_WAIT_V(8); PG8_WAIT_L(0); PG8_BAR; PG8_MMA(0, 0, At, B0); PG8_MMA(0, 1, At, B1); PG8_BAR; PG8_SCHED;
;             PG8_LDA(At, 1, 1); PG8_STAGE(PG8_SB(1, 0), b3, voffB); PG8_STAGE(PG8_SB(1, 1), b3 + hstep, voffB); PG8_STAGE(PG8_SA(1, 0), a3, voffA);
;             PG8_WAIT_V(8); PG8_WAIT_L(0); PG8_BAR; PG8_MMA(1, 0, At, B0); PG8_MMA(1, 1, At, B1); PG8_BAR; PG8_SCHED;
	s_setprio 1
	s_waitcnt lgkmcnt(0)
	v_mfma_f32_16x16x32_bf16 v[60:63], v[144:147], v[186:189], 0
	v_mfma_f32_16x16x32_bf16 v[56:59], v[162:165], v[186:189], 0
	v_mfma_f32_16x16x32_bf16 v[44:47], v[144:147], v[194:197], 0
	v_mfma_f32_16x16x32_bf16 v[40:43], v[162:165], v[194:197], 0
	v_mfma_f32_16x16x32_bf16 v[28:31], v[144:147], v[202:205], 0
	v_mfma_f32_16x16x32_bf16 v[24:27], v[162:165], v[202:205], 0
	v_mfma_f32_16x16x32_bf16 v[12:15], v[144:147], v[214:217], 0
	v_mfma_f32_16x16x32_bf16 v[8:11], v[162:165], v[214:217], 0
	v_mfma_f32_16x16x32_bf16 v[60:63], v[158:161], v[190:193], v[60:63]
	v_mfma_f32_16x16x32_bf16 v[56:59], v[166:169], v[190:193], v[56:59]
	v_mfma_f32_16x16x32_bf16 v[44:47], v[158:161], v[198:201], v[44:47]
	v_mfma_f32_16x16x32_bf16 v[40:43], v[166:169], v[198:201], v[40:43]
	v_mfma_f32_16x16x32_bf16 v[28:31], v[158:161], v[206:209], v[28:31]
	v_mfma_f32_16x16x32_bf16 v[24:27], v[166:169], v[206:209], v[24:27]
	v_mfma_f32_16x16x32_bf16 v[12:15], v[158:161], v[218:221], v[12:15]
	v_mfma_f32_16x16x32_bf16 v[8:11], v[166:169], v[218:221], v[8:11]
	s_setprio 0
	s_setprio 1
	v_mfma_f32_16x16x32_bf16 v[52:55], v[170:173], v[186:189], 0
	v_mfma_f32_16x16x32_bf16 v[48:51], v[178:181], v[186:189], 0
	v_mfma_f32_16x16x32_bf16 v[36:39], v[170:173], v[194:197], 0
	v_mfma_f32_16x16x32_bf16 v[32:35], v[178:181], v[194:197], 0
	v_mfma_f32_16x16x32_bf16 v[20:23], v[170:173], v[202:205], 0
	v_mfma_f32_16x16x32_bf16 v[16:19], v[178:181], v[202:205], 0
	v_mfma_f32_16x16x32_bf16 v[4:7], v[170:173], v[214:217], 0
	v_mfma_f32_16x16x32_bf16 v[0:3], v[178:181], v[214:217], 0
	v_mfma_f32_16x16x32_bf16 v[52:55], v[174:177], v[190:193], v[52:55]
	v_mfma_f32_16x16x32_bf16 v[48:51], v[182:185], v[190:193], v[48:51]
	v_mfma_f32_16x16x32_bf16 v[36:39], v[174:177], v[198:201], v[36:39]
	v_mfma_f32_16x16x32_bf16 v[32:35], v[182:185], v[198:201], v[32:35]
	v_mfma_f32_16x16x32_bf16 v[20:23], v[174:177], v[206:209], v[20:23]
	v_mfma_f32_16x16x32_bf16 v[16:19], v[182:185], v[206:209], v[16:19]
	v_mfma_f32_16x16x32_bf16 v[4:7], v[174:177], v[218:221], v[4:7]
	v_mfma_f32_16x16x32_bf16 v[0:3], v[182:185], v[218:221], v[0:3]
	s_setprio 0
	s_barrier
	s_add_i32 s57, 0, 0x18000
	v_add_u32_e32 v157, s57, v149
	s_add_i32 s58, 0, 0x1c000
	ds_read_b128 v[144:147], v157
	ds_read_b128 v[158:161], v157 offset:1024
	ds_read_b128 v[162:165], v157 offset:2048
	ds_read_b128 v[166:169], v157 offset:3072
	v_add_u32_e32 v157, s58, v149
	ds_read_b128 v[170:173], v157
	ds_read_b128 v[174:177], v157 offset:1024
	ds_read_b128 v[178:181], v157 offset:2048
	ds_read_b128 v[182:185], v157 offset:3072
	s_add_u32 s40, s40, 0x40000
	s_addc_u32 s41, s41, 0
	s_mov_b32 m0, s46
	v_lshl_add_u64 v[228:229], s[40:41], 0, v[128:129]
	ds_read_b128 v[186:189], v154 offset:32768
	ds_read_b128 v[190:193], v154 offset:33792
	ds_read_b128 v[194:197], v154 offset:34816
	ds_read_b128 v[198:201], v154 offset:35840
	ds_read_b128 v[202:205], v154 offset:36864
	ds_read_b128 v[206:209], v154 offset:37888
	ds_read_b128 v[214:217], v154 offset:38912
	ds_read_b128 v[218:221], v154 offset:39936
	global_load_lds_dwordx4 v[228:229], off
	v_lshl_add_u64 v[228:229], s[40:41], 0, v[132:133]
	s_mov_b32 m0, s47
	s_nop 0
	global_load_lds_dwordx4 v[228:229], off
	s_waitcnt vmcnt(24)
	s_waitcnt lgkmcnt(0)
	s_barrier
	s_setprio 1
	s_waitcnt lgkmcnt(0)
	v_mfma_f32_16x16x32_bf16 v[124:127], v[144:147], v[186:189], v[124:127]
	v_mfma_f32_16x16x32_bf16 v[120:123], v[162:165], v[186:189], v[120:123]
	v_mfma_f32_16x16x32_bf16 v[108:111], v[144:147], v[194:197], v[108:111]
	v_mfma_f32_16x16x32_bf16 v[104:107], v[162:165], v[194:197], v[104:107]
	v_mfma_f32_16x16x32_bf16 v[92:95], v[144:147], v[202:205], v[92:95]
	v_mfma_f32_16x16x32_bf16 v[88:91], v[162:165], v[202:205], v[88:91]
	v_mfma_f32_16x16x32_bf16 v[76:79], v[144:147], v[214:217], v[76:79]
	v_mfma_f32_16x16x32_bf16 v[72:75], v[162:165], v[214:217], v[72:75]
	v_mfma_f32_16x16x32_bf16 v[124:127], v[158:161], v[190:193], v[124:127]
	v_mfma_f32_16x16x32_bf16 v[120:123], v[166:169], v[190:193], v[120:123]
	v_mfma_f32_16x16x32_bf16 v[108:111], v[158:161], v[198:201], v[108:111]
	v_mfma_f32_16x16x32_bf16 v[104:107], v[166:169], v[198:201], v[104:107]
	v_mfma_f32_16x16x32_bf16 v[92:95], v[158:161], v[206:209], v[92:95]
	v_mfma_f32_16x16x32_bf16 v[88:91], v[166:169], v[206:209], v[88:91]
	v_mfma_f32_16x16x32_bf16 v[76:79], v[158:161], v[218:221], v[76:79]
	v_mfma_f32_16x16x32_bf16 v[72:75], v[166:169], v[218:221], v[72:75]
	s_setprio 0
	s_setprio 1
	v_mfma_f32_16x16x32_bf16 v[116:119], v[170:173], v[186:189], v[116:119]
	v_mfma_f32_16x16x32_bf16 v[112:115], v[178:181], v[186:189], v[112:115]
	v_mfma_f32_16x16x32_bf16 v[100:103], v[170:173], v[194:197], v[100:103]
	v_mfma_f32_16x16x32_bf16 v[96:99], v[178:181], v[194:197], v[96:99]
	v_mfma_f32_16x16x32_bf16 v[84:87], v[170:173], v[202:205], v[84:87]
	v_mfma_f32_16x16x32_bf16 v[80:83], v[178:181], v[202:205], v[80:83]
	v_mfma_f32_16x16x32_bf16 v[68:71], v[170:173], v[214:217], v[68:71]
	v_mfma_f32_16x16x32_bf16 v[64:67], v[178:181], v[214:217], v[64:67]
	v_mfma_f32_16x16x32_bf16 v[116:119], v[174:177], v[190:193], v[116:119]
	v_mfma_f32_16x16x32_bf16 v[112:115], v[182:185], v[190:193], v[112:115]
	v_mfma_f32_16x16x32_bf16 v[100:103], v[174:177], v[198:201], v[100:103]
	v_mfma_f32_16x16x32_bf16 v[96:99], v[182:185], v[198:201], v[96:99]
	v_mfma_f32_16x16x32_bf16 v[84:87], v[174:177], v[206:209], v[84:87]
	v_mfma_f32_16x16x32_bf16 v[80:83], v[182:185], v[206:209], v[80:83]
	v_mfma_f32_16x16x32_bf16 v[68:71], v[174:177], v[218:221], v[68:71]
	v_mfma_f32_16x16x32_bf16 v[64:67], v[182:185], v[218:221], v[64:67]
	s_setprio 0
	s_barrier
; #define PG8_STAGE(bufoff, gbase, voff) do { _Pragma("unroll") for (int _i = 0; _i < 2; ++_i) \
;         __builtin_amdgcn_global_load_lds((const unsigned*)((const char*)(gbase) + (voff)[_i]), (PG8_LAS unsigned*)(lds + (bufoff) + ldsw + _i * 8192), 16, 0, 0); } while (0)
; #define PG8_LDA(dst, b, h) do { _Pragma("unroll") for (int m = 0; m < 4; ++m) _Pragma("unroll") for (int k = 0; k < 2; ++k) dst[m][k] = *(const PG8_LAS bf16x8*)(lds + PG8_SA(b, h) + aoff + m * 2048 + k * 1024); } while (0)
; #define PG8_LDB(dst, b, h) do { _Pragma("unroll") for (int n = 0; n < 2; ++n) _Pragma("unroll") for (int k = 0; k < 2; ++k) dst[n][k] = *(const PG8_LAS bf16x8*)(lds + PG8_SB(b, h) + boff + n * 2048 + k * 1024); } while (0)
; #define PG8_WAIT_V(n) asm volatile("s_waitcnt vmcnt(" #n ")" ::: "memory")
; #define PG8_BAR __builtin_amdgcn_s_barrier()
; template <class Epi, class Sched, bool ALIGN_EPI = false, bool SP2 = false>
; __device__ __forceinline__ void gemm_phase(PG8_LAS unsigned char* lds, const Gemm g, const Sched& S, const Epi& E, const int wv  ) {
;     ...
;         for (int t = 0; t < nt; t += 2) {
;             const bool last = (t == nt - 2);
;             const char* a1 = cA + (size_t)(t + 1) * kstep;
;             const char* a2 = last ? nA : cA + (size_t)(t + 2) * kstep; const char* b2 = last ? nB : cB + (size_t)(t + 2) * kstep;
;     ...
;             PG8_LDB(B0, 0, 0); PG8_LDB(B1, 0, 1); PG8_SCHED; PG8_LDA(At, 0, 0); PG8_STAGE(PG8_SA(1, 1), a1 + hstep, voffA);
;             PG8_WAIT_V(8); PG8_WAIT_L(0); PG8_BAR; PG8_MMA(0, 0, At, B0); PG8_MMA(0, 1, At, B1); PG8_BAR; PG8_SCHED;
;             PG8_LDA(At, 0, 1); PG8_STAGE(PG8_SB(0, 0), b2, voffB); PG8_STAGE(PG8_SB(0, 1), b2 + hstep, voffB); PG8_STAGE(PG8_SA(0, 0), a2, voffA);
;             PG8_WAIT_V(8); PG8_WAIT_L(0); PG8_BAR; PG8_MMA(1, 0, At, B0); PG8_MMA(1, 1, At, B1); PG8_BAR; PG8_SCHED;
;             PG8_LDB(B0, 1, 0); PG8_LDB(B1, 1, 1); PG8_SCHED; PG8_LDA(At, 1, 0); PG8_STAGE(PG8_SA(0, 1), a2 + hstep, voffA);
;             PG8_WAIT_V(8); PG8_WAIT_L(0); PG8_BAR; PG8_MMA(0, 0, At, B0); PG8_MMA(0, 1, At, B1); PG8_BAR; PG8_SCHED;
;             PG8_LDA(At, 1, 1); PG8_STAGE(PG8_SB(1, 0), b3, voffB); PG8_STAGE(PG8_SB(1, 1), b3 + hstep, voffB); PG8_STAGE(PG8_SA(1, 0), a3, voffA);
;             PG8_WAIT_V(8); PG8_WAIT_L(0); PG8_BAR; PG8_MMA(1, 0, At, B0); PG8_MMA(1, 1, At, B1); PG8_BAR; PG8_SCHED;
	s_add_i32 s40, s57, s20
	v_lshl_add_u64 v[210:211], v[210:211], 0, s[16:17]
	s_mov_b32 m0, s40
	ds_read_b128 v[186:189], v154 offset:49152
	ds_read_b128 v[190:193], v154 offset:50176
	ds_read_b128 v[194:197], v154 offset:51200
	ds_read_b128 v[198:201], v154 offset:52224
	ds_read_b128 v[202:205], v154 offset:53248
	ds_read_b128 v[206:209], v154 offset:54272
	ds_read_b128 v[214:217], v154 offset:55296
	ds_read_b128 v[218:221], v154 offset:56320
	global_load_lds_dwordx4 v[210:211], off
	s_add_i32 m0, s40, 0x2000
	s_add_u32 s38, s38, 0x40080
	v_lshl_add_u64 v[210:211], v[222:223], 0, s[16:17]
	s_addc_u32 s39, s39, 0
	s_add_i32 s40, s58, s20
	global_load_lds_dwordx4 v[210:211], off
	v_lshl_add_u64 v[210:211], s[38:39], 0, v[130:131]
	s_mov_b32 m0, s40
	s_nop 0
	global_load_lds_dwordx4 v[210:211], off
	v_lshl_add_u64 v[210:211], s[38:39], 0, v[134:135]
	s_add_i32 m0, s40, 0x2000
	s_nop 0
	global_load_lds_dwordx4 v[210:211], off
	v_lshl_add_u64 v[210:211], v[224:225], 0, s[16:17]
	s_mov_b32 m0, s49
	s_nop 0
	global_load_lds_dwordx4 v[210:211], off
	v_lshl_add_u64 v[210:211], v[226:227], 0, s[16:17]
	s_mov_b32 m0, s50
	s_nop 0
	global_load_lds_dwordx4 v[210:211], off
	s_waitcnt vmcnt(8)
	s_waitcnt lgkmcnt(0)
	s_barrier
	s_setprio 1
	s_waitcnt lgkmcnt(0)
	v_mfma_f32_16x16x32_bf16 v[60:63], v[144:147], v[186:189], v[60:63]
	v_mfma_f32_16x16x32_bf16 v[56:59], v[162:165], v[186:189], v[56:59]
	v_mfma_f32_16x16x32_bf16 v[44:47], v[144:147], v[194:197], v[44:47]
	v_mfma_f32_16x16x32_bf16 v[40:43], v[162:165], v[194:197], v[40:43]
	v_mfma_f32_16x16x32_bf16 v[28:31], v[144:147], v[202:205], v[28:31]
	v_mfma_f32_16x16x32_bf16 v[24:27], v[162:165], v[202:205], v[24:27]
	v_mfma_f32_16x16x32_bf16 v[12:15], v[144:147], v[214:217], v[12:15]
	v_mfma_f32_16x16x32_bf16 v[8:11], v[162:165], v[214:217], v[8:11]
	v_mfma_f32_16x16x32_bf16 v[60:63], v[158:161], v[190:193], v[60:63]
	v_mfma_f32_16x16x32_bf16 v[56:59], v[166:169], v[190:193], v[56:59]
	v_mfma_f32_16x16x32_bf16 v[44:47], v[158:161], v[198:201], v[44:47]
	v_mfma_f32_16x16x32_bf16 v[40:43], v[166:169], v[198:201], v[40:43]
	v_mfma_f32_16x16x32_bf16 v[28:31], v[158:161], v[206:209], v[28:31]
	v_mfma_f32_16x16x32_bf16 v[24:27], v[166:169], v[206:209], v[24:27]
	v_mfma_f32_16x16x32_bf16 v[12:15], v[158:161], v[218:221], v[12:15]
	v_mfma_f32_16x16x32_bf16 v[8:11], v[166:169], v[218:221], v[8:11]
	s_setprio 0
	s_setprio 1
	v_mfma_f32_16x16x32_bf16 v[52:55], v[170:173], v[186:189], v[52:55]
	v_mfma_f32_16x16x32_bf16 v[48:51], v[178:181], v[186:189], v[48:51]
	v_mfma_f32_16x16x32_bf16 v[36:39], v[170:173], v[194:197], v[36:39]
	v_mfma_f32_16x16x32_bf16 v[32:35], v[178:181], v[194:197], v[32:35]
	v_mfma_f32_16x16x32_bf16 v[20:23], v[170:173], v[202:205], v[20:23]
	v_mfma_f32_16x16x32_bf16 v[16:19], v[178:181], v[202:205], v[16:19]
	v_mfma_f32_16x16x32_bf16 v[4:7], v[170:173], v[214:217], v[4:7]
	v_mfma_f32_16x16x32_bf16 v[0:3], v[178:181], v[214:217], v[0:3]
	v_mfma_f32_16x16x32_bf16 v[52:55], v[174:177], v[190:193], v[52:55]
	v_mfma_f32_16x16x32_bf16 v[48:51], v[182:185], v[190:193], v[48:51]
	v_mfma_f32_16x16x32_bf16 v[36:39], v[174:177], v[198:201], v[36:39]
	v_mfma_f32_16x16x32_bf16 v[32:35], v[182:185], v[198:201], v[32:35]
	v_mfma_f32_16x16x32_bf16 v[20:23], v[174:177], v[206:209], v[20:23]
	v_mfma_f32_16x16x32_bf16 v[16:19], v[182:185], v[206:209], v[16:19]
	v_mfma_f32_16x16x32_bf16 v[4:7], v[174:177], v[218:221], v[4:7]
	v_mfma_f32_16x16x32_bf16 v[0:3], v[182:185], v[218:221], v[0:3]
	s_setprio 0
	s_barrier
	s_add_i32 s56, s56, 2
	s_add_u32 s0, s0, 0x100
	s_addc_u32 s1, s1, 0
	s_add_u32 s27, s27, 0x100
	s_addc_u32 s29, s29, 0
	s_cmp_gt_u32 s56, 13
	s_branch .LBB0_1036
.LpeelA_1036:
	ds_read_b128 v[144:147], v152
	ds_read_b128 v[158:161], v152 offset:1024
	ds_read_b128 v[162:165], v152 offset:2048
	ds_read_b128 v[166:169], v152 offset:3072
	ds_read_b128 v[170:173], v153
	ds_read_b128 v[174:177], v153 offset:1024
	ds_read_b128 v[178:181], v153 offset:2048
	ds_read_b128 v[182:185], v153 offset:3072
	s_add_u32 s38, s0, 0xfffc0080
	s_addc_u32 s39, s1, -1
	s_cmp_eq_u32 s56, 12
	s_cselect_b32 s41, s7, s39
	s_cselect_b32 s40, s9, s38
	s_cselect_b32 s39, s18, s29
	s_cselect_b32 s38, s25, s27
	v_lshl_add_u64 v[210:211], s[0:1], 0, v[136:137]
	s_add_i32 m0, s44, 0xc000
	ds_read_b128 v[186:189], v154
	ds_read_b128 v[190:193], v154 offset:1024
	ds_read_b128 v[194:197], v154 offset:2048
	ds_read_b128 v[198:201], v154 offset:3072
	ds_read_b128 v[202:205], v154 offset:4096
	ds_read_b128 v[206:209], v154 offset:5120
	ds_read_b128 v[214:217], v154 offset:6144
	ds_read_b128 v[218:221], v154 offset:7168
	global_load_lds_dwordx4 v[210:211], off
	v_lshl_add_u64 v[210:211], s[0:1], 0, v[138:139]
	s_add_i32 m0, s44, 0xe000
	s_nop 0
	global_load_lds_dwordx4 v[210:211], off
	s_waitcnt vmcnt(8)
	s_waitcnt lgkmcnt(0)
	s_barrier
; #define PG8_STAGE(bufoff, gbase, voff) do { _Pragma("unroll") for (int _i = 0; _i < 2; ++_i) \
;         __builtin_amdgcn_global_load_lds((const unsigned*)((const char*)(gbase) + (voff)[_i]), (PG8_LAS unsigned*)(lds + (bufoff) + ldsw + _i * 8192), 16, 0, 0); } while (0)
; #define PG8_LDA(dst, b, h) do { _Pragma("unroll") for (int m = 0; m < 4; ++m) _Pragma("unroll") for (int k = 0; k < 2; ++k) dst[m][k] = *(const PG8_LAS bf16x8*)(lds + PG8_SA(b, h) + aoff + m * 2048 + k * 1024); } while (0)
; #define PG8_LDB(dst, b, h) do { _Pragma("unroll") for (int n = 0; n < 2; ++n) _Pragma("unroll") for (int k = 0; k < 2; ++k) dst[n][k] = *(const PG8_LAS bf16x8*)(lds + PG8_SB(b, h) + boff + n * 2048 + k * 1024); } while (0)
; #define PG8_MMA(ai, bj, At, Bt) do { __builtin_amdgcn_s_setprio(1); _Pragma("unroll") for (int m = 0; m < 4; ++m) _Pragma("unroll") for (int n = 0; n < 2; ++n) _Pragma("unroll") for (int k = 0; k < 2; ++k) \
;         acc[ai][bj][m][n] = __builtin_amdgcn_mfma_f32_16x16x32_bf16(Bt[n][k], At[m][k], acc[ai][bj][m][n], 0, 0, 0); __builtin_amdgcn_s_setprio(0); } while (0)
; #define PG8_BAR __builtin_amdgcn_s_barrier()
; template <class Epi, class Sched, bool ALIGN_EPI = false, bool SP2 = false>
; __device__ __forceinline__ void gemm_phase(PG8_LAS unsigned char* lds, const Gemm g, const Sched& S, const Epi& E, const int wv  ) {
;     ...
;             PG8_LDB(B0, 0, 0); PG8_LDB(B1, 0, 1); PG8_SCHED; PG8_LDA(At, 0, 0); PG8_STAGE(PG8_SA(1, 1), a1 + hstep, voffA);
;             PG8_WAIT_V(8); PG8_WAIT_L(0); PG8_BAR; PG8_MMA(0, 0, At, B0); PG8_MMA(0, 1, At, B1); PG8_BAR; PG8_SCHED;
;             PG8_LDA(At, 0, 1); PG8_STAGE(PG8_SB(0, 0), b2, voffB); PG8_STAGE(PG8_SB(0, 1), b2 + hstep, voffB); PG8_STAGE(PG8_SA(0, 0), a2, voffA);
;             PG8_WAIT_V(8); PG8_WAIT_L(0); PG8_BAR; PG8_MMA(1, 0, At, B0); PG8_MMA(1, 1, At, B1); PG8_BAR; PG8_SCHED;
;             PG8_LDB(B0, 1, 0); PG8_LDB(B1, 1, 1); PG8_SCHED; PG8_LDA(At, 1, 0); PG8_STAGE(PG8_SA(0, 1), a2 + hstep, voffA);
;             PG8_WAIT_V(8); PG8_WAIT_L(0); PG8_BAR; PG8_MMA(0, 0, At, B0); PG8_MMA(0, 1, At, B1); PG8_BAR; PG8_SCHED;
;             PG8_LDA(At, 1, 1); PG8_STAGE(PG8_SB(1, 0), b3, voffB); PG8_STAGE(PG8_SB(1, 1), b3 + hstep, voffB); PG8_STAGE(PG8_SA(1, 0), a3, voffA);
;             PG8_WAIT_V(8); PG8_WAIT_L(0); PG8_BAR; PG8_MMA(1, 0, At, B0); PG8_MMA(1, 1, At, B1); PG8_BAR; PG8_SCHED;
	s_setprio 1
	s_waitcnt lgkmcnt(0)
	v_mfma_f32_16x16x32_bf16 v[124:127], v[144:147], v[186:189], 0
	v_mfma_f32_16x16x32_bf16 v[120:123], v[162:165], v[186:189], 0
	v_mfma_f32_16x16x32_bf16 v[108:111], v[144:147], v[194:197], 0
	v_mfma_f32_16x16x32_bf16 v[104:107], v[162:165], v[194:197], 0
	v_mfma_f32_16x16x32_bf16 v[92:95], v[144:147], v[202:205], 0
	v_mfma_f32_16x16x32_bf16 v[88:91], v[162:165], v[202:205], 0
	v_mfma_f32_16x16x32_bf16 v[76:79], v[144:147], v[214:217], 0
	v_mfma_f32_16x16x32_bf16 v[72:75], v[162:165], v[214:217], 0
	v_mfma_f32_16x16x32_bf16 v[124:127], v[158:161], v[190:193], v[124:127]
	v_mfma_f32_16x16x32_bf16 v[120:123], v[166:169], v[190:193], v[120:123]
	v_mfma_f32_16x16x32_bf16 v[108:111], v[158:161], v[198:201], v[108:111]
	v_mfma_f32_16x16x32_bf16 v[104:107], v[166:169], v[198:201], v[104:107]
	v_mfma_f32_16x16x32_bf16 v[92:95], v[158:161], v[206:209], v[92:95]
	v_mfma_f32_16x16x32_bf16 v[88:91], v[166:169], v[206:209], v[88:91]
	v_mfma_f32_16x16x32_bf16 v[76:79], v[158:161], v[218:221], v[76:79]
	v_mfma_f32_16x16x32_bf16 v[72:75], v[166:169], v[218:221], v[72:75]
	s_setprio 0
	s_setprio 1
	v_mfma_f32_16x16x32_bf16 v[116:119], v[170:173], v[186:189], 0
	v_mfma_f32_16x16x32_bf16 v[112:115], v[178:181], v[186:189], 0
	v_mfma_f32_16x16x32_bf16 v[100:103], v[170:173], v[194:197], 0
	v_mfma_f32_16x16x32_bf16 v[96:99], v[178:181], v[194:197], 0
	v_mfma_f32_16x16x32_bf16 v[84:87], v[170:173], v[202:205], 0
	v_mfma_f32_16x16x32_bf16 v[80:83], v[178:181], v[202:205], 0
	v_mfma_f32_16x16x32_bf16 v[68:71], v[170:173], v[214:217], 0
	v_mfma_f32_16x16x32_bf16 v[64:67], v[178:181], v[214:217], 0
	v_mfma_f32_16x16x32_bf16 v[116:119], v[174:177], v[190:193], v[116:119]
	v_mfma_f32_16x16x32_bf16 v[112:115], v[182:185], v[190:193], v[112:115]
	v_mfma_f32_16x16x32_bf16 v[100:103], v[174:177], v[198:201], v[100:103]
	v_mfma_f32_16x16x32_bf16 v[96:99], v[182:185], v[198:201], v[96:99]
	v_mfma_f32_16x16x32_bf16 v[84:87], v[174:177], v[206:209], v[84:87]
	v_mfma_f32_16x16x32_bf16 v[80:83], v[182:185], v[206:209], v[80:83]
	v_mfma_f32_16x16x32_bf16 v[68:71], v[174:177], v[218:221], v[68:71]
	v_mfma_f32_16x16x32_bf16 v[64:67], v[182:185], v[218:221], v[64:67]
	s_setprio 0
	s_barrier
	s_add_i32 s57, s51, s20
	v_lshl_add_u64 v[210:211], s[38:39], 0, v[130:131]
	s_mov_b32 m0, s57
	ds_read_b128 v[186:189], v154 offset:16384
	ds_read_b128 v[190:193], v154 offset:17408
	ds_read_b128 v[194:197], v154 offset:18432
	ds_read_b128 v[198:201], v154 offset:19456
	ds_read_b128 v[202:205], v154 offset:20480
	ds_read_b128 v[206:209], v154 offset:21504
	ds_read_b128 v[214:217], v154 offset:22528
	ds_read_b128 v[218:221], v154 offset:23552
	global_load_lds_dwordx4 v[210:211], off
	s_add_i32 m0, s57, 0x2000
	s_add_u32 s58, s38, 0x40000
	v_lshl_add_u64 v[222:223], s[38:39], 0, v[134:135]
	s_addc_u32 s59, s39, 0
	s_add_i32 s57, s52, s20
	global_load_lds_dwordx4 v[222:223], off
	v_lshl_add_u64 v[224:225], s[58:59], 0, v[130:131]
	s_mov_b32 m0, s57
	v_lshl_add_u64 v[226:227], s[40:41], 0, v[132:133]
	global_load_lds_dwordx4 v[224:225], off
	v_lshl_add_u64 v[224:225], s[58:59], 0, v[134:135]
	s_add_i32 m0, s57, 0x2000
	s_nop 0
	global_load_lds_dwordx4 v[224:225], off
	v_lshl_add_u64 v[224:225], s[40:41], 0, v[128:129]
	s_mov_b32 m0, s44
	s_nop 0
	global_load_lds_dwordx4 v[224:225], off
	s_mov_b32 m0, s45
	s_nop 0
	global_load_lds_dwordx4 v[226:227], off
	s_waitcnt vmcnt(8)
	s_waitcnt lgkmcnt(0)
	s_barrier
	s_setprio 1
	s_waitcnt lgkmcnt(0)
	v_mfma_f32_16x16x32_bf16 v[60:63], v[144:147], v[186:189], 0
	v_mfma_f32_16x16x32_bf16 v[56:59], v[162:165], v[186:189], 0
	v_mfma_f32_16x16x32_bf16 v[44:47], v[144:147], v[194:197], 0
	v_mfma_f32_16x16x32_bf16 v[40:43], v[162:165], v[194:197], 0
	v_mfma_f32_16x16x32_bf16 v[28:31], v[144:147], v[202:205], 0
	v_mfma_f32_16x16x32_bf16 v[24:27], v[162:165], v[202:205], 0
	v_mfma_f32_16x16x32_bf16 v[12:15], v[144:147], v[214:217], 0
	v_mfma_f32_16x16x32_bf16 v[8:11], v[162:165], v[214:217], 0
	v_mfma_f32_16x16x32_bf16 v[60:63], v[158:161], v[190:193], v[60:63]
	v_mfma_f32_16x16x32_bf16 v[56:59], v[166:169], v[190:193], v[56:59]
	v_mfma_f32_16x16x32_bf16 v[44:47], v[158:161], v[198:201], v[44:47]
	v_mfma_f32_16x16x32_bf16 v[40:43], v[166:169], v[198:201], v[40:43]
	v_mfma_f32_16x16x32_bf16 v[28:31], v[158:161], v[206:209], v[28:31]
	v_mfma_f32_16x16x32_bf16 v[24:27], v[166:169], v[206:209], v[24:27]
	v_mfma_f32_16x16x32_bf16 v[12:15], v[158:161], v[218:221], v[12:15]
	v_mfma_f32_16x16x32_bf16 v[8:11], v[166:169], v[218:221], v[8:11]
	s_setprio 0
	s_setprio 1
	v_mfma_f32_16x16x32_bf16 v[52:55], v[170:173], v[186:189], 0
	v_mfma_f32_16x16x32_bf16 v[48:51], v[178:181], v[186:189], 0
	v_mfma_f32_16x16x32_bf16 v[36:39], v[170:173], v[194:197], 0
	v_mfma_f32_16x16x32_bf16 v[32:35], v[178:181], v[194:197], 0
	v_mfma_f32_16x16x32_bf16 v[20:23], v[170:173], v[202:205], 0
	v_mfma_f32_16x16x32_bf16 v[16:19], v[178:181], v[202:205], 0
	v_mfma_f32_16x16x32_bf16 v[4:7], v[170:173], v[214:217], 0
	v_mfma_f32_16x16x32_bf16 v[0:3], v[178:181], v[214:217], 0
	v_mfma_f32_16x16x32_bf16 v[52:55], v[174:177], v[190:193], v[52:55]
	v_mfma_f32_16x16x32_bf16 v[48:51], v[182:185], v[190:193], v[48:51]
	v_mfma_f32_16x16x32_bf16 v[36:39], v[174:177], v[198:201], v[36:39]
	v_mfma_f32_16x16x32_bf16 v[32:35], v[182:185], v[198:201], v[32:35]
	v_mfma_f32_16x16x32_bf16 v[20:23], v[174:177], v[206:209], v[20:23]
	v_mfma_f32_16x16x32_bf16 v[16:19], v[182:185], v[206:209], v[16:19]
	v_mfma_f32_16x16x32_bf16 v[4:7], v[174:177], v[218:221], v[4:7]
	v_mfma_f32_16x16x32_bf16 v[0:3], v[182:185], v[218:221], v[0:3]
	s_setprio 0
	s_barrier
; #define PG8_STAGE(bufoff, gbase, voff) do { _Pragma("unroll") for (int _i = 0; _i < 2; ++_i) \
;         __builtin_amdgcn_global_load_lds((const unsigned*)((const char*)(gbase) + (voff)[_i]), (PG8_LAS unsigned*)(lds + (bufoff) + ldsw + _i * 8192), 16, 0, 0); } while (0)
; #define PG8_LDA(dst, b, h) do { _Pragma("unroll") for (int m = 0; m < 4; ++m) _Pragma("unroll") for (int k = 0; k < 2; ++k) dst[m][k] = *(const PG8_LAS bf16x8*)(lds + PG8_SA(b, h) + aoff + m * 2048 + k * 1024); } while (0)
; #define PG8_LDB(dst, b, h) do { _Pragma("unroll") for (int n = 0; n < 2; ++n) _Pragma("unroll") for (int k = 0; k < 2; ++k) dst[n][k] = *(const PG8_LAS bf16x8*)(lds + PG8_SB(b, h) + boff + n * 2048 + k * 1024); } while (0)
; #define PG8_MMA(ai, bj, At, Bt) do { __builtin_amdgcn_s_setprio(1); _Pragma("unroll") for (int m = 0; m < 4; ++m) _Pragma("unroll") for (int n = 0; n < 2; ++n) _Pragma("unroll") for (int k = 0; k < 2; ++k) \
;         acc[ai][bj][m][n] = __builtin_amdgcn_mfma_f32_16x16x32_bf16(Bt[n][k], At[m][k], acc[ai][bj][m][n], 0, 0, 0); __builtin_amdgcn_s_setprio(0); } while (0)
; #define PG8_BAR __builtin_amdgcn_s_barrier()
; template <class Epi, class Sched, bool ALIGN_EPI = false, bool SP2 = false>
; __device__ __forceinline__ void gemm_phase(PG8_LAS unsigned char* lds, const Gemm g, const Sched& S, const Epi& E, const int wv  ) {
;     ...
;             PG8_LDB(B0, 0, 0); PG8_LDB(B1, 0, 1); PG8_SCHED; PG8_LDA(At, 0, 0); PG8_STAGE(PG8_SA(1, 1), a1 + hstep, voffA);
;             PG8_WAIT_V(8); PG8_WAIT_L(0); PG8_BAR; PG8_MMA(0, 0, At, B0); PG8_MMA(0, 1, At, B1); PG8_BAR; PG8_SCHED;
;             PG8_LDA(At, 0, 1); PG8_STAGE(PG8_SB(0, 0), b2, voffB); PG8_STAGE(PG8_SB(0, 1), b2 + hstep, voffB); PG8_STAGE(PG8_SA(0, 0), a2, voffA);
;             PG8_WAIT_V(8); PG8_WAIT_L(0); PG8_BAR; PG8_MMA(1, 0, At, B0); PG8_MMA(1, 1, At, B1); PG8_BAR; PG8_SCHED;
;             PG8_LDB(B0, 1, 0); PG8_LDB(B1, 1, 1); PG8_SCHED; PG8_LDA(At, 1, 0); PG8_STAGE(PG8_SA(0, 1), a2 + hstep, voffA);
;             PG8_WAIT_V(8); PG8_WAIT_L(0); PG8_BAR; PG8_MMA(0, 0, At, B0); PG8_MMA(0, 1, At, B1); PG8_BAR; PG8_SCHED;
;             PG8_LDA(At, 1, 1); PG8_STAGE(PG8_SB(1, 0), b3, voffB); PG8_STAGE(PG8_SB(1, 1), b3 + hstep, voffB); PG8_STAGE(PG8_SA(1, 0), a3, voffA);
;             PG8_WAIT_V(8); PG8_WAIT_L(0); PG8_BAR; PG8_MMA(1, 0, At, B0); PG8_MMA(1, 1, At, B1); PG8_BAR; PG8_SCHED;
	s_add_i32 s57, 0, 0x18000
	v_add_u32_e32 v157, s57, v149
	s_add_i32 s58, 0, 0x1c000
	ds_read_b128 v[144:147], v157
	ds_read_b128 v[158:161], v157 offset:1024
	ds_read_b128 v[162:165], v157 offset:2048
	ds_read_b128 v[166:169], v157 offset:3072
	v_add_u32_e32 v157, s58, v149
	ds_read_b128 v[170:173], v157
	ds_read_b128 v[174:177], v157 offset:1024
	ds_read_b128 v[178:181], v157 offset:2048
	ds_read_b128 v[182:185], v157 offset:3072
	s_add_u32 s40, s40, 0x40000
	s_addc_u32 s41, s41, 0
	s_mov_b32 m0, s46
	v_lshl_add_u64 v[228:229], s[40:41], 0, v[128:129]
	ds_read_b128 v[186:189], v154 offset:32768
	ds_read_b128 v[190:193], v154 offset:33792
	ds_read_b128 v[194:197], v154 offset:34816
	ds_read_b128 v[198:201], v154 offset:35840
	ds_read_b128 v[202:205], v154 offset:36864
	ds_read_b128 v[206:209], v154 offset:37888
	ds_read_b128 v[214:217], v154 offset:38912
	ds_read_b128 v[218:221], v154 offset:39936
	global_load_lds_dwordx4 v[228:229], off
	v_lshl_add_u64 v[228:229], s[40:41], 0, v[132:133]
	s_mov_b32 m0, s47
	s_nop 0
	global_load_lds_dwordx4 v[228:229], off
	s_waitcnt vmcnt(8)
	s_waitcnt lgkmcnt(0)
	s_barrier
	s_setprio 1
	s_waitcnt lgkmcnt(0)
	v_mfma_f32_16x16x32_bf16 v[124:127], v[144:147], v[186:189], v[124:127]
	v_mfma_f32_16x16x32_bf16 v[120:123], v[162:165], v[186:189], v[120:123]
	v_mfma_f32_16x16x32_bf16 v[108:111], v[144:147], v[194:197], v[108:111]
	v_mfma_f32_16x16x32_bf16 v[104:107], v[162:165], v[194:197], v[104:107]
	v_mfma_f32_16x16x32_bf16 v[92:95], v[144:147], v[202:205], v[92:95]
	v_mfma_f32_16x16x32_bf16 v[88:91], v[162:165], v[202:205], v[88:91]
	v_mfma_f32_16x16x32_bf16 v[76:79], v[144:147], v[214:217], v[76:79]
	v_mfma_f32_16x16x32_bf16 v[72:75], v[162:165], v[214:217], v[72:75]
	v_mfma_f32_16x16x32_bf16 v[124:127], v[158:161], v[190:193], v[124:127]
	v_mfma_f32_16x16x32_bf16 v[120:123], v[166:169], v[190:193], v[120:123]
	v_mfma_f32_16x16x32_bf16 v[108:111], v[158:161], v[198:201], v[108:111]
	v_mfma_f32_16x16x32_bf16 v[104:107], v[166:169], v[198:201], v[104:107]
	v_mfma_f32_16x16x32_bf16 v[92:95], v[158:161], v[206:209], v[92:95]
	v_mfma_f32_16x16x32_bf16 v[88:91], v[166:169], v[206:209], v[88:91]
	v_mfma_f32_16x16x32_bf16 v[76:79], v[158:161], v[218:221], v[76:79]
	v_mfma_f32_16x16x32_bf16 v[72:75], v[166:169], v[218:221], v[72:75]
	s_setprio 0
	s_setprio 1
	v_mfma_f32_16x16x32_bf16 v[116:119], v[170:173], v[186:189], v[116:119]
	v_mfma_f32_16x16x32_bf16 v[112:115], v[178:181], v[186:189], v[112:115]
	v_mfma_f32_16x16x32_bf16 v[100:103], v[170:173], v[194:197], v[100:103]
	v_mfma_f32_16x16x32_bf16 v[96:99], v[178:181], v[194:197], v[96:99]
	v_mfma_f32_16x16x32_bf16 v[84:87], v[170:173], v[202:205], v[84:87]
	v_mfma_f32_16x16x32_bf16 v[80:83], v[178:181], v[202:205], v[80:83]
	v_mfma_f32_16x16x32_bf16 v[68:71], v[170:173], v[214:217], v[68:71]
	v_mfma_f32_16x16x32_bf16 v[64:67], v[178:181], v[214:217], v[64:67]
	v_mfma_f32_16x16x32_bf16 v[116:119], v[174:177], v[190:193], v[116:119]
	v_mfma_f32_16x16x32_bf16 v[112:115], v[182:185], v[190:193], v[112:115]
	v_mfma_f32_16x16x32_bf16 v[100:103], v[174:177], v[198:201], v[100:103]
	v_mfma_f32_16x16x32_bf16 v[96:99], v[182:185], v[198:201], v[96:99]
	v_mfma_f32_16x16x32_bf16 v[84:87], v[174:177], v[206:209], v[84:87]
	v_mfma_f32_16x16x32_bf16 v[80:83], v[182:185], v[206:209], v[80:83]
	v_mfma_f32_16x16x32_bf16 v[68:71], v[174:177], v[218:221], v[68:71]
	v_mfma_f32_16x16x32_bf16 v[64:67], v[182:185], v[218:221], v[64:67]
	s_setprio 0
	s_barrier
; #define PG8_STAGE(bufoff, gbase, voff) do { _Pragma("unroll") for (int _i = 0; _i < 2; ++_i) \
;         __builtin_amdgcn_global_load_lds((const unsigned*)((const char*)(gbase) + (voff)[_i]), (PG8_LAS unsigned*)(lds + (bufoff) + ldsw + _i * 8192), 16, 0, 0); } while (0)
; #define PG8_LDA(dst, b, h) do { _Pragma("unroll") for (int m = 0; m < 4; ++m) _Pragma("unroll") for (int k = 0; k < 2; ++k) dst[m][k] = *(const PG8_LAS bf16x8*)(lds + PG8_SA(b, h) + aoff + m * 2048 + k * 1024); } while (0)
; #define PG8_LDB(dst, b, h) do { _Pragma("unroll") for (int n = 0; n < 2; ++n) _Pragma("unroll") for (int k = 0; k < 2; ++k) dst[n][k] = *(const PG8_LAS bf16x8*)(lds + PG8_SB(b, h) + boff + n * 2048 + k * 1024); } while (0)
; #define PG8_MMA(ai, bj, At, Bt) do { __builtin_amdgcn_s_setprio(1); _Pragma("unroll") for (int m = 0; m < 4; ++m) _Pragma("unroll") for (int n = 0; n < 2; ++n) _Pragma("unroll") for (int k = 0; k < 2; ++k) \
;         acc[ai][bj][m][n] = __builtin_amdgcn_mfma_f32_16x16x32_bf16(Bt[n][k], At[m][k], acc[ai][bj][m][n], 0, 0, 0); __builtin_amdgcn_s_setprio(0); } while (0)
; #define PG8_BAR __builtin_amdgcn_s_barrier()
; template <class Epi, class Sched, bool ALIGN_EPI = false, bool SP2 = false>
; __device__ __forceinline__ void gemm_phase(PG8_LAS unsigned char* lds, const Gemm g, const Sched& S, const Epi& E, const int wv  ) {
;     ...
;             PG8_LDB(B0, 0, 0); PG8_LDB(B1, 0, 1); PG8_SCHED; PG8_LDA(At, 0, 0); PG8_STAGE(PG8_SA(1, 1), a1 + hstep, voffA);
;             PG8_WAIT_V(8); PG8_WAIT_L(0); PG8_BAR; PG8_MMA(0, 0, At, B0); PG8_MMA(0, 1, At, B1); PG8_BAR; PG8_SCHED;
;             PG8_LDA(At, 0, 1); PG8_STAGE(PG8_SB(0, 0), b2, voffB); PG8_STAGE(PG8_SB(0, 1), b2 + hstep, voffB); PG8_STAGE(PG8_SA(0, 0), a2, voffA);
;             PG8_WAIT_V(8); PG8_WAIT_L(0); PG8_BAR; PG8_MMA(1, 0, At, B0); PG8_MMA(1, 1, At, B1); PG8_BAR; PG8_SCHED;
;             PG8_LDB(B0, 1, 0); PG8_LDB(B1, 1, 1); PG8_SCHED; PG8_LDA(At, 1, 0); PG8_STAGE(PG8_SA(0, 1), a2 + hstep, voffA);
;             PG8_WAIT_V(8); PG8_WAIT_L(0); PG8_BAR; PG8_MMA(0, 0, At, B0); PG8_MMA(0, 1, At, B1); PG8_BAR; PG8_SCHED;
;             PG8_LDA(At, 1, 1); PG8_STAGE(PG8_SB(1, 0), b3, voffB); PG8_STAGE(PG8_SB(1, 1), b3 + hstep, voffB); PG8_STAGE(PG8_SA(1, 0), a3, voffA);
;             PG8_WAIT_V(8); PG8_WAIT_L(0); PG8_BAR; PG8_MMA(1, 0, At, B0); PG8_MMA(1, 1, At, B1); PG8_BAR; PG8_SCHED;
	s_add_i32 s40, s57, s20
	v_lshl_add_u64 v[210:211], v[210:211], 0, s[16:17]
	s_mov_b32 m0, s40
	ds_read_b128 v[186:189], v154 offset:49152
	ds_read_b128 v[190:193], v154 offset:50176
	ds_read_b128 v[194:197], v154 offset:51200
	ds_read_b128 v[198:201], v154 offset:52224
	ds_read_b128 v[202:205], v154 offset:53248
	ds_read_b128 v[206:209], v154 offset:54272
	ds_read_b128 v[214:217], v154 offset:55296
	ds_read_b128 v[218:221], v154 offset:56320
	global_load_lds_dwordx4 v[210:211], off
	s_add_i32 m0, s40, 0x2000
	s_add_u32 s38, s38, 0x40080
	v_lshl_add_u64 v[210:211], v[222:223], 0, s[16:17]
	s_addc_u32 s39, s39, 0
	s_add_i32 s40, s58, s20
	global_load_lds_dwordx4 v[210:211], off
	v_lshl_add_u64 v[210:211], s[38:39], 0, v[130:131]
	s_mov_b32 m0, s40
	s_nop 0
	global_load_lds_dwordx4 v[210:211], off
	v_lshl_add_u64 v[210:211], s[38:39], 0, v[134:135]
	s_add_i32 m0, s40, 0x2000
	s_nop 0
	global_load_lds_dwordx4 v[210:211], off
	v_lshl_add_u64 v[210:211], v[224:225], 0, s[16:17]
	s_mov_b32 m0, s49
	s_nop 0
	global_load_lds_dwordx4 v[210:211], off
	v_lshl_add_u64 v[210:211], v[226:227], 0, s[16:17]
	s_mov_b32 m0, s50
	s_nop 0
	global_load_lds_dwordx4 v[210:211], off
	s_waitcnt vmcnt(8)
	s_waitcnt lgkmcnt(0)
	s_barrier
	s_setprio 1
	s_waitcnt lgkmcnt(0)
	v_mfma_f32_16x16x32_bf16 v[60:63], v[144:147], v[186:189], v[60:63]
	v_mfma_f32_16x16x32_bf16 v[56:59], v[162:165], v[186:189], v[56:59]
	v_mfma_f32_16x16x32_bf16 v[44:47], v[144:147], v[194:197], v[44:47]
	v_mfma_f32_16x16x32_bf16 v[40:43], v[162:165], v[194:197], v[40:43]
	v_mfma_f32_16x16x32_bf16 v[28:31], v[144:147], v[202:205], v[28:31]
	v_mfma_f32_16x16x32_bf16 v[24:27], v[162:165], v[202:205], v[24:27]
	v_mfma_f32_16x16x32_bf16 v[12:15], v[144:147], v[214:217], v[12:15]
	v_mfma_f32_16x16x32_bf16 v[8:11], v[162:165], v[214:217], v[8:11]
	v_mfma_f32_16x16x32_bf16 v[60:63], v[158:161], v[190:193], v[60:63]
	v_mfma_f32_16x16x32_bf16 v[56:59], v[166:169], v[190:193], v[56:59]
	v_mfma_f32_16x16x32_bf16 v[44:47], v[158:161], v[198:201], v[44:47]
	v_mfma_f32_16x16x32_bf16 v[40:43], v[166:169], v[198:201], v[40:43]
	v_mfma_f32_16x16x32_bf16 v[28:31], v[158:161], v[206:209], v[28:31]
	v_mfma_f32_16x16x32_bf16 v[24:27], v[166:169], v[206:209], v[24:27]
	v_mfma_f32_16x16x32_bf16 v[12:15], v[158:161], v[218:221], v[12:15]
	v_mfma_f32_16x16x32_bf16 v[8:11], v[166:169], v[218:221], v[8:11]
	s_setprio 0
	s_setprio 1
	v_mfma_f32_16x16x32_bf16 v[52:55], v[170:173], v[186:189], v[52:55]
	v_mfma_f32_16x16x32_bf16 v[48:51], v[178:181], v[186:189], v[48:51]
	v_mfma_f32_16x16x32_bf16 v[36:39], v[170:173], v[194:197], v[36:39]
	v_mfma_f32_16x16x32_bf16 v[32:35], v[178:181], v[194:197], v[32:35]
	v_mfma_f32_16x16x32_bf16 v[20:23], v[170:173], v[202:205], v[20:23]
	v_mfma_f32_16x16x32_bf16 v[16:19], v[178:181], v[202:205], v[16:19]
	v_mfma_f32_16x16x32_bf16 v[4:7], v[170:173], v[214:217], v[4:7]
	v_mfma_f32_16x16x32_bf16 v[0:3], v[178:181], v[214:217], v[0:3]
	v_mfma_f32_16x16x32_bf16 v[52:55], v[174:177], v[190:193], v[52:55]
	v_mfma_f32_16x16x32_bf16 v[48:51], v[182:185], v[190:193], v[48:51]
	v_mfma_f32_16x16x32_bf16 v[36:39], v[174:177], v[198:201], v[36:39]
	v_mfma_f32_16x16x32_bf16 v[32:35], v[182:185], v[198:201], v[32:35]
	v_mfma_f32_16x16x32_bf16 v[20:23], v[174:177], v[206:209], v[20:23]
	v_mfma_f32_16x16x32_bf16 v[16:19], v[182:185], v[206:209], v[16:19]
	v_mfma_f32_16x16x32_bf16 v[4:7], v[174:177], v[218:221], v[4:7]
	v_mfma_f32_16x16x32_bf16 v[0:3], v[182:185], v[218:221], v[0:3]
	s_setprio 0
	s_barrier
	s_add_i32 s56, s56, 2
	s_add_u32 s0, s0, 0x100
	s_addc_u32 s1, s1, 0
	s_add_u32 s27, s27, 0x100
	s_addc_u32 s29, s29, 0
	s_cmp_gt_u32 s56, 13

; #define PG8_STAGE(bufoff, gbase, voff) do { _Pragma("unroll") for (int _i = 0; _i < 2; ++_i) \
;         __builtin_amdgcn_global_load_lds((const unsigned*)((const char*)(gbase) + (voff)[_i]), (PG8_LAS unsigned*)(lds + (bufoff) + ldsw + _i * 8192), 16, 0, 0); } while (0)
; #define PG8_LDA(dst, b, h) do { _Pragma("unroll") for (int m = 0; m < 4; ++m) _Pragma("unroll") for (int k = 0; k < 2; ++k) dst[m][k] = *(const PG8_LAS bf16x8*)(lds + PG8_SA(b, h) + aoff + m * 2048 + k * 1024); } while (0)
; #define PG8_LDB(dst, b, h) do { _Pragma("unroll") for (int n = 0; n < 2; ++n) _Pragma("unroll") for (int k = 0; k < 2; ++k) dst[n][k] = *(const PG8_LAS bf16x8*)(lds + PG8_SB(b, h) + boff + n * 2048 + k * 1024); } while (0)
; #define PG8_SCHED __builtin_amdgcn_sched_barrier(0)
;     __device__ __forceinline__ void operator()(const f32x4 (&acc)[2][2][4][2], const Unit& u, int wr, int wc, int fr, int fq) const {
;         const int row0 = u.pm * BM + wr * 64 + fr, col0 = u.pn * BM + wc * 32 + 8 * fq;
;         int slot = -1;
;         if (tab) { const int n = pml[8]; for (int j = 0; j < n; ++j) if (pml[j] == u.pm) slot = j; }
; template <class Epi, class Sched, bool ALIGN_EPI = false, bool SP2 = false>
; __device__ __forceinline__ void gemm_phase(PG8_LAS unsigned char* lds, const Gemm g, const Sched& S, const Epi& E, const int wv  ) {
;     ...
;             PG8_LDB(B0, 0, 0); PG8_LDB(B1, 0, 1); PG8_SCHED; PG8_LDA(At, 0, 0); PG8_STAGE(PG8_SA(1, 1), a1 + hstep, voffA);
.LBB0_1039:
	s_add_u32 s60, s9, 0x40080
	s_addc_u32 s61, s7, 0
	v_lshl_add_u64 v[210:211], s[60:61], 0, v[136:137]
	s_add_i32 m0, s44, 0xc000
	s_nop 0
	global_load_lds_dwordx4 v[210:211], off
	v_lshl_add_u64 v[210:211], s[60:61], 0, v[138:139]
	s_add_i32 m0, s44, 0xe000
	s_nop 0
	global_load_lds_dwordx4 v[210:211], off
	v_mov_b32_e32 v144, s53
	ds_read_b32 v144, v144
	s_waitcnt lgkmcnt(0)
	v_cmp_gt_i32_e32 vcc, 1, v144
	v_readfirstlane_b32 s7, v144
	s_cbranch_vccnz .LBB0_1045
	s_cmp_eq_u32 s7, 1
	s_cbranch_scc1 .LBB0_1046
	s_add_i32 s0, s7, -2
	s_lshr_b32 s9, s0, 1
	s_add_i32 s9, s9, 1
	s_cmp_lt_u32 s0, 14
	s_cbranch_scc1 .LBB0_1047
	s_mov_b32 s18, 0
	s_and_b32 s25, s9, -8
	s_mov_b32 s39, 1
	v_bfrev_b32_e32 v144, 1
	s_mov_b32 s27, s54
	v_bfrev_b32_e32 v145, 1
	s_mov_b32 s38, s18

; #define PG8_STAGE(bufoff, gbase, voff) do { _Pragma("unroll") for (int _i = 0; _i < 2; ++_i) \
;         __builtin_amdgcn_global_load_lds((const unsigned*)((const char*)(gbase) + (voff)[_i]), (PG8_LAS unsigned*)(lds + (bufoff) + ldsw + _i * 8192), 16, 0, 0); } while (0)
; #define PG8_LDA(dst, b, h) do { _Pragma("unroll") for (int m = 0; m < 4; ++m) _Pragma("unroll") for (int k = 0; k < 2; ++k) dst[m][k] = *(const PG8_LAS bf16x8*)(lds + PG8_SA(b, h) + aoff + m * 2048 + k * 1024); } while (0)
; #define PG8_LDB(dst, b, h) do { _Pragma("unroll") for (int n = 0; n < 2; ++n) _Pragma("unroll") for (int k = 0; k < 2; ++k) dst[n][k] = *(const PG8_LAS bf16x8*)(lds + PG8_SB(b, h) + boff + n * 2048 + k * 1024); } while (0)
; #define PG8_WAIT_V(n) asm volatile("s_waitcnt vmcnt(" #n ")" ::: "memory")
; #define PG8_WAIT_L(n) asm volatile("s_waitcnt lgkmcnt(" #n ")" ::: "memory")
; #define PG8_BAR __builtin_amdgcn_s_barrier()
; #define PG8_SCHED __builtin_amdgcn_sched_barrier(0)
; template <class Epi, class Sched, bool ALIGN_EPI = false, bool SP2 = false>
; __device__ __forceinline__ void gemm_phase(PG8_LAS unsigned char* lds, const Gemm g, const Sched& S, const Epi& E, const int wv  ) {
;     ...
;         const bool has_next = S.next(ui + 1, nxt);
;         const char* nA = has_next ? (const char*)g.A + (size_t)nxt.pm * tstep : cA; const char* nB = has_next ? (const char*)g.Bt + (size_t)nxt.pn * tstep : cB;
;         for (int t = 0; t < nt; t += 2) {
;             const bool last = (t == nt - 2);
;             const char* a1 = cA + (size_t)(t + 1) * kstep;
;             const char* a2 = last ? nA : cA + (size_t)(t + 2) * kstep; const char* b2 = last ? nB : cB + (size_t)(t + 2) * kstep;
;             const char* a3 = a2 + kstep; const char* b3 = b2 + kstep;
;             if (last && has_next) S.a_ready(nxt);
;             if constexpr (SP2) {
;             PG8_LDB(B0, 0, 0); PG8_LDB(B1, 0, 1); PG8_SCHED; PG8_LDA(At, 0, 0); PG8_STAGE(PG8_SA(1, 1), a1 + hstep, voffA);
;             PG8_WAIT_V(8); PG8_WAIT_L(0); PG8_BAR; PG8_MMA(0, 0, At, B0); PG8_MMA(0, 1, At, B1); PG8_BAR; PG8_SCHED;
;             PG8_LDA(At, 0, 1); PG8_STAGE(PG8_SB(0, 0), b2, voffB); PG8_STAGE(PG8_SB(0, 1), b2 + hstep, voffB); PG8_STAGE(PG8_SA(0, 0), a2, voffA);
;             PG8_WAIT_V(8); PG8_WAIT_L(0); PG8_BAR; PG8_MMA(1, 0, At, B0); PG8_MMA(1, 1, At, B1); PG8_BAR; PG8_SCHED;
.LBB0_1214:
	s_ashr_i32 s27, s26, 31
	s_lshl_b64 s[28:29], s[26:27], 19
	s_add_u32 s28, s2, s28
	s_addc_u32 s29, s3, s29
	s_and_b64 s[30:31], s[6:7], exec
	s_cselect_b32 s27, s29, s37
	s_cselect_b32 s35, s28, s36
	s_ashr_i32 s25, s24, 31
	s_lshl_b64 s[30:31], s[24:25], 19
	s_add_u32 s30, s20, s30
	s_addc_u32 s31, s21, s31
	s_and_b64 s[40:41], s[6:7], exec
	s_cselect_b32 s25, s31, s39
	s_cselect_b32 s54, s30, s38
	s_add_u32 s36, s36, 0x40080
	s_addc_u32 s37, s37, 0
	s_add_u32 s55, s38, 0x100
	s_addc_u32 s56, s39, 0
	s_mov_b32 s57, -2
	s_waitcnt lgkmcnt(0)
	s_cmp_eq_u32 s53, 1
	s_cbranch_scc1 .LpeelA_1215
	ds_read_b128 v[128:131], v191
	ds_read_b128 v[132:135], v191 offset:1024
	ds_read_b128 v[136:139], v191 offset:2048
	ds_read_b128 v[140:143], v191 offset:3072
	ds_read_b128 v[144:147], v192
	ds_read_b128 v[148:151], v192 offset:1024
	ds_read_b128 v[168:171], v192 offset:2048
	ds_read_b128 v[172:175], v192 offset:3072
	s_add_u32 s38, s36, 0xfffc0080
	s_addc_u32 s39, s37, -1
	s_cmp_eq_u32 s57, 12
	s_cselect_b32 s41, s27, s39
	s_cselect_b32 s40, s35, s38
	s_cselect_b32 s39, s25, s56
	s_cselect_b32 s38, s54, s55
	ds_read_b128 v[176:179], v193
	ds_read_b128 v[180:183], v193 offset:1024
	ds_read_b128 v[194:197], v193 offset:2048
	ds_read_b128 v[198:201], v193 offset:3072
	ds_read_b128 v[202:205], v193 offset:4096
	ds_read_b128 v[206:209], v193 offset:5120
	ds_read_b128 v[214:217], v193 offset:6144
	ds_read_b128 v[218:221], v193 offset:7168
	s_waitcnt vmcnt(24)
	s_waitcnt lgkmcnt(0)
	s_barrier
	s_setprio 1
	s_waitcnt lgkmcnt(0)
	v_mfma_f32_16x16x32_bf16 v[124:127], v[128:131], v[176:179], 0
	v_mfma_f32_16x16x32_bf16 v[120:123], v[136:139], v[176:179], 0
	v_mfma_f32_16x16x32_bf16 v[108:111], v[128:131], v[194:197], 0
	v_mfma_f32_16x16x32_bf16 v[104:107], v[136:139], v[194:197], 0
	v_mfma_f32_16x16x32_bf16 v[92:95], v[128:131], v[202:205], 0
	v_mfma_f32_16x16x32_bf16 v[88:91], v[136:139], v[202:205], 0
	v_mfma_f32_16x16x32_bf16 v[76:79], v[128:131], v[214:217], 0
	v_mfma_f32_16x16x32_bf16 v[72:75], v[136:139], v[214:217], 0
	v_mfma_f32_16x16x32_bf16 v[124:127], v[132:135], v[180:183], v[124:127]
	v_mfma_f32_16x16x32_bf16 v[120:123], v[140:143], v[180:183], v[120:123]
	v_mfma_f32_16x16x32_bf16 v[108:111], v[132:135], v[198:201], v[108:111]
	v_mfma_f32_16x16x32_bf16 v[104:107], v[140:143], v[198:201], v[104:107]
	v_mfma_f32_16x16x32_bf16 v[92:95], v[132:135], v[206:209], v[92:95]
	v_mfma_f32_16x16x32_bf16 v[88:91], v[140:143], v[206:209], v[88:91]
	v_mfma_f32_16x16x32_bf16 v[76:79], v[132:135], v[218:221], v[76:79]
	v_mfma_f32_16x16x32_bf16 v[72:75], v[140:143], v[218:221], v[72:75]
	s_setprio 0
	s_setprio 1
	v_mfma_f32_16x16x32_bf16 v[116:119], v[144:147], v[176:179], 0
	v_mfma_f32_16x16x32_bf16 v[112:115], v[168:171], v[176:179], 0
	v_mfma_f32_16x16x32_bf16 v[100:103], v[144:147], v[194:197], 0
	v_mfma_f32_16x16x32_bf16 v[96:99], v[168:171], v[194:197], 0
	v_mfma_f32_16x16x32_bf16 v[84:87], v[144:147], v[202:205], 0
	v_mfma_f32_16x16x32_bf16 v[80:83], v[168:171], v[202:205], 0
	v_mfma_f32_16x16x32_bf16 v[68:71], v[144:147], v[214:217], 0
	v_mfma_f32_16x16x32_bf16 v[64:67], v[168:171], v[214:217], 0
	v_mfma_f32_16x16x32_bf16 v[116:119], v[148:151], v[180:183], v[116:119]
	v_mfma_f32_16x16x32_bf16 v[112:115], v[172:175], v[180:183], v[112:115]
	v_mfma_f32_16x16x32_bf16 v[100:103], v[148:151], v[198:201], v[100:103]
	v_mfma_f32_16x16x32_bf16 v[96:99], v[172:175], v[198:201], v[96:99]
	v_mfma_f32_16x16x32_bf16 v[84:87], v[148:151], v[206:209], v[84:87]
	v_mfma_f32_16x16x32_bf16 v[80:83], v[172:175], v[206:209], v[80:83]
	v_mfma_f32_16x16x32_bf16 v[68:71], v[148:151], v[218:221], v[68:71]
	v_mfma_f32_16x16x32_bf16 v[64:67], v[172:175], v[218:221], v[64:67]
	s_setprio 0
	s_barrier
	s_add_i32 s58, s51, s33
	v_lshl_add_u64 v[184:185], s[38:39], 0, v[154:155]
	s_mov_b32 m0, s58
	ds_read_b128 v[176:179], v193 offset:16384
	ds_read_b128 v[180:183], v193 offset:17408
	ds_read_b128 v[194:197], v193 offset:18432
	ds_read_b128 v[198:201], v193 offset:19456
	ds_read_b128 v[202:205], v193 offset:20480
	ds_read_b128 v[206:209], v193 offset:21504
	ds_read_b128 v[214:217], v193 offset:22528
	ds_read_b128 v[218:221], v193 offset:23552
	global_load_lds_dwordx4 v[184:185], off
	s_add_i32 m0, s58, 0x2000
	s_add_u32 s58, s38, 0x40000
	v_lshl_add_u64 v[210:211], s[38:39], 0, v[158:159]
	s_addc_u32 s59, s39, 0
	s_add_i32 s60, s52, s33
	global_load_lds_dwordx4 v[210:211], off
	v_lshl_add_u64 v[222:223], s[58:59], 0, v[154:155]
	s_mov_b32 m0, s60
	v_lshl_add_u64 v[224:225], s[40:41], 0, v[156:157]
	global_load_lds_dwordx4 v[222:223], off
	v_lshl_add_u64 v[222:223], s[58:59], 0, v[158:159]
	s_add_i32 m0, s60, 0x2000
	s_nop 0
	global_load_lds_dwordx4 v[222:223], off
	v_lshl_add_u64 v[222:223], s[40:41], 0, v[152:153]
	s_mov_b32 m0, s42
	s_nop 0
	global_load_lds_dwordx4 v[222:223], off
	s_mov_b32 m0, s43
	s_nop 0
	global_load_lds_dwordx4 v[224:225], off
	s_waitcnt vmcnt(24)
	s_waitcnt lgkmcnt(0)
	s_barrier
; #define PG8_STAGE(bufoff, gbase, voff) do { _Pragma("unroll") for (int _i = 0; _i < 2; ++_i) \
;         __builtin_amdgcn_global_load_lds((const unsigned*)((const char*)(gbase) + (voff)[_i]), (PG8_LAS unsigned*)(lds + (bufoff) + ldsw + _i * 8192), 16, 0, 0); } while (0)
; #define PG8_LDA(dst, b, h) do { _Pragma("unroll") for (int m = 0; m < 4; ++m) _Pragma("unroll") for (int k = 0; k < 2; ++k) dst[m][k] = *(const PG8_LAS bf16x8*)(lds + PG8_SA(b, h) + aoff + m * 2048 + k * 1024); } while (0)
; #define PG8_LDB(dst, b, h) do { _Pragma("unroll") for (int n = 0; n < 2; ++n) _Pragma("unroll") for (int k = 0; k < 2; ++k) dst[n][k] = *(const PG8_LAS bf16x8*)(lds + PG8_SB(b, h) + boff + n * 2048 + k * 1024); } while (0)
; #define PG8_MMA(ai, bj, At, Bt) do { __builtin_amdgcn_s_setprio(1); _Pragma("unroll") for (int m = 0; m < 4; ++m) _Pragma("unroll") for (int n = 0; n < 2; ++n) _Pragma("unroll") for (int k = 0; k < 2; ++k) \
;         acc[ai][bj][m][n] = __builtin_amdgcn_mfma_f32_16x16x32_bf16(Bt[n][k], At[m][k], acc[ai][bj][m][n], 0, 0, 0); __builtin_amdgcn_s_setprio(0); } while (0)
; #define PG8_BAR __builtin_amdgcn_s_barrier()
; template <class Epi, class Sched, bool ALIGN_EPI = false, bool SP2 = false>
; __device__ __forceinline__ void gemm_phase(PG8_LAS unsigned char* lds, const Gemm g, const Sched& S, const Epi& E, const int wv  ) {
;     ...
;             PG8_LDB(B0, 0, 0); PG8_LDB(B1, 0, 1); PG8_SCHED; PG8_LDA(At, 0, 0); PG8_STAGE(PG8_SA(1, 1), a1 + hstep, voffA);
;             PG8_WAIT_V(8); PG8_WAIT_L(0); PG8_BAR; PG8_MMA(0, 0, At, B0); PG8_MMA(0, 1, At, B1); PG8_BAR; PG8_SCHED;
;             PG8_LDA(At, 0, 1); PG8_STAGE(PG8_SB(0, 0), b2, voffB); PG8_STAGE(PG8_SB(0, 1), b2 + hstep, voffB); PG8_STAGE(PG8_SA(0, 0), a2, voffA);
;             PG8_WAIT_V(8); PG8_WAIT_L(0); PG8_BAR; PG8_MMA(1, 0, At, B0); PG8_MMA(1, 1, At, B1); PG8_BAR; PG8_SCHED;
;             PG8_LDB(B0, 1, 0); PG8_LDB(B1, 1, 1); PG8_SCHED; PG8_LDA(At, 1, 0); PG8_STAGE(PG8_SA(0, 1), a2 + hstep, voffA);
;             PG8_WAIT_V(8); PG8_WAIT_L(0); PG8_BAR; PG8_MMA(0, 0, At, B0); PG8_MMA(0, 1, At, B1); PG8_BAR; PG8_SCHED;
;             PG8_LDA(At, 1, 1); PG8_STAGE(PG8_SB(1, 0), b3, voffB); PG8_STAGE(PG8_SB(1, 1), b3 + hstep, voffB); PG8_STAGE(PG8_SA(1, 0), a3, voffA);
;             PG8_WAIT_V(8); PG8_WAIT_L(0); PG8_BAR; PG8_MMA(1, 0, At, B0); PG8_MMA(1, 1, At, B1); PG8_BAR; PG8_SCHED;
	s_setprio 1
	s_waitcnt lgkmcnt(0)
	v_mfma_f32_16x16x32_bf16 v[60:63], v[128:131], v[176:179], 0
	v_mfma_f32_16x16x32_bf16 v[56:59], v[136:139], v[176:179], 0
	v_mfma_f32_16x16x32_bf16 v[44:47], v[128:131], v[194:197], 0
	v_mfma_f32_16x16x32_bf16 v[40:43], v[136:139], v[194:197], 0
	v_mfma_f32_16x16x32_bf16 v[28:31], v[128:131], v[202:205], 0
	v_mfma_f32_16x16x32_bf16 v[24:27], v[136:139], v[202:205], 0
	v_mfma_f32_16x16x32_bf16 v[12:15], v[128:131], v[214:217], 0
	v_mfma_f32_16x16x32_bf16 v[8:11], v[136:139], v[214:217], 0
	v_mfma_f32_16x16x32_bf16 v[60:63], v[132:135], v[180:183], v[60:63]
	v_mfma_f32_16x16x32_bf16 v[56:59], v[140:143], v[180:183], v[56:59]
	v_mfma_f32_16x16x32_bf16 v[44:47], v[132:135], v[198:201], v[44:47]
	v_mfma_f32_16x16x32_bf16 v[40:43], v[140:143], v[198:201], v[40:43]
	v_mfma_f32_16x16x32_bf16 v[28:31], v[132:135], v[206:209], v[28:31]
	v_mfma_f32_16x16x32_bf16 v[24:27], v[140:143], v[206:209], v[24:27]
	v_mfma_f32_16x16x32_bf16 v[12:15], v[132:135], v[218:221], v[12:15]
	v_mfma_f32_16x16x32_bf16 v[8:11], v[140:143], v[218:221], v[8:11]
	s_setprio 0
	s_setprio 1
	v_mfma_f32_16x16x32_bf16 v[52:55], v[144:147], v[176:179], 0
	v_mfma_f32_16x16x32_bf16 v[48:51], v[168:171], v[176:179], 0
	v_mfma_f32_16x16x32_bf16 v[36:39], v[144:147], v[194:197], 0
	v_mfma_f32_16x16x32_bf16 v[32:35], v[168:171], v[194:197], 0
	v_mfma_f32_16x16x32_bf16 v[20:23], v[144:147], v[202:205], 0
	v_mfma_f32_16x16x32_bf16 v[16:19], v[168:171], v[202:205], 0
	v_mfma_f32_16x16x32_bf16 v[4:7], v[144:147], v[214:217], 0
	v_mfma_f32_16x16x32_bf16 v[0:3], v[168:171], v[214:217], 0
	v_mfma_f32_16x16x32_bf16 v[52:55], v[148:151], v[180:183], v[52:55]
	v_mfma_f32_16x16x32_bf16 v[48:51], v[172:175], v[180:183], v[48:51]
	v_mfma_f32_16x16x32_bf16 v[36:39], v[148:151], v[198:201], v[36:39]
	v_mfma_f32_16x16x32_bf16 v[32:35], v[172:175], v[198:201], v[32:35]
	v_mfma_f32_16x16x32_bf16 v[20:23], v[148:151], v[206:209], v[20:23]
	v_mfma_f32_16x16x32_bf16 v[16:19], v[172:175], v[206:209], v[16:19]
	v_mfma_f32_16x16x32_bf16 v[4:7], v[148:151], v[218:221], v[4:7]
	v_mfma_f32_16x16x32_bf16 v[0:3], v[172:175], v[218:221], v[0:3]
	s_setprio 0
	s_barrier
	s_add_i32 s58, 0, 0x18000
	s_add_i32 s59, 0, 0x1c000
	v_add_u32_e32 v140, s58, v189
	v_add_u32_e32 v172, s59, v189
	ds_read_b128 v[128:131], v140
	ds_read_b128 v[132:135], v140 offset:1024
	ds_read_b128 v[136:139], v140 offset:2048
	ds_read_b128 v[140:143], v140 offset:3072
	ds_read_b128 v[144:147], v172
	ds_read_b128 v[148:151], v172 offset:1024
	ds_read_b128 v[168:171], v172 offset:2048
	ds_read_b128 v[172:175], v172 offset:3072
	s_add_u32 s40, s40, 0x40000
	s_addc_u32 s41, s41, 0
	s_mov_b32 m0, s44
	v_lshl_add_u64 v[226:227], s[40:41], 0, v[152:153]
	ds_read_b128 v[176:179], v193 offset:32768
	ds_read_b128 v[180:183], v193 offset:33792
	ds_read_b128 v[194:197], v193 offset:34816
	ds_read_b128 v[198:201], v193 offset:35840
	ds_read_b128 v[202:205], v193 offset:36864
	ds_read_b128 v[206:209], v193 offset:37888
	ds_read_b128 v[214:217], v193 offset:38912
	ds_read_b128 v[218:221], v193 offset:39936
	global_load_lds_dwordx4 v[226:227], off
	v_lshl_add_u64 v[226:227], s[40:41], 0, v[156:157]
	s_mov_b32 m0, s45
	s_nop 0
	global_load_lds_dwordx4 v[226:227], off
	s_waitcnt vmcnt(24)
	s_waitcnt lgkmcnt(0)
	s_barrier
	s_setprio 1
	s_waitcnt lgkmcnt(0)
	v_mfma_f32_16x16x32_bf16 v[124:127], v[128:131], v[176:179], v[124:127]
	v_mfma_f32_16x16x32_bf16 v[120:123], v[136:139], v[176:179], v[120:123]
	v_mfma_f32_16x16x32_bf16 v[108:111], v[128:131], v[194:197], v[108:111]
	v_mfma_f32_16x16x32_bf16 v[104:107], v[136:139], v[194:197], v[104:107]
	v_mfma_f32_16x16x32_bf16 v[92:95], v[128:131], v[202:205], v[92:95]
	v_mfma_f32_16x16x32_bf16 v[88:91], v[136:139], v[202:205], v[88:91]
	v_mfma_f32_16x16x32_bf16 v[76:79], v[128:131], v[214:217], v[76:79]
	v_mfma_f32_16x16x32_bf16 v[72:75], v[136:139], v[214:217], v[72:75]
	v_mfma_f32_16x16x32_bf16 v[124:127], v[132:135], v[180:183], v[124:127]
	v_mfma_f32_16x16x32_bf16 v[120:123], v[140:143], v[180:183], v[120:123]
	v_mfma_f32_16x16x32_bf16 v[108:111], v[132:135], v[198:201], v[108:111]
	v_mfma_f32_16x16x32_bf16 v[104:107], v[140:143], v[198:201], v[104:107]
	v_mfma_f32_16x16x32_bf16 v[92:95], v[132:135], v[206:209], v[92:95]
	v_mfma_f32_16x16x32_bf16 v[88:91], v[140:143], v[206:209], v[88:91]
	v_mfma_f32_16x16x32_bf16 v[76:79], v[132:135], v[218:221], v[76:79]
	v_mfma_f32_16x16x32_bf16 v[72:75], v[140:143], v[218:221], v[72:75]
	s_setprio 0
	s_setprio 1
	v_mfma_f32_16x16x32_bf16 v[116:119], v[144:147], v[176:179], v[116:119]
	v_mfma_f32_16x16x32_bf16 v[112:115], v[168:171], v[176:179], v[112:115]
	v_mfma_f32_16x16x32_bf16 v[100:103], v[144:147], v[194:197], v[100:103]
	v_mfma_f32_16x16x32_bf16 v[96:99], v[168:171], v[194:197], v[96:99]
	v_mfma_f32_16x16x32_bf16 v[84:87], v[144:147], v[202:205], v[84:87]
	v_mfma_f32_16x16x32_bf16 v[80:83], v[168:171], v[202:205], v[80:83]
	v_mfma_f32_16x16x32_bf16 v[68:71], v[144:147], v[214:217], v[68:71]
	v_mfma_f32_16x16x32_bf16 v[64:67], v[168:171], v[214:217], v[64:67]
	v_mfma_f32_16x16x32_bf16 v[116:119], v[148:151], v[180:183], v[116:119]
	v_mfma_f32_16x16x32_bf16 v[112:115], v[172:175], v[180:183], v[112:115]
	v_mfma_f32_16x16x32_bf16 v[100:103], v[148:151], v[198:201], v[100:103]
	v_mfma_f32_16x16x32_bf16 v[96:99], v[172:175], v[198:201], v[96:99]
	v_mfma_f32_16x16x32_bf16 v[84:87], v[148:151], v[206:209], v[84:87]
	v_mfma_f32_16x16x32_bf16 v[80:83], v[172:175], v[206:209], v[80:83]
	v_mfma_f32_16x16x32_bf16 v[68:71], v[148:151], v[218:221], v[68:71]
	v_mfma_f32_16x16x32_bf16 v[64:67], v[172:175], v[218:221], v[64:67]
	s_setprio 0
	s_barrier
; #define PG8_STAGE(bufoff, gbase, voff) do { _Pragma("unroll") for (int _i = 0; _i < 2; ++_i) \
;         __builtin_amdgcn_global_load_lds((const unsigned*)((const char*)(gbase) + (voff)[_i]), (PG8_LAS unsigned*)(lds + (bufoff) + ldsw + _i * 8192), 16, 0, 0); } while (0)
; #define PG8_LDA(dst, b, h) do { _Pragma("unroll") for (int m = 0; m < 4; ++m) _Pragma("unroll") for (int k = 0; k < 2; ++k) dst[m][k] = *(const PG8_LAS bf16x8*)(lds + PG8_SA(b, h) + aoff + m * 2048 + k * 1024); } while (0)
; #define PG8_LDB(dst, b, h) do { _Pragma("unroll") for (int n = 0; n < 2; ++n) _Pragma("unroll") for (int k = 0; k < 2; ++k) dst[n][k] = *(const PG8_LAS bf16x8*)(lds + PG8_SB(b, h) + boff + n * 2048 + k * 1024); } while (0)
; #define PG8_WAIT_V(n) asm volatile("s_waitcnt vmcnt(" #n ")" ::: "memory")
; #define PG8_BAR __builtin_amdgcn_s_barrier()
; template <class Epi, class Sched, bool ALIGN_EPI = false, bool SP2 = false>
; __device__ __forceinline__ void gemm_phase(PG8_LAS unsigned char* lds, const Gemm g, const Sched& S, const Epi& E, const int wv  ) {
;     ...
;         for (int t = 0; t < nt; t += 2) {
;             const bool last = (t == nt - 2);
;             const char* a1 = cA + (size_t)(t + 1) * kstep;
;             const char* a2 = last ? nA : cA + (size_t)(t + 2) * kstep; const char* b2 = last ? nB : cB + (size_t)(t + 2) * kstep;
;     ...
;             PG8_LDB(B0, 0, 0); PG8_LDB(B1, 0, 1); PG8_SCHED; PG8_LDA(At, 0, 0); PG8_STAGE(PG8_SA(1, 1), a1 + hstep, voffA);
;             PG8_WAIT_V(8); PG8_WAIT_L(0); PG8_BAR; PG8_MMA(0, 0, At, B0); PG8_MMA(0, 1, At, B1); PG8_BAR; PG8_SCHED;
;             PG8_LDA(At, 0, 1); PG8_STAGE(PG8_SB(0, 0), b2, voffB); PG8_STAGE(PG8_SB(0, 1), b2 + hstep, voffB); PG8_STAGE(PG8_SA(0, 0), a2, voffA);
;             PG8_WAIT_V(8); PG8_WAIT_L(0); PG8_BAR; PG8_MMA(1, 0, At, B0); PG8_MMA(1, 1, At, B1); PG8_BAR; PG8_SCHED;
;             PG8_LDB(B0, 1, 0); PG8_LDB(B1, 1, 1); PG8_SCHED; PG8_LDA(At, 1, 0); PG8_STAGE(PG8_SA(0, 1), a2 + hstep, voffA);
;             PG8_WAIT_V(8); PG8_WAIT_L(0); PG8_BAR; PG8_MMA(0, 0, At, B0); PG8_MMA(0, 1, At, B1); PG8_BAR; PG8_SCHED;
;             PG8_LDA(At, 1, 1); PG8_STAGE(PG8_SB(1, 0), b3, voffB); PG8_STAGE(PG8_SB(1, 1), b3 + hstep, voffB); PG8_STAGE(PG8_SA(1, 0), a3, voffA);
;             PG8_WAIT_V(8); PG8_WAIT_L(0); PG8_BAR; PG8_MMA(1, 0, At, B0); PG8_MMA(1, 1, At, B1); PG8_BAR; PG8_SCHED;
	s_add_i32 s40, s58, s33
	v_lshl_add_u64 v[184:185], v[184:185], 0, s[18:19]
	s_mov_b32 m0, s40
	ds_read_b128 v[176:179], v193 offset:49152
	ds_read_b128 v[180:183], v193 offset:50176
	ds_read_b128 v[194:197], v193 offset:51200
	ds_read_b128 v[198:201], v193 offset:52224
	ds_read_b128 v[202:205], v193 offset:53248
	ds_read_b128 v[206:209], v193 offset:54272
	ds_read_b128 v[214:217], v193 offset:55296
	ds_read_b128 v[218:221], v193 offset:56320
	global_load_lds_dwordx4 v[184:185], off
	s_add_i32 m0, s40, 0x2000
	s_add_u32 s38, s38, 0x40080
	v_lshl_add_u64 v[184:185], v[210:211], 0, s[18:19]
	s_addc_u32 s39, s39, 0
	s_add_i32 s40, s59, s33
	global_load_lds_dwordx4 v[184:185], off
	v_lshl_add_u64 v[184:185], s[38:39], 0, v[154:155]
	s_mov_b32 m0, s40
	s_nop 0
	global_load_lds_dwordx4 v[184:185], off
	v_lshl_add_u64 v[184:185], s[38:39], 0, v[158:159]
	s_add_i32 m0, s40, 0x2000
	s_nop 0
	global_load_lds_dwordx4 v[184:185], off
	v_lshl_add_u64 v[184:185], v[222:223], 0, s[18:19]
	s_mov_b32 m0, s49
	s_nop 0
	global_load_lds_dwordx4 v[184:185], off
	v_lshl_add_u64 v[184:185], v[224:225], 0, s[18:19]
	s_mov_b32 m0, s50
	s_nop 0
	global_load_lds_dwordx4 v[184:185], off
	s_waitcnt vmcnt(8)
	s_waitcnt lgkmcnt(0)
	s_barrier
	s_setprio 1
	s_waitcnt lgkmcnt(0)
	v_mfma_f32_16x16x32_bf16 v[60:63], v[128:131], v[176:179], v[60:63]
	v_mfma_f32_16x16x32_bf16 v[56:59], v[136:139], v[176:179], v[56:59]
	v_mfma_f32_16x16x32_bf16 v[44:47], v[128:131], v[194:197], v[44:47]
	v_mfma_f32_16x16x32_bf16 v[40:43], v[136:139], v[194:197], v[40:43]
	v_mfma_f32_16x16x32_bf16 v[28:31], v[128:131], v[202:205], v[28:31]
	v_mfma_f32_16x16x32_bf16 v[24:27], v[136:139], v[202:205], v[24:27]
	v_mfma_f32_16x16x32_bf16 v[12:15], v[128:131], v[214:217], v[12:15]
	v_mfma_f32_16x16x32_bf16 v[8:11], v[136:139], v[214:217], v[8:11]
	v_mfma_f32_16x16x32_bf16 v[60:63], v[132:135], v[180:183], v[60:63]
	v_mfma_f32_16x16x32_bf16 v[56:59], v[140:143], v[180:183], v[56:59]
	v_mfma_f32_16x16x32_bf16 v[44:47], v[132:135], v[198:201], v[44:47]
	v_mfma_f32_16x16x32_bf16 v[40:43], v[140:143], v[198:201], v[40:43]
	v_mfma_f32_16x16x32_bf16 v[28:31], v[132:135], v[206:209], v[28:31]
	v_mfma_f32_16x16x32_bf16 v[24:27], v[140:143], v[206:209], v[24:27]
	v_mfma_f32_16x16x32_bf16 v[12:15], v[132:135], v[218:221], v[12:15]
	v_mfma_f32_16x16x32_bf16 v[8:11], v[140:143], v[218:221], v[8:11]
	s_setprio 0
	s_setprio 1
	v_mfma_f32_16x16x32_bf16 v[52:55], v[144:147], v[176:179], v[52:55]
	v_mfma_f32_16x16x32_bf16 v[48:51], v[168:171], v[176:179], v[48:51]
	v_mfma_f32_16x16x32_bf16 v[36:39], v[144:147], v[194:197], v[36:39]
	v_mfma_f32_16x16x32_bf16 v[32:35], v[168:171], v[194:197], v[32:35]
	v_mfma_f32_16x16x32_bf16 v[20:23], v[144:147], v[202:205], v[20:23]
	v_mfma_f32_16x16x32_bf16 v[16:19], v[168:171], v[202:205], v[16:19]
	v_mfma_f32_16x16x32_bf16 v[4:7], v[144:147], v[214:217], v[4:7]
	v_mfma_f32_16x16x32_bf16 v[0:3], v[168:171], v[214:217], v[0:3]
	v_mfma_f32_16x16x32_bf16 v[52:55], v[148:151], v[180:183], v[52:55]
	v_mfma_f32_16x16x32_bf16 v[48:51], v[172:175], v[180:183], v[48:51]
	v_mfma_f32_16x16x32_bf16 v[36:39], v[148:151], v[198:201], v[36:39]
	v_mfma_f32_16x16x32_bf16 v[32:35], v[172:175], v[198:201], v[32:35]
	v_mfma_f32_16x16x32_bf16 v[20:23], v[148:151], v[206:209], v[20:23]
	v_mfma_f32_16x16x32_bf16 v[16:19], v[172:175], v[206:209], v[16:19]
	v_mfma_f32_16x16x32_bf16 v[4:7], v[148:151], v[218:221], v[4:7]
	v_mfma_f32_16x16x32_bf16 v[0:3], v[172:175], v[218:221], v[0:3]
	s_setprio 0
	s_barrier
	s_add_i32 s57, s57, 2
	s_add_u32 s36, s36, 0x100
	s_addc_u32 s37, s37, 0
	s_add_u32 s55, s55, 0x100
	s_addc_u32 s56, s56, 0
	s_cmp_gt_u32 s57, 13
	s_branch .LBB0_1215
.LpeelA_1215:
	ds_read_b128 v[128:131], v191
	ds_read_b128 v[132:135], v191 offset:1024
	ds_read_b128 v[136:139], v191 offset:2048
	ds_read_b128 v[140:143], v191 offset:3072
	ds_read_b128 v[144:147], v192
	ds_read_b128 v[148:151], v192 offset:1024
	ds_read_b128 v[168:171], v192 offset:2048
	ds_read_b128 v[172:175], v192 offset:3072
	s_add_u32 s38, s36, 0xfffc0080
	s_addc_u32 s39, s37, -1
	s_cmp_eq_u32 s57, 12
	s_cselect_b32 s41, s27, s39
	s_cselect_b32 s40, s35, s38
	s_cselect_b32 s39, s25, s56
	s_cselect_b32 s38, s54, s55
	v_lshl_add_u64 v[184:185], s[36:37], 0, v[160:161]
	s_add_i32 m0, s42, 0xc000
	ds_read_b128 v[176:179], v193
	ds_read_b128 v[180:183], v193 offset:1024
	ds_read_b128 v[194:197], v193 offset:2048
	ds_read_b128 v[198:201], v193 offset:3072
	ds_read_b128 v[202:205], v193 offset:4096
	ds_read_b128 v[206:209], v193 offset:5120
	ds_read_b128 v[214:217], v193 offset:6144
	ds_read_b128 v[218:221], v193 offset:7168
	global_load_lds_dwordx4 v[184:185], off
	v_lshl_add_u64 v[184:185], s[36:37], 0, v[162:163]
	s_add_i32 m0, s42, 0xe000
	s_nop 0
	global_load_lds_dwordx4 v[184:185], off
	s_waitcnt vmcnt(8)
	s_waitcnt lgkmcnt(0)
	s_barrier
; #define PG8_STAGE(bufoff, gbase, voff) do { _Pragma("unroll") for (int _i = 0; _i < 2; ++_i) \
;         __builtin_amdgcn_global_load_lds((const unsigned*)((const char*)(gbase) + (voff)[_i]), (PG8_LAS unsigned*)(lds + (bufoff) + ldsw + _i * 8192), 16, 0, 0); } while (0)
; #define PG8_LDA(dst, b, h) do { _Pragma("unroll") for (int m = 0; m < 4; ++m) _Pragma("unroll") for (int k = 0; k < 2; ++k) dst[m][k] = *(const PG8_LAS bf16x8*)(lds + PG8_SA(b, h) + aoff + m * 2048 + k * 1024); } while (0)
; #define PG8_LDB(dst, b, h) do { _Pragma("unroll") for (int n = 0; n < 2; ++n) _Pragma("unroll") for (int k = 0; k < 2; ++k) dst[n][k] = *(const PG8_LAS bf16x8*)(lds + PG8_SB(b, h) + boff + n * 2048 + k * 1024); } while (0)
; #define PG8_MMA(ai, bj, At, Bt) do { __builtin_amdgcn_s_setprio(1); _Pragma("unroll") for (int m = 0; m < 4; ++m) _Pragma("unroll") for (int n = 0; n < 2; ++n) _Pragma("unroll") for (int k = 0; k < 2; ++k) \
;         acc[ai][bj][m][n] = __builtin_amdgcn_mfma_f32_16x16x32_bf16(Bt[n][k], At[m][k], acc[ai][bj][m][n], 0, 0, 0); __builtin_amdgcn_s_setprio(0); } while (0)
; #define PG8_BAR __builtin_amdgcn_s_barrier()
; template <class Epi, class Sched, bool ALIGN_EPI = false, bool SP2 = false>
; __device__ __forceinline__ void gemm_phase(PG8_LAS unsigned char* lds, const Gemm g, const Sched& S, const Epi& E, const int wv  ) {
;     ...
;             PG8_LDB(B0, 0, 0); PG8_LDB(B1, 0, 1); PG8_SCHED; PG8_LDA(At, 0, 0); PG8_STAGE(PG8_SA(1, 1), a1 + hstep, voffA);
;             PG8_WAIT_V(8); PG8_WAIT_L(0); PG8_BAR; PG8_MMA(0, 0, At, B0); PG8_MMA(0, 1, At, B1); PG8_BAR; PG8_SCHED;
;             PG8_LDA(At, 0, 1); PG8_STAGE(PG8_SB(0, 0), b2, voffB); PG8_STAGE(PG8_SB(0, 1), b2 + hstep, voffB); PG8_STAGE(PG8_SA(0, 0), a2, voffA);
;             PG8_WAIT_V(8); PG8_WAIT_L(0); PG8_BAR; PG8_MMA(1, 0, At, B0); PG8_MMA(1, 1, At, B1); PG8_BAR; PG8_SCHED;
;             PG8_LDB(B0, 1, 0); PG8_LDB(B1, 1, 1); PG8_SCHED; PG8_LDA(At, 1, 0); PG8_STAGE(PG8_SA(0, 1), a2 + hstep, voffA);
;             PG8_WAIT_V(8); PG8_WAIT_L(0); PG8_BAR; PG8_MMA(0, 0, At, B0); PG8_MMA(0, 1, At, B1); PG8_BAR; PG8_SCHED;
;             PG8_LDA(At, 1, 1); PG8_STAGE(PG8_SB(1, 0), b3, voffB); PG8_STAGE(PG8_SB(1, 1), b3 + hstep, voffB); PG8_STAGE(PG8_SA(1, 0), a3, voffA);
;             PG8_WAIT_V(8); PG8_WAIT_L(0); PG8_BAR; PG8_MMA(1, 0, At, B0); PG8_MMA(1, 1, At, B1); PG8_BAR; PG8_SCHED;
	s_setprio 1
	s_waitcnt lgkmcnt(0)
	v_mfma_f32_16x16x32_bf16 v[124:127], v[128:131], v[176:179], 0
	v_mfma_f32_16x16x32_bf16 v[120:123], v[136:139], v[176:179], 0
	v_mfma_f32_16x16x32_bf16 v[108:111], v[128:131], v[194:197], 0
	v_mfma_f32_16x16x32_bf16 v[104:107], v[136:139], v[194:197], 0
	v_mfma_f32_16x16x32_bf16 v[92:95], v[128:131], v[202:205], 0
	v_mfma_f32_16x16x32_bf16 v[88:91], v[136:139], v[202:205], 0
	v_mfma_f32_16x16x32_bf16 v[76:79], v[128:131], v[214:217], 0
	v_mfma_f32_16x16x32_bf16 v[72:75], v[136:139], v[214:217], 0
	v_mfma_f32_16x16x32_bf16 v[124:127], v[132:135], v[180:183], v[124:127]
	v_mfma_f32_16x16x32_bf16 v[120:123], v[140:143], v[180:183], v[120:123]
	v_mfma_f32_16x16x32_bf16 v[108:111], v[132:135], v[198:201], v[108:111]
	v_mfma_f32_16x16x32_bf16 v[104:107], v[140:143], v[198:201], v[104:107]
	v_mfma_f32_16x16x32_bf16 v[92:95], v[132:135], v[206:209], v[92:95]
	v_mfma_f32_16x16x32_bf16 v[88:91], v[140:143], v[206:209], v[88:91]
	v_mfma_f32_16x16x32_bf16 v[76:79], v[132:135], v[218:221], v[76:79]
	v_mfma_f32_16x16x32_bf16 v[72:75], v[140:143], v[218:221], v[72:75]
	s_setprio 0
	s_setprio 1
	v_mfma_f32_16x16x32_bf16 v[116:119], v[144:147], v[176:179], 0
	v_mfma_f32_16x16x32_bf16 v[112:115], v[168:171], v[176:179], 0
	v_mfma_f32_16x16x32_bf16 v[100:103], v[144:147], v[194:197], 0
	v_mfma_f32_16x16x32_bf16 v[96:99], v[168:171], v[194:197], 0
	v_mfma_f32_16x16x32_bf16 v[84:87], v[144:147], v[202:205], 0
	v_mfma_f32_16x16x32_bf16 v[80:83], v[168:171], v[202:205], 0
	v_mfma_f32_16x16x32_bf16 v[68:71], v[144:147], v[214:217], 0
	v_mfma_f32_16x16x32_bf16 v[64:67], v[168:171], v[214:217], 0
	v_mfma_f32_16x16x32_bf16 v[116:119], v[148:151], v[180:183], v[116:119]
	v_mfma_f32_16x16x32_bf16 v[112:115], v[172:175], v[180:183], v[112:115]
	v_mfma_f32_16x16x32_bf16 v[100:103], v[148:151], v[198:201], v[100:103]
	v_mfma_f32_16x16x32_bf16 v[96:99], v[172:175], v[198:201], v[96:99]
	v_mfma_f32_16x16x32_bf16 v[84:87], v[148:151], v[206:209], v[84:87]
	v_mfma_f32_16x16x32_bf16 v[80:83], v[172:175], v[206:209], v[80:83]
	v_mfma_f32_16x16x32_bf16 v[68:71], v[148:151], v[218:221], v[68:71]
	v_mfma_f32_16x16x32_bf16 v[64:67], v[172:175], v[218:221], v[64:67]
	s_setprio 0
	s_barrier
	s_add_i32 s58, s51, s33
	v_lshl_add_u64 v[184:185], s[38:39], 0, v[154:155]
	s_mov_b32 m0, s58
	ds_read_b128 v[176:179], v193 offset:16384
	ds_read_b128 v[180:183], v193 offset:17408
	ds_read_b128 v[194:197], v193 offset:18432
	ds_read_b128 v[198:201], v193 offset:19456
	ds_read_b128 v[202:205], v193 offset:20480
	ds_read_b128 v[206:209], v193 offset:21504
	ds_read_b128 v[214:217], v193 offset:22528
	ds_read_b128 v[218:221], v193 offset:23552
	global_load_lds_dwordx4 v[184:185], off
	s_add_i32 m0, s58, 0x2000
	s_add_u32 s58, s38, 0x40000
	v_lshl_add_u64 v[210:211], s[38:39], 0, v[158:159]
	s_addc_u32 s59, s39, 0
	s_add_i32 s60, s52, s33
	global_load_lds_dwordx4 v[210:211], off
	v_lshl_add_u64 v[222:223], s[58:59], 0, v[154:155]
	s_mov_b32 m0, s60
	v_lshl_add_u64 v[224:225], s[40:41], 0, v[156:157]
	global_load_lds_dwordx4 v[222:223], off
	v_lshl_add_u64 v[222:223], s[58:59], 0, v[158:159]
	s_add_i32 m0, s60, 0x2000
	s_nop 0
	global_load_lds_dwordx4 v[222:223], off
	v_lshl_add_u64 v[222:223], s[40:41], 0, v[152:153]
	s_mov_b32 m0, s42
	s_nop 0
	global_load_lds_dwordx4 v[222:223], off
	s_mov_b32 m0, s43
	s_nop 0
	global_load_lds_dwordx4 v[224:225], off
	s_waitcnt vmcnt(8)
	s_waitcnt lgkmcnt(0)
	s_barrier
	s_setprio 1
	s_waitcnt lgkmcnt(0)
	v_mfma_f32_16x16x32_bf16 v[60:63], v[128:131], v[176:179], 0
	v_mfma_f32_16x16x32_bf16 v[56:59], v[136:139], v[176:179], 0
	v_mfma_f32_16x16x32_bf16 v[44:47], v[128:131], v[194:197], 0
	v_mfma_f32_16x16x32_bf16 v[40:43], v[136:139], v[194:197], 0
	v_mfma_f32_16x16x32_bf16 v[28:31], v[128:131], v[202:205], 0
	v_mfma_f32_16x16x32_bf16 v[24:27], v[136:139], v[202:205], 0
	v_mfma_f32_16x16x32_bf16 v[12:15], v[128:131], v[214:217], 0
	v_mfma_f32_16x16x32_bf16 v[8:11], v[136:139], v[214:217], 0
	v_mfma_f32_16x16x32_bf16 v[60:63], v[132:135], v[180:183], v[60:63]
	v_mfma_f32_16x16x32_bf16 v[56:59], v[140:143], v[180:183], v[56:59]
	v_mfma_f32_16x16x32_bf16 v[44:47], v[132:135], v[198:201], v[44:47]
	v_mfma_f32_16x16x32_bf16 v[40:43], v[140:143], v[198:201], v[40:43]
	v_mfma_f32_16x16x32_bf16 v[28:31], v[132:135], v[206:209], v[28:31]
	v_mfma_f32_16x16x32_bf16 v[24:27], v[140:143], v[206:209], v[24:27]
	v_mfma_f32_16x16x32_bf16 v[12:15], v[132:135], v[218:221], v[12:15]
	v_mfma_f32_16x16x32_bf16 v[8:11], v[140:143], v[218:221], v[8:11]
	s_setprio 0
	s_setprio 1
	v_mfma_f32_16x16x32_bf16 v[52:55], v[144:147], v[176:179], 0
	v_mfma_f32_16x16x32_bf16 v[48:51], v[168:171], v[176:179], 0
	v_mfma_f32_16x16x32_bf16 v[36:39], v[144:147], v[194:197], 0
	v_mfma_f32_16x16x32_bf16 v[32:35], v[168:171], v[194:197], 0
	v_mfma_f32_16x16x32_bf16 v[20:23], v[144:147], v[202:205], 0
	v_mfma_f32_16x16x32_bf16 v[16:19], v[168:171], v[202:205], 0
	v_mfma_f32_16x16x32_bf16 v[4:7], v[144:147], v[214:217], 0
	v_mfma_f32_16x16x32_bf16 v[0:3], v[168:171], v[214:217], 0
	v_mfma_f32_16x16x32_bf16 v[52:55], v[148:151], v[180:183], v[52:55]
	v_mfma_f32_16x16x32_bf16 v[48:51], v[172:175], v[180:183], v[48:51]
	v_mfma_f32_16x16x32_bf16 v[36:39], v[148:151], v[198:201], v[36:39]
	v_mfma_f32_16x16x32_bf16 v[32:35], v[172:175], v[198:201], v[32:35]
	v_mfma_f32_16x16x32_bf16 v[20:23], v[148:151], v[206:209], v[20:23]
	v_mfma_f32_16x16x32_bf16 v[16:19], v[172:175], v[206:209], v[16:19]
	v_mfma_f32_16x16x32_bf16 v[4:7], v[148:151], v[218:221], v[4:7]
	v_mfma_f32_16x16x32_bf16 v[0:3], v[172:175], v[218:221], v[0:3]
	s_setprio 0
	s_barrier
; #define PG8_STAGE(bufoff, gbase, voff) do { _Pragma("unroll") for (int _i = 0; _i < 2; ++_i) \
;         __builtin_amdgcn_global_load_lds((const unsigned*)((const char*)(gbase) + (voff)[_i]), (PG8_LAS unsigned*)(lds + (bufoff) + ldsw + _i * 8192), 16, 0, 0); } while (0)
; #define PG8_LDA(dst, b, h) do { _Pragma("unroll") for (int m = 0; m < 4; ++m) _Pragma("unroll") for (int k = 0; k < 2; ++k) dst[m][k] = *(const PG8_LAS bf16x8*)(lds + PG8_SA(b, h) + aoff + m * 2048 + k * 1024); } while (0)
; #define PG8_LDB(dst, b, h) do { _Pragma("unroll") for (int n = 0; n < 2; ++n) _Pragma("unroll") for (int k = 0; k < 2; ++k) dst[n][k] = *(const PG8_LAS bf16x8*)(lds + PG8_SB(b, h) + boff + n * 2048 + k * 1024); } while (0)
; #define PG8_MMA(ai, bj, At, Bt) do { __builtin_amdgcn_s_setprio(1); _Pragma("unroll") for (int m = 0; m < 4; ++m) _Pragma("unroll") for (int n = 0; n < 2; ++n) _Pragma("unroll") for (int k = 0; k < 2; ++k) \
;         acc[ai][bj][m][n] = __builtin_amdgcn_mfma_f32_16x16x32_bf16(Bt[n][k], At[m][k], acc[ai][bj][m][n], 0, 0, 0); __builtin_amdgcn_s_setprio(0); } while (0)
; #define PG8_BAR __builtin_amdgcn_s_barrier()
; template <class Epi, class Sched, bool ALIGN_EPI = false, bool SP2 = false>
; __device__ __forceinline__ void gemm_phase(PG8_LAS unsigned char* lds, const Gemm g, const Sched& S, const Epi& E, const int wv  ) {
;     ...
;             PG8_LDB(B0, 0, 0); PG8_LDB(B1, 0, 1); PG8_SCHED; PG8_LDA(At, 0, 0); PG8_STAGE(PG8_SA(1, 1), a1 + hstep, voffA);
;             PG8_WAIT_V(8); PG8_WAIT_L(0); PG8_BAR; PG8_MMA(0, 0, At, B0); PG8_MMA(0, 1, At, B1); PG8_BAR; PG8_SCHED;
;             PG8_LDA(At, 0, 1); PG8_STAGE(PG8_SB(0, 0), b2, voffB); PG8_STAGE(PG8_SB(0, 1), b2 + hstep, voffB); PG8_STAGE(PG8_SA(0, 0), a2, voffA);
;             PG8_WAIT_V(8); PG8_WAIT_L(0); PG8_BAR; PG8_MMA(1, 0, At, B0); PG8_MMA(1, 1, At, B1); PG8_BAR; PG8_SCHED;
;             PG8_LDB(B0, 1, 0); PG8_LDB(B1, 1, 1); PG8_SCHED; PG8_LDA(At, 1, 0); PG8_STAGE(PG8_SA(0, 1), a2 + hstep, voffA);
;             PG8_WAIT_V(8); PG8_WAIT_L(0); PG8_BAR; PG8_MMA(0, 0, At, B0); PG8_MMA(0, 1, At, B1); PG8_BAR; PG8_SCHED;
;             PG8_LDA(At, 1, 1); PG8_STAGE(PG8_SB(1, 0), b3, voffB); PG8_STAGE(PG8_SB(1, 1), b3 + hstep, voffB); PG8_STAGE(PG8_SA(1, 0), a3, voffA);
;             PG8_WAIT_V(8); PG8_WAIT_L(0); PG8_BAR; PG8_MMA(1, 0, At, B0); PG8_MMA(1, 1, At, B1); PG8_BAR; PG8_SCHED;
	s_add_i32 s58, 0, 0x18000
	s_add_i32 s59, 0, 0x1c000
	v_add_u32_e32 v140, s58, v189
	v_add_u32_e32 v172, s59, v189
	ds_read_b128 v[128:131], v140
	ds_read_b128 v[132:135], v140 offset:1024
	ds_read_b128 v[136:139], v140 offset:2048
	ds_read_b128 v[140:143], v140 offset:3072
	ds_read_b128 v[144:147], v172
	ds_read_b128 v[148:151], v172 offset:1024
	ds_read_b128 v[168:171], v172 offset:2048
	ds_read_b128 v[172:175], v172 offset:3072
	s_add_u32 s40, s40, 0x40000
	s_addc_u32 s41, s41, 0
	s_mov_b32 m0, s44
	v_lshl_add_u64 v[226:227], s[40:41], 0, v[152:153]
	ds_read_b128 v[176:179], v193 offset:32768
	ds_read_b128 v[180:183], v193 offset:33792
	ds_read_b128 v[194:197], v193 offset:34816
	ds_read_b128 v[198:201], v193 offset:35840
	ds_read_b128 v[202:205], v193 offset:36864
	ds_read_b128 v[206:209], v193 offset:37888
	ds_read_b128 v[214:217], v193 offset:38912
	ds_read_b128 v[218:221], v193 offset:39936
	global_load_lds_dwordx4 v[226:227], off
	v_lshl_add_u64 v[226:227], s[40:41], 0, v[156:157]
	s_mov_b32 m0, s45
	s_nop 0
	global_load_lds_dwordx4 v[226:227], off
	s_waitcnt vmcnt(8)
	s_waitcnt lgkmcnt(0)
	s_barrier
	s_setprio 1
	s_waitcnt lgkmcnt(0)
	v_mfma_f32_16x16x32_bf16 v[124:127], v[128:131], v[176:179], v[124:127]
	v_mfma_f32_16x16x32_bf16 v[120:123], v[136:139], v[176:179], v[120:123]
	v_mfma_f32_16x16x32_bf16 v[108:111], v[128:131], v[194:197], v[108:111]
	v_mfma_f32_16x16x32_bf16 v[104:107], v[136:139], v[194:197], v[104:107]
	v_mfma_f32_16x16x32_bf16 v[92:95], v[128:131], v[202:205], v[92:95]
	v_mfma_f32_16x16x32_bf16 v[88:91], v[136:139], v[202:205], v[88:91]
	v_mfma_f32_16x16x32_bf16 v[76:79], v[128:131], v[214:217], v[76:79]
	v_mfma_f32_16x16x32_bf16 v[72:75], v[136:139], v[214:217], v[72:75]
	v_mfma_f32_16x16x32_bf16 v[124:127], v[132:135], v[180:183], v[124:127]
	v_mfma_f32_16x16x32_bf16 v[120:123], v[140:143], v[180:183], v[120:123]
	v_mfma_f32_16x16x32_bf16 v[108:111], v[132:135], v[198:201], v[108:111]
	v_mfma_f32_16x16x32_bf16 v[104:107], v[140:143], v[198:201], v[104:107]
	v_mfma_f32_16x16x32_bf16 v[92:95], v[132:135], v[206:209], v[92:95]
	v_mfma_f32_16x16x32_bf16 v[88:91], v[140:143], v[206:209], v[88:91]
	v_mfma_f32_16x16x32_bf16 v[76:79], v[132:135], v[218:221], v[76:79]
	v_mfma_f32_16x16x32_bf16 v[72:75], v[140:143], v[218:221], v[72:75]
	s_setprio 0
	s_setprio 1
	v_mfma_f32_16x16x32_bf16 v[116:119], v[144:147], v[176:179], v[116:119]
	v_mfma_f32_16x16x32_bf16 v[112:115], v[168:171], v[176:179], v[112:115]
	v_mfma_f32_16x16x32_bf16 v[100:103], v[144:147], v[194:197], v[100:103]
	v_mfma_f32_16x16x32_bf16 v[96:99], v[168:171], v[194:197], v[96:99]
	v_mfma_f32_16x16x32_bf16 v[84:87], v[144:147], v[202:205], v[84:87]
	v_mfma_f32_16x16x32_bf16 v[80:83], v[168:171], v[202:205], v[80:83]
	v_mfma_f32_16x16x32_bf16 v[68:71], v[144:147], v[214:217], v[68:71]
	v_mfma_f32_16x16x32_bf16 v[64:67], v[168:171], v[214:217], v[64:67]
	v_mfma_f32_16x16x32_bf16 v[116:119], v[148:151], v[180:183], v[116:119]
	v_mfma_f32_16x16x32_bf16 v[112:115], v[172:175], v[180:183], v[112:115]
	v_mfma_f32_16x16x32_bf16 v[100:103], v[148:151], v[198:201], v[100:103]
	v_mfma_f32_16x16x32_bf16 v[96:99], v[172:175], v[198:201], v[96:99]
	v_mfma_f32_16x16x32_bf16 v[84:87], v[148:151], v[206:209], v[84:87]
	v_mfma_f32_16x16x32_bf16 v[80:83], v[172:175], v[206:209], v[80:83]
	v_mfma_f32_16x16x32_bf16 v[68:71], v[148:151], v[218:221], v[68:71]
	v_mfma_f32_16x16x32_bf16 v[64:67], v[172:175], v[218:221], v[64:67]
	s_setprio 0
	s_barrier
; #define PG8_STAGE(bufoff, gbase, voff) do { _Pragma("unroll") for (int _i = 0; _i < 2; ++_i) \
;         __builtin_amdgcn_global_load_lds((const unsigned*)((const char*)(gbase) + (voff)[_i]), (PG8_LAS unsigned*)(lds + (bufoff) + ldsw + _i * 8192), 16, 0, 0); } while (0)
; #define PG8_LDA(dst, b, h) do { _Pragma("unroll") for (int m = 0; m < 4; ++m) _Pragma("unroll") for (int k = 0; k < 2; ++k) dst[m][k] = *(const PG8_LAS bf16x8*)(lds + PG8_SA(b, h) + aoff + m * 2048 + k * 1024); } while (0)
; #define PG8_LDB(dst, b, h) do { _Pragma("unroll") for (int n = 0; n < 2; ++n) _Pragma("unroll") for (int k = 0; k < 2; ++k) dst[n][k] = *(const PG8_LAS bf16x8*)(lds + PG8_SB(b, h) + boff + n * 2048 + k * 1024); } while (0)
; #define PG8_MMA(ai, bj, At, Bt) do { __builtin_amdgcn_s_setprio(1); _Pragma("unroll") for (int m = 0; m < 4; ++m) _Pragma("unroll") for (int n = 0; n < 2; ++n) _Pragma("unroll") for (int k = 0; k < 2; ++k) \
;         acc[ai][bj][m][n] = __builtin_amdgcn_mfma_f32_16x16x32_bf16(Bt[n][k], At[m][k], acc[ai][bj][m][n], 0, 0, 0); __builtin_amdgcn_s_setprio(0); } while (0)
; #define PG8_BAR __builtin_amdgcn_s_barrier()
; template <class Epi, class Sched, bool ALIGN_EPI = false, bool SP2 = false>
; __device__ __forceinline__ void gemm_phase(PG8_LAS unsigned char* lds, const Gemm g, const Sched& S, const Epi& E, const int wv  ) {
;     ...
;             PG8_LDB(B0, 0, 0); PG8_LDB(B1, 0, 1); PG8_SCHED; PG8_LDA(At, 0, 0); PG8_STAGE(PG8_SA(1, 1), a1 + hstep, voffA);
;             PG8_WAIT_V(8); PG8_WAIT_L(0); PG8_BAR; PG8_MMA(0, 0, At, B0); PG8_MMA(0, 1, At, B1); PG8_BAR; PG8_SCHED;
;             PG8_LDA(At, 0, 1); PG8_STAGE(PG8_SB(0, 0), b2, voffB); PG8_STAGE(PG8_SB(0, 1), b2 + hstep, voffB); PG8_STAGE(PG8_SA(0, 0), a2, voffA);
;             PG8_WAIT_V(8); PG8_WAIT_L(0); PG8_BAR; PG8_MMA(1, 0, At, B0); PG8_MMA(1, 1, At, B1); PG8_BAR; PG8_SCHED;
;             PG8_LDB(B0, 1, 0); PG8_LDB(B1, 1, 1); PG8_SCHED; PG8_LDA(At, 1, 0); PG8_STAGE(PG8_SA(0, 1), a2 + hstep, voffA);
;             PG8_WAIT_V(8); PG8_WAIT_L(0); PG8_BAR; PG8_MMA(0, 0, At, B0); PG8_MMA(0, 1, At, B1); PG8_BAR; PG8_SCHED;
;             PG8_LDA(At, 1, 1); PG8_STAGE(PG8_SB(1, 0), b3, voffB); PG8_STAGE(PG8_SB(1, 1), b3 + hstep, voffB); PG8_STAGE(PG8_SA(1, 0), a3, voffA);
;             PG8_WAIT_V(8); PG8_WAIT_L(0); PG8_BAR; PG8_MMA(1, 0, At, B0); PG8_MMA(1, 1, At, B1); PG8_BAR; PG8_SCHED;
	s_add_i32 s40, s58, s33
	v_lshl_add_u64 v[184:185], v[184:185], 0, s[18:19]
	s_mov_b32 m0, s40
	ds_read_b128 v[176:179], v193 offset:49152
	ds_read_b128 v[180:183], v193 offset:50176
	ds_read_b128 v[194:197], v193 offset:51200
	ds_read_b128 v[198:201], v193 offset:52224
	ds_read_b128 v[202:205], v193 offset:53248
	ds_read_b128 v[206:209], v193 offset:54272
	ds_read_b128 v[214:217], v193 offset:55296
	ds_read_b128 v[218:221], v193 offset:56320
	global_load_lds_dwordx4 v[184:185], off
	s_add_i32 m0, s40, 0x2000
	s_add_u32 s38, s38, 0x40080
	v_lshl_add_u64 v[184:185], v[210:211], 0, s[18:19]
	s_addc_u32 s39, s39, 0
	s_add_i32 s40, s59, s33
	global_load_lds_dwordx4 v[184:185], off
	v_lshl_add_u64 v[184:185], s[38:39], 0, v[154:155]
	s_mov_b32 m0, s40
	s_nop 0
	global_load_lds_dwordx4 v[184:185], off
	v_lshl_add_u64 v[184:185], s[38:39], 0, v[158:159]
	s_add_i32 m0, s40, 0x2000
	s_nop 0
	global_load_lds_dwordx4 v[184:185], off
	v_lshl_add_u64 v[184:185], v[222:223], 0, s[18:19]
	s_mov_b32 m0, s49
	s_nop 0
	global_load_lds_dwordx4 v[184:185], off
	v_lshl_add_u64 v[184:185], v[224:225], 0, s[18:19]
	s_mov_b32 m0, s50
	s_nop 0
	global_load_lds_dwordx4 v[184:185], off
	s_waitcnt vmcnt(8)
	s_waitcnt lgkmcnt(0)
	s_barrier
	s_setprio 1
	s_waitcnt lgkmcnt(0)
	v_mfma_f32_16x16x32_bf16 v[60:63], v[128:131], v[176:179], v[60:63]
	v_mfma_f32_16x16x32_bf16 v[56:59], v[136:139], v[176:179], v[56:59]
	v_mfma_f32_16x16x32_bf16 v[44:47], v[128:131], v[194:197], v[44:47]
	v_mfma_f32_16x16x32_bf16 v[40:43], v[136:139], v[194:197], v[40:43]
	v_mfma_f32_16x16x32_bf16 v[28:31], v[128:131], v[202:205], v[28:31]
	v_mfma_f32_16x16x32_bf16 v[24:27], v[136:139], v[202:205], v[24:27]
	v_mfma_f32_16x16x32_bf16 v[12:15], v[128:131], v[214:217], v[12:15]
	v_mfma_f32_16x16x32_bf16 v[8:11], v[136:139], v[214:217], v[8:11]
	v_mfma_f32_16x16x32_bf16 v[60:63], v[132:135], v[180:183], v[60:63]
	v_mfma_f32_16x16x32_bf16 v[56:59], v[140:143], v[180:183], v[56:59]
	v_mfma_f32_16x16x32_bf16 v[44:47], v[132:135], v[198:201], v[44:47]
	v_mfma_f32_16x16x32_bf16 v[40:43], v[140:143], v[198:201], v[40:43]
	v_mfma_f32_16x16x32_bf16 v[28:31], v[132:135], v[206:209], v[28:31]
	v_mfma_f32_16x16x32_bf16 v[24:27], v[140:143], v[206:209], v[24:27]
	v_mfma_f32_16x16x32_bf16 v[12:15], v[132:135], v[218:221], v[12:15]
	v_mfma_f32_16x16x32_bf16 v[8:11], v[140:143], v[218:221], v[8:11]
	s_setprio 0
	s_setprio 1
	v_mfma_f32_16x16x32_bf16 v[52:55], v[144:147], v[176:179], v[52:55]
	v_mfma_f32_16x16x32_bf16 v[48:51], v[168:171], v[176:179], v[48:51]
	v_mfma_f32_16x16x32_bf16 v[36:39], v[144:147], v[194:197], v[36:39]
	v_mfma_f32_16x16x32_bf16 v[32:35], v[168:171], v[194:197], v[32:35]
	v_mfma_f32_16x16x32_bf16 v[20:23], v[144:147], v[202:205], v[20:23]
	v_mfma_f32_16x16x32_bf16 v[16:19], v[168:171], v[202:205], v[16:19]
	v_mfma_f32_16x16x32_bf16 v[4:7], v[144:147], v[214:217], v[4:7]
	v_mfma_f32_16x16x32_bf16 v[0:3], v[168:171], v[214:217], v[0:3]
	v_mfma_f32_16x16x32_bf16 v[52:55], v[148:151], v[180:183], v[52:55]
	v_mfma_f32_16x16x32_bf16 v[48:51], v[172:175], v[180:183], v[48:51]
	v_mfma_f32_16x16x32_bf16 v[36:39], v[148:151], v[198:201], v[36:39]
	v_mfma_f32_16x16x32_bf16 v[32:35], v[172:175], v[198:201], v[32:35]
	v_mfma_f32_16x16x32_bf16 v[20:23], v[148:151], v[206:209], v[20:23]
	v_mfma_f32_16x16x32_bf16 v[16:19], v[172:175], v[206:209], v[16:19]
	v_mfma_f32_16x16x32_bf16 v[4:7], v[148:151], v[218:221], v[4:7]
	v_mfma_f32_16x16x32_bf16 v[0:3], v[172:175], v[218:221], v[0:3]
	s_setprio 0
	s_barrier
	s_add_i32 s57, s57, 2
	s_add_u32 s36, s36, 0x100
	s_addc_u32 s37, s37, 0
	s_add_u32 s55, s55, 0x100
	s_addc_u32 s56, s56, 0
	s_cmp_gt_u32 s57, 13

; __device__ __forceinline__ unsigned cvt_pk_bf16(float lo, float hi) { unsigned r; asm volatile("v_cvt_pk_bf16_f32 %0, %1, %2" : "=v"(r) : "v"(lo), "v"(hi)); return r; }
;     __device__ __forceinline__ void operator()(const f32x4 (&acc)[2][2][4][2], const Unit& u, int wr, int wc, int fr, int fq) const {
;     ...
;                 for (int bj = 0; bj < 2; ++bj) { const size_t off = (size_t)(row0 + ai * HALF + m * 16) * 1024 + col0 + bj * HALF;
;                     if (BASE_BF16) bw[m][bj] = *(const u32x4*)((const bf16_t*)base + off);
;                     else { bf[m][bj][0] = *(const f32x4*)((const float*)base + off); bf[m][bj][1] = *(const f32x4*)((const float*)base + off + 4); } }
; #pragma unroll
;             for (int m = 0; m < 4; ++m) {
;                 const int row = row0 + ai * HALF + m * 16; const size_t off = (size_t)row * 1024 + col0;
;                 float ss = 0.f;
; #pragma unroll
;                 for (int bj = 0; bj < 2; ++bj) {
;                     f32x4 b0, b1;
;                     if (BASE_BF16) { const u32x4 w = bw[m][bj];
;                         b0 = (f32x4){__builtin_bit_cast(float, w.x << 16), __builtin_bit_cast(float, w.x & 0xffff0000u), __builtin_bit_cast(float, w.y << 16), __builtin_bit_cast(float, w.y & 0xffff0000u)};
;                         b1 = (f32x4){__builtin_bit_cast(float, w.z << 16), __builtin_bit_cast(float, w.z & 0xffff0000u), __builtin_bit_cast(float, w.w << 16), __builtin_bit_cast(float, w.w & 0xffff0000u)}; }
;                     else { b0 = bf[m][bj][0]; b1 = bf[m][bj][1]; }
;                     const f32x4 v0 = acc[ai][bj][m][0] + b0, v1 = acc[ai][bj][m][1] + b1;
;                     ss += (v0[0] * v0[0] + v0[1] * v0[1]) + (v0[2] * v0[2] + v0[3] * v0[3]) + (v1[0] * v1[0] + v1[1] * v1[1]) + (v1[2] * v1[2] + v1[3] * v1[3]);
;                     if (OUT_BF16) { u32x4 w; w.x = cvt_pk_bf16(v0[0], v0[1]); w.y = cvt_pk_bf16(v0[2], v0[3]); w.z = cvt_pk_bf16(v1[0], v1[1]); w.w = cvt_pk_bf16(v1[2], v1[3]);
;                         *(u32x4*)((bf16_t*)out + off + bj * HALF) = w; }
;                     else { *(f32x4*)((float*)out + off + bj * HALF) = v0; *(f32x4*)((float*)out + off + bj * HALF + 4) = v1; }
;                 }
;                 ss += __shfl_xor(ss, 16); ss += __shfl_xor(ss, 32);
;                 if (fq == 0) sspart[(size_t)row * 16 + u.pn * 4 + wc] = ss;
.LBB0_1218:
	s_add_u32 s60, s35, 0x40080
	s_addc_u32 s61, s27, 0
	v_lshl_add_u64 v[184:185], s[60:61], 0, v[160:161]
	s_add_i32 m0, s42, 0xc000
	s_nop 0
	global_load_lds_dwordx4 v[184:185], off
	v_lshl_add_u64 v[184:185], s[60:61], 0, v[162:163]
	s_add_i32 m0, s42, 0xe000
	s_nop 0
	global_load_lds_dwordx4 v[184:185], off
	v_lshl_or_b32 v168, s8, 8, v190
	v_lshl_add_u32 v172, s34, 8, v188
	v_ashrrev_i32_e32 v169, 31, v168
	v_lshlrev_b64 v[202:203], 1, v[168:169]
	v_ashrrev_i32_e32 v173, 31, v172
	v_lshl_add_u64 v[170:171], s[12:13], 0, v[202:203]
	v_lshlrev_b64 v[204:205], 11, v[172:173]
	v_lshl_add_u64 v[128:129], v[170:171], 0, v[204:205]
	global_load_dwordx4 v[194:197], v[128:129], off
	global_load_dwordx4 v[198:201], v[128:129], off offset:256
	v_or_b32_e32 v182, 16, v172
	v_or_b32_e32 v178, 32, v172
	v_or_b32_e32 v174, 48, v172
	v_ashrrev_i32_e32 v183, 31, v182
	v_ashrrev_i32_e32 v179, 31, v178
	v_ashrrev_i32_e32 v175, 31, v174
	v_lshlrev_b64 v[184:185], 11, v[182:183]
	v_lshlrev_b64 v[180:181], 11, v[178:179]
	v_lshlrev_b64 v[176:177], 11, v[174:175]
	v_lshl_add_u64 v[128:129], v[170:171], 0, v[184:185]
	v_lshl_add_u64 v[130:131], v[170:171], 0, v[180:181]
	v_lshl_add_u64 v[206:207], v[170:171], 0, v[176:177]
	global_load_dwordx4 v[148:151], v[128:129], off
	global_load_dwordx4 v[144:147], v[128:129], off offset:256
	global_load_dwordx4 v[140:143], v[130:131], off
	global_load_dwordx4 v[136:139], v[130:131], off offset:256
	global_load_dwordx4 v[132:135], v[206:207], off
	s_nop 0
	global_load_dwordx4 v[128:131], v[206:207], off offset:256
	s_lshl_b32 s34, s8, 2
	s_ashr_i32 s35, s34, 31
	s_waitcnt vmcnt(0)
	v_lshlrev_b32_e32 v206, 16, v194
	v_and_b32_e32 v207, 0xffff0000, v194
	v_lshlrev_b32_e32 v194, 16, v195
	v_and_b32_e32 v195, 0xffff0000, v195
	v_lshlrev_b32_e32 v208, 16, v196
	v_and_b32_e32 v209, 0xffff0000, v196
	v_lshlrev_b32_e32 v196, 16, v197
	v_and_b32_e32 v197, 0xffff0000, v197
	v_lshlrev_b32_e32 v210, 16, v198
	v_and_b32_e32 v211, 0xffff0000, v198
	v_lshlrev_b32_e32 v198, 16, v199
	v_and_b32_e32 v199, 0xffff0000, v199
	v_lshlrev_b32_e32 v214, 16, v200
	v_and_b32_e32 v215, 0xffff0000, v200
	v_lshlrev_b32_e32 v200, 16, v201
	v_and_b32_e32 v201, 0xffff0000, v201
	v_pk_add_f32 v[126:127], v[126:127], v[194:195]
	v_pk_add_f32 v[124:125], v[124:125], v[206:207]
	v_pk_add_f32 v[122:123], v[122:123], v[196:197]
	v_pk_add_f32 v[120:121], v[120:121], v[208:209]
	v_pk_add_f32 v[118:119], v[118:119], v[198:199]
	v_pk_add_f32 v[116:117], v[116:117], v[210:211]
	v_pk_add_f32 v[194:195], v[114:115], v[200:201]
	v_pk_add_f32 v[196:197], v[112:113], v[214:215]
	v_mul_f32_e32 v198, v125, v125
	v_mul_f32_e32 v199, v127, v127
	v_mul_f32_e32 v200, v121, v121
	v_mul_f32_e32 v201, v123, v123
	v_cvt_pk_bf16_f32 v112, v124, v125
	v_cvt_pk_bf16_f32 v113, v126, v127
	v_cvt_pk_bf16_f32 v114, v120, v121
	v_cvt_pk_bf16_f32 v115, v122, v123
	v_mul_f32_e32 v121, v117, v117
	v_mul_f32_e32 v123, v119, v119
	v_mul_f32_e32 v125, v197, v197
	v_fmac_f32_e32 v198, v124, v124
	v_fmac_f32_e32 v199, v126, v126
	v_fmac_f32_e32 v121, v116, v116
	v_fmac_f32_e32 v123, v118, v118
	v_mul_f32_e32 v127, v195, v195
	v_fmac_f32_e32 v200, v120, v120
	v_fmac_f32_e32 v125, v196, v196
	v_add_f32_e32 v120, v198, v199
	v_add_f32_e32 v121, v121, v123
	v_fmac_f32_e32 v201, v122, v122
	v_fmac_f32_e32 v127, v194, v194
	v_add_f32_e32 v120, v200, v120
	v_add_f32_e32 v121, v125, v121
	v_add_f32_e32 v120, v201, v120
	v_add_f32_e32 v121, v127, v121
	v_add_f32_e32 v122, v120, v121
	ds_bpermute_b32 v123, v186, v122
	v_lshl_add_u64 v[120:121], s[14:15], 0, v[204:205]
	v_lshl_add_u64 v[120:121], v[120:121], 0, v[202:203]
	ds_bpermute_b32 v240, v253, v112
	ds_bpermute_b32 v241, v253, v113
	ds_bpermute_b32 v242, v253, v114
	ds_bpermute_b32 v243, v253, v115
	v_lshl_add_u64 v[236:237], v[120:121], 0, v[250:251]
	s_waitcnt lgkmcnt(4)
	s_nop 0
	v_add_f32_e32 v112, v122, v123
	ds_bpermute_b32 v113, v187, v112
	v_cvt_pk_bf16_f32 v114, v116, v117
	v_cvt_pk_bf16_f32 v115, v118, v119
	v_cvt_pk_bf16_f32 v116, v196, v197
	v_cvt_pk_bf16_f32 v117, v194, v195
	ds_bpermute_b32 v244, v253, v114
	ds_bpermute_b32 v245, v253, v115
	ds_bpermute_b32 v246, v253, v116
	ds_bpermute_b32 v247, v253, v117
	v_lshl_add_u64 v[238:239], v[120:121], 0, v[250:251]
	s_waitcnt lgkmcnt(4)
	global_store_dwordx4 v[236:237], v[240:243], off
	s_and_saveexec_b64 s[36:37], s[4:5]
	s_cbranch_execz .LBB0_1220
	v_lshlrev_b64 v[114:115], 6, v[172:173]
	v_lshl_add_u64 v[114:115], s[16:17], 0, v[114:115]
	v_lshl_add_u64 v[114:115], s[34:35], 2, v[114:115]
	s_lshl_b32 s8, s48, 2
	v_lshl_add_u64 v[114:115], v[114:115], 0, s[8:9]
	s_waitcnt lgkmcnt(4)
	v_add_f32_e32 v112, v112, v113
	global_store_dword v[114:115], v112, off

; #define PG8_STAGE(bufoff, gbase, voff) do { _Pragma("unroll") for (int _i = 0; _i < 2; ++_i) \
;         __builtin_amdgcn_global_load_lds((const unsigned*)((const char*)(gbase) + (voff)[_i]), (PG8_LAS unsigned*)(lds + (bufoff) + ldsw + _i * 8192), 16, 0, 0); } while (0)
; #define PG8_LDA(dst, b, h) do { _Pragma("unroll") for (int m = 0; m < 4; ++m) _Pragma("unroll") for (int k = 0; k < 2; ++k) dst[m][k] = *(const PG8_LAS bf16x8*)(lds + PG8_SA(b, h) + aoff + m * 2048 + k * 1024); } while (0)
; #define PG8_LDB(dst, b, h) do { _Pragma("unroll") for (int n = 0; n < 2; ++n) _Pragma("unroll") for (int k = 0; k < 2; ++k) dst[n][k] = *(const PG8_LAS bf16x8*)(lds + PG8_SB(b, h) + boff + n * 2048 + k * 1024); } while (0)
; #define PG8_WAIT_V(n) asm volatile("s_waitcnt vmcnt(" #n ")" ::: "memory")
; #define PG8_WAIT_L(n) asm volatile("s_waitcnt lgkmcnt(" #n ")" ::: "memory")
; #define PG8_BAR __builtin_amdgcn_s_barrier()
; #define PG8_SCHED __builtin_amdgcn_sched_barrier(0)
; template <class Epi, class Sched, bool ALIGN_EPI = false, bool SP2 = false>
; __device__ __forceinline__ void gemm_phase(PG8_LAS unsigned char* lds, const Gemm g, const Sched& S, const Epi& E, const int wv  ) {
;     ...
;         const bool has_next = S.next(ui + 1, nxt);
;         const char* nA = has_next ? (const char*)g.A + (size_t)nxt.pm * tstep : cA; const char* nB = has_next ? (const char*)g.Bt + (size_t)nxt.pn * tstep : cB;
;         for (int t = 0; t < nt; t += 2) {
;             const bool last = (t == nt - 2);
;             const char* a1 = cA + (size_t)(t + 1) * kstep;
;             const char* a2 = last ? nA : cA + (size_t)(t + 2) * kstep; const char* b2 = last ? nB : cB + (size_t)(t + 2) * kstep;
;             const char* a3 = a2 + kstep; const char* b3 = b2 + kstep;
;             if (last && has_next) S.a_ready(nxt);
;             if constexpr (SP2) {
;             PG8_LDB(B0, 0, 0); PG8_LDB(B1, 0, 1); PG8_SCHED; PG8_LDA(At, 0, 0); PG8_STAGE(PG8_SA(1, 1), a1 + hstep, voffA);
;             PG8_WAIT_V(8); PG8_WAIT_L(0); PG8_BAR; PG8_MMA(0, 0, At, B0); PG8_MMA(0, 1, At, B1); PG8_BAR; PG8_SCHED;
;             PG8_LDA(At, 0, 1); PG8_STAGE(PG8_SB(0, 0), b2, voffB); PG8_STAGE(PG8_SB(0, 1), b2 + hstep, voffB); PG8_STAGE(PG8_SA(0, 0), a2, voffA);
;             PG8_WAIT_V(8); PG8_WAIT_L(0); PG8_BAR; PG8_MMA(1, 0, At, B0); PG8_MMA(1, 1, At, B1); PG8_BAR; PG8_SCHED;
.LBB0_1334:
	s_ashr_i32 s29, s28, 31
	s_lshl_b64 s[30:31], s[28:29], 19
	s_add_u32 s30, s21, s30
	s_addc_u32 s31, s33, s31
	s_and_b64 s[34:35], s[4:5], exec
	s_cselect_b32 s7, s31, s1
	s_cselect_b32 s9, s30, s0
	s_ashr_i32 s27, s26, 31
	s_lshl_b64 s[34:35], s[26:27], 19
	s_add_u32 s34, s42, s34
	s_addc_u32 s35, s43, s35
	s_and_b64 s[40:41], s[4:5], exec
	s_cselect_b32 s18, s35, s39
	s_cselect_b32 s25, s34, s38
	s_add_u32 s0, s0, 0x40080
	s_addc_u32 s1, s1, 0
	s_add_u32 s27, s38, 0x100
	s_addc_u32 s29, s39, 0
	s_mov_b32 s56, -2
	s_cmp_eq_u32 s48, 1
	s_cbranch_scc1 .LpeelA_1335
	ds_read_b128 v[144:147], v153
	ds_read_b128 v[158:161], v153 offset:1024
	ds_read_b128 v[162:165], v153 offset:2048
	ds_read_b128 v[166:169], v153 offset:3072
	ds_read_b128 v[170:173], v154
	ds_read_b128 v[174:177], v154 offset:1024
	ds_read_b128 v[178:181], v154 offset:2048
	ds_read_b128 v[182:185], v154 offset:3072
	s_add_u32 s38, s0, 0xfffc0080
	s_addc_u32 s39, s1, -1
	s_cmp_eq_u32 s56, 12
	s_cselect_b32 s41, s7, s39
	s_cselect_b32 s40, s9, s38
	s_cselect_b32 s39, s18, s29
	s_cselect_b32 s38, s25, s27
	ds_read_b128 v[186:189], v155
	ds_read_b128 v[190:193], v155 offset:1024
	ds_read_b128 v[194:197], v155 offset:2048
	ds_read_b128 v[198:201], v155 offset:3072
	ds_read_b128 v[202:205], v155 offset:4096
	ds_read_b128 v[206:209], v155 offset:5120
	ds_read_b128 v[214:217], v155 offset:6144
	ds_read_b128 v[218:221], v155 offset:7168
	s_waitcnt vmcnt(24)
	s_waitcnt lgkmcnt(0)
	s_barrier
	s_setprio 1
	s_waitcnt lgkmcnt(0)
	v_mfma_f32_16x16x32_bf16 v[124:127], v[144:147], v[186:189], 0
	v_mfma_f32_16x16x32_bf16 v[120:123], v[162:165], v[186:189], 0
	v_mfma_f32_16x16x32_bf16 v[108:111], v[144:147], v[194:197], 0
	v_mfma_f32_16x16x32_bf16 v[104:107], v[162:165], v[194:197], 0
	v_mfma_f32_16x16x32_bf16 v[92:95], v[144:147], v[202:205], 0
	v_mfma_f32_16x16x32_bf16 v[88:91], v[162:165], v[202:205], 0
	v_mfma_f32_16x16x32_bf16 v[76:79], v[144:147], v[214:217], 0
	v_mfma_f32_16x16x32_bf16 v[72:75], v[162:165], v[214:217], 0
	v_mfma_f32_16x16x32_bf16 v[124:127], v[158:161], v[190:193], v[124:127]
	v_mfma_f32_16x16x32_bf16 v[120:123], v[166:169], v[190:193], v[120:123]
	v_mfma_f32_16x16x32_bf16 v[108:111], v[158:161], v[198:201], v[108:111]
	v_mfma_f32_16x16x32_bf16 v[104:107], v[166:169], v[198:201], v[104:107]
	v_mfma_f32_16x16x32_bf16 v[92:95], v[158:161], v[206:209], v[92:95]
	v_mfma_f32_16x16x32_bf16 v[88:91], v[166:169], v[206:209], v[88:91]
	v_mfma_f32_16x16x32_bf16 v[76:79], v[158:161], v[218:221], v[76:79]
	v_mfma_f32_16x16x32_bf16 v[72:75], v[166:169], v[218:221], v[72:75]
	s_setprio 0
	s_setprio 1
	v_mfma_f32_16x16x32_bf16 v[116:119], v[170:173], v[186:189], 0
	v_mfma_f32_16x16x32_bf16 v[112:115], v[178:181], v[186:189], 0
	v_mfma_f32_16x16x32_bf16 v[100:103], v[170:173], v[194:197], 0
	v_mfma_f32_16x16x32_bf16 v[96:99], v[178:181], v[194:197], 0
	v_mfma_f32_16x16x32_bf16 v[84:87], v[170:173], v[202:205], 0
	v_mfma_f32_16x16x32_bf16 v[80:83], v[178:181], v[202:205], 0
	v_mfma_f32_16x16x32_bf16 v[68:71], v[170:173], v[214:217], 0
	v_mfma_f32_16x16x32_bf16 v[64:67], v[178:181], v[214:217], 0
	v_mfma_f32_16x16x32_bf16 v[116:119], v[174:177], v[190:193], v[116:119]
	v_mfma_f32_16x16x32_bf16 v[112:115], v[182:185], v[190:193], v[112:115]
	v_mfma_f32_16x16x32_bf16 v[100:103], v[174:177], v[198:201], v[100:103]
	v_mfma_f32_16x16x32_bf16 v[96:99], v[182:185], v[198:201], v[96:99]
	v_mfma_f32_16x16x32_bf16 v[84:87], v[174:177], v[206:209], v[84:87]
	v_mfma_f32_16x16x32_bf16 v[80:83], v[182:185], v[206:209], v[80:83]
	v_mfma_f32_16x16x32_bf16 v[68:71], v[174:177], v[218:221], v[68:71]
	v_mfma_f32_16x16x32_bf16 v[64:67], v[182:185], v[218:221], v[64:67]
	s_setprio 0
	s_barrier
	s_add_i32 s57, s51, s20
	v_lshl_add_u64 v[210:211], s[38:39], 0, v[130:131]
	s_mov_b32 m0, s57
	ds_read_b128 v[186:189], v155 offset:16384
	ds_read_b128 v[190:193], v155 offset:17408
	ds_read_b128 v[194:197], v155 offset:18432
	ds_read_b128 v[198:201], v155 offset:19456
	ds_read_b128 v[202:205], v155 offset:20480
	ds_read_b128 v[206:209], v155 offset:21504
	ds_read_b128 v[214:217], v155 offset:22528
	ds_read_b128 v[218:221], v155 offset:23552
	global_load_lds_dwordx4 v[210:211], off
	s_add_i32 m0, s57, 0x2000
	s_add_u32 s58, s38, 0x40000
	v_lshl_add_u64 v[222:223], s[38:39], 0, v[134:135]
	s_addc_u32 s59, s39, 0
	s_add_i32 s57, s52, s20
	global_load_lds_dwordx4 v[222:223], off
	v_lshl_add_u64 v[224:225], s[58:59], 0, v[130:131]
	s_mov_b32 m0, s57
	v_lshl_add_u64 v[226:227], s[40:41], 0, v[132:133]
	global_load_lds_dwordx4 v[224:225], off
	v_lshl_add_u64 v[224:225], s[58:59], 0, v[134:135]
	s_add_i32 m0, s57, 0x2000
	s_nop 0
	global_load_lds_dwordx4 v[224:225], off
	v_lshl_add_u64 v[224:225], s[40:41], 0, v[128:129]
	s_mov_b32 m0, s44
	s_nop 0
	global_load_lds_dwordx4 v[224:225], off
	s_mov_b32 m0, s45
	s_nop 0
	global_load_lds_dwordx4 v[226:227], off
	s_waitcnt vmcnt(24)
	s_waitcnt lgkmcnt(0)
	s_barrier
; #define PG8_STAGE(bufoff, gbase, voff) do { _Pragma("unroll") for (int _i = 0; _i < 2; ++_i) \
;         __builtin_amdgcn_global_load_lds((const unsigned*)((const char*)(gbase) + (voff)[_i]), (PG8_LAS unsigned*)(lds + (bufoff) + ldsw + _i * 8192), 16, 0, 0); } while (0)
; #define PG8_LDA(dst, b, h) do { _Pragma("unroll") for (int m = 0; m < 4; ++m) _Pragma("unroll") for (int k = 0; k < 2; ++k) dst[m][k] = *(const PG8_LAS bf16x8*)(lds + PG8_SA(b, h) + aoff + m * 2048 + k * 1024); } while (0)
; #define PG8_LDB(dst, b, h) do { _Pragma("unroll") for (int n = 0; n < 2; ++n) _Pragma("unroll") for (int k = 0; k < 2; ++k) dst[n][k] = *(const PG8_LAS bf16x8*)(lds + PG8_SB(b, h) + boff + n * 2048 + k * 1024); } while (0)
; #define PG8_MMA(ai, bj, At, Bt) do { __builtin_amdgcn_s_setprio(1); _Pragma("unroll") for (int m = 0; m < 4; ++m) _Pragma("unroll") for (int n = 0; n < 2; ++n) _Pragma("unroll") for (int k = 0; k < 2; ++k) \
;         acc[ai][bj][m][n] = __builtin_amdgcn_mfma_f32_16x16x32_bf16(Bt[n][k], At[m][k], acc[ai][bj][m][n], 0, 0, 0); __builtin_amdgcn_s_setprio(0); } while (0)
; #define PG8_BAR __builtin_amdgcn_s_barrier()
; template <class Epi, class Sched, bool ALIGN_EPI = false, bool SP2 = false>
; __device__ __forceinline__ void gemm_phase(PG8_LAS unsigned char* lds, const Gemm g, const Sched& S, const Epi& E, const int wv  ) {
;     ...
;             PG8_LDB(B0, 0, 0); PG8_LDB(B1, 0, 1); PG8_SCHED; PG8_LDA(At, 0, 0); PG8_STAGE(PG8_SA(1, 1), a1 + hstep, voffA);
;             PG8_WAIT_V(8); PG8_WAIT_L(0); PG8_BAR; PG8_MMA(0, 0, At, B0); PG8_MMA(0, 1, At, B1); PG8_BAR; PG8_SCHED;
;             PG8_LDA(At, 0, 1); PG8_STAGE(PG8_SB(0, 0), b2, voffB); PG8_STAGE(PG8_SB(0, 1), b2 + hstep, voffB); PG8_STAGE(PG8_SA(0, 0), a2, voffA);
;             PG8_WAIT_V(8); PG8_WAIT_L(0); PG8_BAR; PG8_MMA(1, 0, At, B0); PG8_MMA(1, 1, At, B1); PG8_BAR; PG8_SCHED;
;             PG8_LDB(B0, 1, 0); PG8_LDB(B1, 1, 1); PG8_SCHED; PG8_LDA(At, 1, 0); PG8_STAGE(PG8_SA(0, 1), a2 + hstep, voffA);
;             PG8_WAIT_V(8); PG8_WAIT_L(0); PG8_BAR; PG8_MMA(0, 0, At, B0); PG8_MMA(0, 1, At, B1); PG8_BAR; PG8_SCHED;
;             PG8_LDA(At, 1, 1); PG8_STAGE(PG8_SB(1, 0), b3, voffB); PG8_STAGE(PG8_SB(1, 1), b3 + hstep, voffB); PG8_STAGE(PG8_SA(1, 0), a3, voffA);
;             PG8_WAIT_V(8); PG8_WAIT_L(0); PG8_BAR; PG8_MMA(1, 0, At, B0); PG8_MMA(1, 1, At, B1); PG8_BAR; PG8_SCHED;
	s_setprio 1
	s_waitcnt lgkmcnt(0)
	v_mfma_f32_16x16x32_bf16 v[60:63], v[144:147], v[186:189], 0
	v_mfma_f32_16x16x32_bf16 v[56:59], v[162:165], v[186:189], 0
	v_mfma_f32_16x16x32_bf16 v[44:47], v[144:147], v[194:197], 0
	v_mfma_f32_16x16x32_bf16 v[40:43], v[162:165], v[194:197], 0
	v_mfma_f32_16x16x32_bf16 v[28:31], v[144:147], v[202:205], 0
	v_mfma_f32_16x16x32_bf16 v[24:27], v[162:165], v[202:205], 0
	v_mfma_f32_16x16x32_bf16 v[12:15], v[144:147], v[214:217], 0
	v_mfma_f32_16x16x32_bf16 v[8:11], v[162:165], v[214:217], 0
	v_mfma_f32_16x16x32_bf16 v[60:63], v[158:161], v[190:193], v[60:63]
	v_mfma_f32_16x16x32_bf16 v[56:59], v[166:169], v[190:193], v[56:59]
	v_mfma_f32_16x16x32_bf16 v[44:47], v[158:161], v[198:201], v[44:47]
	v_mfma_f32_16x16x32_bf16 v[40:43], v[166:169], v[198:201], v[40:43]
	v_mfma_f32_16x16x32_bf16 v[28:31], v[158:161], v[206:209], v[28:31]
	v_mfma_f32_16x16x32_bf16 v[24:27], v[166:169], v[206:209], v[24:27]
	v_mfma_f32_16x16x32_bf16 v[12:15], v[158:161], v[218:221], v[12:15]
	v_mfma_f32_16x16x32_bf16 v[8:11], v[166:169], v[218:221], v[8:11]
	s_setprio 0
	s_setprio 1
	v_mfma_f32_16x16x32_bf16 v[52:55], v[170:173], v[186:189], 0
	v_mfma_f32_16x16x32_bf16 v[48:51], v[178:181], v[186:189], 0
	v_mfma_f32_16x16x32_bf16 v[36:39], v[170:173], v[194:197], 0
	v_mfma_f32_16x16x32_bf16 v[32:35], v[178:181], v[194:197], 0
	v_mfma_f32_16x16x32_bf16 v[20:23], v[170:173], v[202:205], 0
	v_mfma_f32_16x16x32_bf16 v[16:19], v[178:181], v[202:205], 0
	v_mfma_f32_16x16x32_bf16 v[4:7], v[170:173], v[214:217], 0
	v_mfma_f32_16x16x32_bf16 v[0:3], v[178:181], v[214:217], 0
	v_mfma_f32_16x16x32_bf16 v[52:55], v[174:177], v[190:193], v[52:55]
	v_mfma_f32_16x16x32_bf16 v[48:51], v[182:185], v[190:193], v[48:51]
	v_mfma_f32_16x16x32_bf16 v[36:39], v[174:177], v[198:201], v[36:39]
	v_mfma_f32_16x16x32_bf16 v[32:35], v[182:185], v[198:201], v[32:35]
	v_mfma_f32_16x16x32_bf16 v[20:23], v[174:177], v[206:209], v[20:23]
	v_mfma_f32_16x16x32_bf16 v[16:19], v[182:185], v[206:209], v[16:19]
	v_mfma_f32_16x16x32_bf16 v[4:7], v[174:177], v[218:221], v[4:7]
	v_mfma_f32_16x16x32_bf16 v[0:3], v[182:185], v[218:221], v[0:3]
	s_setprio 0
	s_barrier
	s_add_i32 s57, 0, 0x18000
	v_add_u32_e32 v148, s57, v150
	s_add_i32 s58, 0, 0x1c000
	ds_read_b128 v[144:147], v148
	ds_read_b128 v[158:161], v148 offset:1024
	ds_read_b128 v[162:165], v148 offset:2048
	ds_read_b128 v[166:169], v148 offset:3072
	v_add_u32_e32 v148, s58, v150
	ds_read_b128 v[170:173], v148
	ds_read_b128 v[174:177], v148 offset:1024
	ds_read_b128 v[178:181], v148 offset:2048
	ds_read_b128 v[182:185], v148 offset:3072
	s_add_u32 s40, s40, 0x40000
	s_addc_u32 s41, s41, 0
	s_mov_b32 m0, s46
	v_lshl_add_u64 v[228:229], s[40:41], 0, v[128:129]
	ds_read_b128 v[186:189], v155 offset:32768
	ds_read_b128 v[190:193], v155 offset:33792
	ds_read_b128 v[194:197], v155 offset:34816
	ds_read_b128 v[198:201], v155 offset:35840
	ds_read_b128 v[202:205], v155 offset:36864
	ds_read_b128 v[206:209], v155 offset:37888
	ds_read_b128 v[214:217], v155 offset:38912
	ds_read_b128 v[218:221], v155 offset:39936
	global_load_lds_dwordx4 v[228:229], off
	v_lshl_add_u64 v[228:229], s[40:41], 0, v[132:133]
	s_mov_b32 m0, s47
	s_nop 0
	global_load_lds_dwordx4 v[228:229], off
	s_waitcnt vmcnt(24)
	s_waitcnt lgkmcnt(0)
	s_barrier
	s_setprio 1
	s_waitcnt lgkmcnt(0)
	v_mfma_f32_16x16x32_bf16 v[124:127], v[144:147], v[186:189], v[124:127]
	v_mfma_f32_16x16x32_bf16 v[120:123], v[162:165], v[186:189], v[120:123]
	v_mfma_f32_16x16x32_bf16 v[108:111], v[144:147], v[194:197], v[108:111]
	v_mfma_f32_16x16x32_bf16 v[104:107], v[162:165], v[194:197], v[104:107]
	v_mfma_f32_16x16x32_bf16 v[92:95], v[144:147], v[202:205], v[92:95]
	v_mfma_f32_16x16x32_bf16 v[88:91], v[162:165], v[202:205], v[88:91]
	v_mfma_f32_16x16x32_bf16 v[76:79], v[144:147], v[214:217], v[76:79]
	v_mfma_f32_16x16x32_bf16 v[72:75], v[162:165], v[214:217], v[72:75]
	v_mfma_f32_16x16x32_bf16 v[124:127], v[158:161], v[190:193], v[124:127]
	v_mfma_f32_16x16x32_bf16 v[120:123], v[166:169], v[190:193], v[120:123]
	v_mfma_f32_16x16x32_bf16 v[108:111], v[158:161], v[198:201], v[108:111]
	v_mfma_f32_16x16x32_bf16 v[104:107], v[166:169], v[198:201], v[104:107]
	v_mfma_f32_16x16x32_bf16 v[92:95], v[158:161], v[206:209], v[92:95]
	v_mfma_f32_16x16x32_bf16 v[88:91], v[166:169], v[206:209], v[88:91]
	v_mfma_f32_16x16x32_bf16 v[76:79], v[158:161], v[218:221], v[76:79]
	v_mfma_f32_16x16x32_bf16 v[72:75], v[166:169], v[218:221], v[72:75]
	s_setprio 0
	s_setprio 1
	v_mfma_f32_16x16x32_bf16 v[116:119], v[170:173], v[186:189], v[116:119]
	v_mfma_f32_16x16x32_bf16 v[112:115], v[178:181], v[186:189], v[112:115]
	v_mfma_f32_16x16x32_bf16 v[100:103], v[170:173], v[194:197], v[100:103]
	v_mfma_f32_16x16x32_bf16 v[96:99], v[178:181], v[194:197], v[96:99]
	v_mfma_f32_16x16x32_bf16 v[84:87], v[170:173], v[202:205], v[84:87]
	v_mfma_f32_16x16x32_bf16 v[80:83], v[178:181], v[202:205], v[80:83]
	v_mfma_f32_16x16x32_bf16 v[68:71], v[170:173], v[214:217], v[68:71]
	v_mfma_f32_16x16x32_bf16 v[64:67], v[178:181], v[214:217], v[64:67]
	v_mfma_f32_16x16x32_bf16 v[116:119], v[174:177], v[190:193], v[116:119]
	v_mfma_f32_16x16x32_bf16 v[112:115], v[182:185], v[190:193], v[112:115]
	v_mfma_f32_16x16x32_bf16 v[100:103], v[174:177], v[198:201], v[100:103]
	v_mfma_f32_16x16x32_bf16 v[96:99], v[182:185], v[198:201], v[96:99]
	v_mfma_f32_16x16x32_bf16 v[84:87], v[174:177], v[206:209], v[84:87]
	v_mfma_f32_16x16x32_bf16 v[80:83], v[182:185], v[206:209], v[80:83]
	v_mfma_f32_16x16x32_bf16 v[68:71], v[174:177], v[218:221], v[68:71]
	v_mfma_f32_16x16x32_bf16 v[64:67], v[182:185], v[218:221], v[64:67]
	s_setprio 0
	s_barrier
; #define PG8_STAGE(bufoff, gbase, voff) do { _Pragma("unroll") for (int _i = 0; _i < 2; ++_i) \
;         __builtin_amdgcn_global_load_lds((const unsigned*)((const char*)(gbase) + (voff)[_i]), (PG8_LAS unsigned*)(lds + (bufoff) + ldsw + _i * 8192), 16, 0, 0); } while (0)
; #define PG8_LDA(dst, b, h) do { _Pragma("unroll") for (int m = 0; m < 4; ++m) _Pragma("unroll") for (int k = 0; k < 2; ++k) dst[m][k] = *(const PG8_LAS bf16x8*)(lds + PG8_SA(b, h) + aoff + m * 2048 + k * 1024); } while (0)
; #define PG8_LDB(dst, b, h) do { _Pragma("unroll") for (int n = 0; n < 2; ++n) _Pragma("unroll") for (int k = 0; k < 2; ++k) dst[n][k] = *(const PG8_LAS bf16x8*)(lds + PG8_SB(b, h) + boff + n * 2048 + k * 1024); } while (0)
; #define PG8_WAIT_V(n) asm volatile("s_waitcnt vmcnt(" #n ")" ::: "memory")
; #define PG8_BAR __builtin_amdgcn_s_barrier()
; template <class Epi, class Sched, bool ALIGN_EPI = false, bool SP2 = false>
; __device__ __forceinline__ void gemm_phase(PG8_LAS unsigned char* lds, const Gemm g, const Sched& S, const Epi& E, const int wv  ) {
;     ...
;         for (int t = 0; t < nt; t += 2) {
;             const bool last = (t == nt - 2);
;             const char* a1 = cA + (size_t)(t + 1) * kstep;
;             const char* a2 = last ? nA : cA + (size_t)(t + 2) * kstep; const char* b2 = last ? nB : cB + (size_t)(t + 2) * kstep;
;     ...
;             PG8_LDB(B0, 0, 0); PG8_LDB(B1, 0, 1); PG8_SCHED; PG8_LDA(At, 0, 0); PG8_STAGE(PG8_SA(1, 1), a1 + hstep, voffA);
;             PG8_WAIT_V(8); PG8_WAIT_L(0); PG8_BAR; PG8_MMA(0, 0, At, B0); PG8_MMA(0, 1, At, B1); PG8_BAR; PG8_SCHED;
;             PG8_LDA(At, 0, 1); PG8_STAGE(PG8_SB(0, 0), b2, voffB); PG8_STAGE(PG8_SB(0, 1), b2 + hstep, voffB); PG8_STAGE(PG8_SA(0, 0), a2, voffA);
;             PG8_WAIT_V(8); PG8_WAIT_L(0); PG8_BAR; PG8_MMA(1, 0, At, B0); PG8_MMA(1, 1, At, B1); PG8_BAR; PG8_SCHED;
;             PG8_LDB(B0, 1, 0); PG8_LDB(B1, 1, 1); PG8_SCHED; PG8_LDA(At, 1, 0); PG8_STAGE(PG8_SA(0, 1), a2 + hstep, voffA);
;             PG8_WAIT_V(8); PG8_WAIT_L(0); PG8_BAR; PG8_MMA(0, 0, At, B0); PG8_MMA(0, 1, At, B1); PG8_BAR; PG8_SCHED;
;             PG8_LDA(At, 1, 1); PG8_STAGE(PG8_SB(1, 0), b3, voffB); PG8_STAGE(PG8_SB(1, 1), b3 + hstep, voffB); PG8_STAGE(PG8_SA(1, 0), a3, voffA);
;             PG8_WAIT_V(8); PG8_WAIT_L(0); PG8_BAR; PG8_MMA(1, 0, At, B0); PG8_MMA(1, 1, At, B1); PG8_BAR; PG8_SCHED;
	s_add_i32 s40, s57, s20
	v_lshl_add_u64 v[210:211], v[210:211], 0, s[16:17]
	s_mov_b32 m0, s40
	ds_read_b128 v[186:189], v155 offset:49152
	ds_read_b128 v[190:193], v155 offset:50176
	ds_read_b128 v[194:197], v155 offset:51200
	ds_read_b128 v[198:201], v155 offset:52224
	ds_read_b128 v[202:205], v155 offset:53248
	ds_read_b128 v[206:209], v155 offset:54272
	ds_read_b128 v[214:217], v155 offset:55296
	ds_read_b128 v[218:221], v155 offset:56320
	global_load_lds_dwordx4 v[210:211], off
	s_add_i32 m0, s40, 0x2000
	s_add_u32 s38, s38, 0x40080
	v_lshl_add_u64 v[210:211], v[222:223], 0, s[16:17]
	s_addc_u32 s39, s39, 0
	s_add_i32 s40, s58, s20
	global_load_lds_dwordx4 v[210:211], off
	v_lshl_add_u64 v[210:211], s[38:39], 0, v[130:131]
	s_mov_b32 m0, s40
	s_nop 0
	global_load_lds_dwordx4 v[210:211], off
	v_lshl_add_u64 v[210:211], s[38:39], 0, v[134:135]
	s_add_i32 m0, s40, 0x2000
	s_nop 0
	global_load_lds_dwordx4 v[210:211], off
	v_lshl_add_u64 v[210:211], v[224:225], 0, s[16:17]
	s_mov_b32 m0, s49
	s_nop 0
	global_load_lds_dwordx4 v[210:211], off
	v_lshl_add_u64 v[210:211], v[226:227], 0, s[16:17]
	s_mov_b32 m0, s50
	s_nop 0
	global_load_lds_dwordx4 v[210:211], off
	s_waitcnt vmcnt(8)
	s_waitcnt lgkmcnt(0)
	s_barrier
	s_setprio 1
	s_waitcnt lgkmcnt(0)
	v_mfma_f32_16x16x32_bf16 v[60:63], v[144:147], v[186:189], v[60:63]
	v_mfma_f32_16x16x32_bf16 v[56:59], v[162:165], v[186:189], v[56:59]
	v_mfma_f32_16x16x32_bf16 v[44:47], v[144:147], v[194:197], v[44:47]
	v_mfma_f32_16x16x32_bf16 v[40:43], v[162:165], v[194:197], v[40:43]
	v_mfma_f32_16x16x32_bf16 v[28:31], v[144:147], v[202:205], v[28:31]
	v_mfma_f32_16x16x32_bf16 v[24:27], v[162:165], v[202:205], v[24:27]
	v_mfma_f32_16x16x32_bf16 v[12:15], v[144:147], v[214:217], v[12:15]
	v_mfma_f32_16x16x32_bf16 v[8:11], v[162:165], v[214:217], v[8:11]
	v_mfma_f32_16x16x32_bf16 v[60:63], v[158:161], v[190:193], v[60:63]
	v_mfma_f32_16x16x32_bf16 v[56:59], v[166:169], v[190:193], v[56:59]
	v_mfma_f32_16x16x32_bf16 v[44:47], v[158:161], v[198:201], v[44:47]
	v_mfma_f32_16x16x32_bf16 v[40:43], v[166:169], v[198:201], v[40:43]
	v_mfma_f32_16x16x32_bf16 v[28:31], v[158:161], v[206:209], v[28:31]
	v_mfma_f32_16x16x32_bf16 v[24:27], v[166:169], v[206:209], v[24:27]
	v_mfma_f32_16x16x32_bf16 v[12:15], v[158:161], v[218:221], v[12:15]
	v_mfma_f32_16x16x32_bf16 v[8:11], v[166:169], v[218:221], v[8:11]
	s_setprio 0
	s_setprio 1
	v_mfma_f32_16x16x32_bf16 v[52:55], v[170:173], v[186:189], v[52:55]
	v_mfma_f32_16x16x32_bf16 v[48:51], v[178:181], v[186:189], v[48:51]
	v_mfma_f32_16x16x32_bf16 v[36:39], v[170:173], v[194:197], v[36:39]
	v_mfma_f32_16x16x32_bf16 v[32:35], v[178:181], v[194:197], v[32:35]
	v_mfma_f32_16x16x32_bf16 v[20:23], v[170:173], v[202:205], v[20:23]
	v_mfma_f32_16x16x32_bf16 v[16:19], v[178:181], v[202:205], v[16:19]
	v_mfma_f32_16x16x32_bf16 v[4:7], v[170:173], v[214:217], v[4:7]
	v_mfma_f32_16x16x32_bf16 v[0:3], v[178:181], v[214:217], v[0:3]
	v_mfma_f32_16x16x32_bf16 v[52:55], v[174:177], v[190:193], v[52:55]
	v_mfma_f32_16x16x32_bf16 v[48:51], v[182:185], v[190:193], v[48:51]
	v_mfma_f32_16x16x32_bf16 v[36:39], v[174:177], v[198:201], v[36:39]
	v_mfma_f32_16x16x32_bf16 v[32:35], v[182:185], v[198:201], v[32:35]
	v_mfma_f32_16x16x32_bf16 v[20:23], v[174:177], v[206:209], v[20:23]
	v_mfma_f32_16x16x32_bf16 v[16:19], v[182:185], v[206:209], v[16:19]
	v_mfma_f32_16x16x32_bf16 v[4:7], v[174:177], v[218:221], v[4:7]
	v_mfma_f32_16x16x32_bf16 v[0:3], v[182:185], v[218:221], v[0:3]
	s_setprio 0
	s_barrier
	s_add_i32 s56, s56, 2
	s_add_u32 s0, s0, 0x100
	s_addc_u32 s1, s1, 0
	s_add_u32 s27, s27, 0x100
	s_addc_u32 s29, s29, 0
	s_cmp_gt_u32 s56, 13
	s_branch .LBB0_1335
.LpeelA_1335:
	ds_read_b128 v[144:147], v153
	ds_read_b128 v[158:161], v153 offset:1024
	ds_read_b128 v[162:165], v153 offset:2048
	ds_read_b128 v[166:169], v153 offset:3072
	ds_read_b128 v[170:173], v154
	ds_read_b128 v[174:177], v154 offset:1024
	ds_read_b128 v[178:181], v154 offset:2048
	ds_read_b128 v[182:185], v154 offset:3072
	s_add_u32 s38, s0, 0xfffc0080
	s_addc_u32 s39, s1, -1
	s_cmp_eq_u32 s56, 12
	s_cselect_b32 s41, s7, s39
	s_cselect_b32 s40, s9, s38
	s_cselect_b32 s39, s18, s29
	s_cselect_b32 s38, s25, s27
	v_lshl_add_u64 v[210:211], s[0:1], 0, v[136:137]
	s_add_i32 m0, s44, 0xc000
	ds_read_b128 v[186:189], v155
	ds_read_b128 v[190:193], v155 offset:1024
	ds_read_b128 v[194:197], v155 offset:2048
	ds_read_b128 v[198:201], v155 offset:3072
	ds_read_b128 v[202:205], v155 offset:4096
	ds_read_b128 v[206:209], v155 offset:5120
	ds_read_b128 v[214:217], v155 offset:6144
	ds_read_b128 v[218:221], v155 offset:7168
	global_load_lds_dwordx4 v[210:211], off
	v_lshl_add_u64 v[210:211], s[0:1], 0, v[138:139]
	s_add_i32 m0, s44, 0xe000
	s_nop 0
	global_load_lds_dwordx4 v[210:211], off
	s_waitcnt vmcnt(8)
	s_waitcnt lgkmcnt(0)
	s_barrier
; #define PG8_STAGE(bufoff, gbase, voff) do { _Pragma("unroll") for (int _i = 0; _i < 2; ++_i) \
;         __builtin_amdgcn_global_load_lds((const unsigned*)((const char*)(gbase) + (voff)[_i]), (PG8_LAS unsigned*)(lds + (bufoff) + ldsw + _i * 8192), 16, 0, 0); } while (0)
; #define PG8_LDA(dst, b, h) do { _Pragma("unroll") for (int m = 0; m < 4; ++m) _Pragma("unroll") for (int k = 0; k < 2; ++k) dst[m][k] = *(const PG8_LAS bf16x8*)(lds + PG8_SA(b, h) + aoff + m * 2048 + k * 1024); } while (0)
; #define PG8_LDB(dst, b, h) do { _Pragma("unroll") for (int n = 0; n < 2; ++n) _Pragma("unroll") for (int k = 0; k < 2; ++k) dst[n][k] = *(const PG8_LAS bf16x8*)(lds + PG8_SB(b, h) + boff + n * 2048 + k * 1024); } while (0)
; #define PG8_MMA(ai, bj, At, Bt) do { __builtin_amdgcn_s_setprio(1); _Pragma("unroll") for (int m = 0; m < 4; ++m) _Pragma("unroll") for (int n = 0; n < 2; ++n) _Pragma("unroll") for (int k = 0; k < 2; ++k) \
;         acc[ai][bj][m][n] = __builtin_amdgcn_mfma_f32_16x16x32_bf16(Bt[n][k], At[m][k], acc[ai][bj][m][n], 0, 0, 0); __builtin_amdgcn_s_setprio(0); } while (0)
; #define PG8_BAR __builtin_amdgcn_s_barrier()
; template <class Epi, class Sched, bool ALIGN_EPI = false, bool SP2 = false>
; __device__ __forceinline__ void gemm_phase(PG8_LAS unsigned char* lds, const Gemm g, const Sched& S, const Epi& E, const int wv  ) {
;     ...
;             PG8_LDB(B0, 0, 0); PG8_LDB(B1, 0, 1); PG8_SCHED; PG8_LDA(At, 0, 0); PG8_STAGE(PG8_SA(1, 1), a1 + hstep, voffA);
;             PG8_WAIT_V(8); PG8_WAIT_L(0); PG8_BAR; PG8_MMA(0, 0, At, B0); PG8_MMA(0, 1, At, B1); PG8_BAR; PG8_SCHED;
;             PG8_LDA(At, 0, 1); PG8_STAGE(PG8_SB(0, 0), b2, voffB); PG8_STAGE(PG8_SB(0, 1), b2 + hstep, voffB); PG8_STAGE(PG8_SA(0, 0), a2, voffA);
;             PG8_WAIT_V(8); PG8_WAIT_L(0); PG8_BAR; PG8_MMA(1, 0, At, B0); PG8_MMA(1, 1, At, B1); PG8_BAR; PG8_SCHED;
;             PG8_LDB(B0, 1, 0); PG8_LDB(B1, 1, 1); PG8_SCHED; PG8_LDA(At, 1, 0); PG8_STAGE(PG8_SA(0, 1), a2 + hstep, voffA);
;             PG8_WAIT_V(8); PG8_WAIT_L(0); PG8_BAR; PG8_MMA(0, 0, At, B0); PG8_MMA(0, 1, At, B1); PG8_BAR; PG8_SCHED;
;             PG8_LDA(At, 1, 1); PG8_STAGE(PG8_SB(1, 0), b3, voffB); PG8_STAGE(PG8_SB(1, 1), b3 + hstep, voffB); PG8_STAGE(PG8_SA(1, 0), a3, voffA);
;             PG8_WAIT_V(8); PG8_WAIT_L(0); PG8_BAR; PG8_MMA(1, 0, At, B0); PG8_MMA(1, 1, At, B1); PG8_BAR; PG8_SCHED;
	s_setprio 1
	s_waitcnt lgkmcnt(0)
	v_mfma_f32_16x16x32_bf16 v[124:127], v[144:147], v[186:189], 0
	v_mfma_f32_16x16x32_bf16 v[120:123], v[162:165], v[186:189], 0
	v_mfma_f32_16x16x32_bf16 v[108:111], v[144:147], v[194:197], 0
	v_mfma_f32_16x16x32_bf16 v[104:107], v[162:165], v[194:197], 0
	v_mfma_f32_16x16x32_bf16 v[92:95], v[144:147], v[202:205], 0
	v_mfma_f32_16x16x32_bf16 v[88:91], v[162:165], v[202:205], 0
	v_mfma_f32_16x16x32_bf16 v[76:79], v[144:147], v[214:217], 0
	v_mfma_f32_16x16x32_bf16 v[72:75], v[162:165], v[214:217], 0
	v_mfma_f32_16x16x32_bf16 v[124:127], v[158:161], v[190:193], v[124:127]
	v_mfma_f32_16x16x32_bf16 v[120:123], v[166:169], v[190:193], v[120:123]
	v_mfma_f32_16x16x32_bf16 v[108:111], v[158:161], v[198:201], v[108:111]
	v_mfma_f32_16x16x32_bf16 v[104:107], v[166:169], v[198:201], v[104:107]
	v_mfma_f32_16x16x32_bf16 v[92:95], v[158:161], v[206:209], v[92:95]
	v_mfma_f32_16x16x32_bf16 v[88:91], v[166:169], v[206:209], v[88:91]
	v_mfma_f32_16x16x32_bf16 v[76:79], v[158:161], v[218:221], v[76:79]
	v_mfma_f32_16x16x32_bf16 v[72:75], v[166:169], v[218:221], v[72:75]
	s_setprio 0
	s_setprio 1
	v_mfma_f32_16x16x32_bf16 v[116:119], v[170:173], v[186:189], 0
	v_mfma_f32_16x16x32_bf16 v[112:115], v[178:181], v[186:189], 0
	v_mfma_f32_16x16x32_bf16 v[100:103], v[170:173], v[194:197], 0
	v_mfma_f32_16x16x32_bf16 v[96:99], v[178:181], v[194:197], 0
	v_mfma_f32_16x16x32_bf16 v[84:87], v[170:173], v[202:205], 0
	v_mfma_f32_16x16x32_bf16 v[80:83], v[178:181], v[202:205], 0
	v_mfma_f32_16x16x32_bf16 v[68:71], v[170:173], v[214:217], 0
	v_mfma_f32_16x16x32_bf16 v[64:67], v[178:181], v[214:217], 0
	v_mfma_f32_16x16x32_bf16 v[116:119], v[174:177], v[190:193], v[116:119]
	v_mfma_f32_16x16x32_bf16 v[112:115], v[182:185], v[190:193], v[112:115]
	v_mfma_f32_16x16x32_bf16 v[100:103], v[174:177], v[198:201], v[100:103]
	v_mfma_f32_16x16x32_bf16 v[96:99], v[182:185], v[198:201], v[96:99]
	v_mfma_f32_16x16x32_bf16 v[84:87], v[174:177], v[206:209], v[84:87]
	v_mfma_f32_16x16x32_bf16 v[80:83], v[182:185], v[206:209], v[80:83]
	v_mfma_f32_16x16x32_bf16 v[68:71], v[174:177], v[218:221], v[68:71]
	v_mfma_f32_16x16x32_bf16 v[64:67], v[182:185], v[218:221], v[64:67]
	s_setprio 0
	s_barrier
	s_add_i32 s57, s51, s20
	v_lshl_add_u64 v[210:211], s[38:39], 0, v[130:131]
	s_mov_b32 m0, s57
	ds_read_b128 v[186:189], v155 offset:16384
	ds_read_b128 v[190:193], v155 offset:17408
	ds_read_b128 v[194:197], v155 offset:18432
	ds_read_b128 v[198:201], v155 offset:19456
	ds_read_b128 v[202:205], v155 offset:20480
	ds_read_b128 v[206:209], v155 offset:21504
	ds_read_b128 v[214:217], v155 offset:22528
	ds_read_b128 v[218:221], v155 offset:23552
	global_load_lds_dwordx4 v[210:211], off
	s_add_i32 m0, s57, 0x2000
	s_add_u32 s58, s38, 0x40000
	v_lshl_add_u64 v[222:223], s[38:39], 0, v[134:135]
	s_addc_u32 s59, s39, 0
	s_add_i32 s57, s52, s20
	global_load_lds_dwordx4 v[222:223], off
	v_lshl_add_u64 v[224:225], s[58:59], 0, v[130:131]
	s_mov_b32 m0, s57
	v_lshl_add_u64 v[226:227], s[40:41], 0, v[132:133]
	global_load_lds_dwordx4 v[224:225], off
	v_lshl_add_u64 v[224:225], s[58:59], 0, v[134:135]
	s_add_i32 m0, s57, 0x2000
	s_nop 0
	global_load_lds_dwordx4 v[224:225], off
	v_lshl_add_u64 v[224:225], s[40:41], 0, v[128:129]
	s_mov_b32 m0, s44
	s_nop 0
	global_load_lds_dwordx4 v[224:225], off
	s_mov_b32 m0, s45
	s_nop 0
	global_load_lds_dwordx4 v[226:227], off
	s_waitcnt vmcnt(8)
	s_waitcnt lgkmcnt(0)
	s_barrier
	s_setprio 1
	s_waitcnt lgkmcnt(0)
	v_mfma_f32_16x16x32_bf16 v[60:63], v[144:147], v[186:189], 0
	v_mfma_f32_16x16x32_bf16 v[56:59], v[162:165], v[186:189], 0
	v_mfma_f32_16x16x32_bf16 v[44:47], v[144:147], v[194:197], 0
	v_mfma_f32_16x16x32_bf16 v[40:43], v[162:165], v[194:197], 0
	v_mfma_f32_16x16x32_bf16 v[28:31], v[144:147], v[202:205], 0
	v_mfma_f32_16x16x32_bf16 v[24:27], v[162:165], v[202:205], 0
	v_mfma_f32_16x16x32_bf16 v[12:15], v[144:147], v[214:217], 0
	v_mfma_f32_16x16x32_bf16 v[8:11], v[162:165], v[214:217], 0
	v_mfma_f32_16x16x32_bf16 v[60:63], v[158:161], v[190:193], v[60:63]
	v_mfma_f32_16x16x32_bf16 v[56:59], v[166:169], v[190:193], v[56:59]
	v_mfma_f32_16x16x32_bf16 v[44:47], v[158:161], v[198:201], v[44:47]
	v_mfma_f32_16x16x32_bf16 v[40:43], v[166:169], v[198:201], v[40:43]
	v_mfma_f32_16x16x32_bf16 v[28:31], v[158:161], v[206:209], v[28:31]
	v_mfma_f32_16x16x32_bf16 v[24:27], v[166:169], v[206:209], v[24:27]
	v_mfma_f32_16x16x32_bf16 v[12:15], v[158:161], v[218:221], v[12:15]
	v_mfma_f32_16x16x32_bf16 v[8:11], v[166:169], v[218:221], v[8:11]
	s_setprio 0
	s_setprio 1
	v_mfma_f32_16x16x32_bf16 v[52:55], v[170:173], v[186:189], 0
	v_mfma_f32_16x16x32_bf16 v[48:51], v[178:181], v[186:189], 0
	v_mfma_f32_16x16x32_bf16 v[36:39], v[170:173], v[194:197], 0
	v_mfma_f32_16x16x32_bf16 v[32:35], v[178:181], v[194:197], 0
	v_mfma_f32_16x16x32_bf16 v[20:23], v[170:173], v[202:205], 0
	v_mfma_f32_16x16x32_bf16 v[16:19], v[178:181], v[202:205], 0
	v_mfma_f32_16x16x32_bf16 v[4:7], v[170:173], v[214:217], 0
	v_mfma_f32_16x16x32_bf16 v[0:3], v[178:181], v[214:217], 0
	v_mfma_f32_16x16x32_bf16 v[52:55], v[174:177], v[190:193], v[52:55]
	v_mfma_f32_16x16x32_bf16 v[48:51], v[182:185], v[190:193], v[48:51]
	v_mfma_f32_16x16x32_bf16 v[36:39], v[174:177], v[198:201], v[36:39]
	v_mfma_f32_16x16x32_bf16 v[32:35], v[182:185], v[198:201], v[32:35]
	v_mfma_f32_16x16x32_bf16 v[20:23], v[174:177], v[206:209], v[20:23]
	v_mfma_f32_16x16x32_bf16 v[16:19], v[182:185], v[206:209], v[16:19]
	v_mfma_f32_16x16x32_bf16 v[4:7], v[174:177], v[218:221], v[4:7]
	v_mfma_f32_16x16x32_bf16 v[0:3], v[182:185], v[218:221], v[0:3]
	s_setprio 0
	s_barrier
; #define PG8_STAGE(bufoff, gbase, voff) do { _Pragma("unroll") for (int _i = 0; _i < 2; ++_i) \
;         __builtin_amdgcn_global_load_lds((const unsigned*)((const char*)(gbase) + (voff)[_i]), (PG8_LAS unsigned*)(lds + (bufoff) + ldsw + _i * 8192), 16, 0, 0); } while (0)
; #define PG8_LDA(dst, b, h) do { _Pragma("unroll") for (int m = 0; m < 4; ++m) _Pragma("unroll") for (int k = 0; k < 2; ++k) dst[m][k] = *(const PG8_LAS bf16x8*)(lds + PG8_SA(b, h) + aoff + m * 2048 + k * 1024); } while (0)
; #define PG8_LDB(dst, b, h) do { _Pragma("unroll") for (int n = 0; n < 2; ++n) _Pragma("unroll") for (int k = 0; k < 2; ++k) dst[n][k] = *(const PG8_LAS bf16x8*)(lds + PG8_SB(b, h) + boff + n * 2048 + k * 1024); } while (0)
; #define PG8_MMA(ai, bj, At, Bt) do { __builtin_amdgcn_s_setprio(1); _Pragma("unroll") for (int m = 0; m < 4; ++m) _Pragma("unroll") for (int n = 0; n < 2; ++n) _Pragma("unroll") for (int k = 0; k < 2; ++k) \
;         acc[ai][bj][m][n] = __builtin_amdgcn_mfma_f32_16x16x32_bf16(Bt[n][k], At[m][k], acc[ai][bj][m][n], 0, 0, 0); __builtin_amdgcn_s_setprio(0); } while (0)
; #define PG8_BAR __builtin_amdgcn_s_barrier()
; template <class Epi, class Sched, bool ALIGN_EPI = false, bool SP2 = false>
; __device__ __forceinline__ void gemm_phase(PG8_LAS unsigned char* lds, const Gemm g, const Sched& S, const Epi& E, const int wv  ) {
;     ...
;             PG8_LDB(B0, 0, 0); PG8_LDB(B1, 0, 1); PG8_SCHED; PG8_LDA(At, 0, 0); PG8_STAGE(PG8_SA(1, 1), a1 + hstep, voffA);
;             PG8_WAIT_V(8); PG8_WAIT_L(0); PG8_BAR; PG8_MMA(0, 0, At, B0); PG8_MMA(0, 1, At, B1); PG8_BAR; PG8_SCHED;
;             PG8_LDA(At, 0, 1); PG8_STAGE(PG8_SB(0, 0), b2, voffB); PG8_STAGE(PG8_SB(0, 1), b2 + hstep, voffB); PG8_STAGE(PG8_SA(0, 0), a2, voffA);
;             PG8_WAIT_V(8); PG8_WAIT_L(0); PG8_BAR; PG8_MMA(1, 0, At, B0); PG8_MMA(1, 1, At, B1); PG8_BAR; PG8_SCHED;
;             PG8_LDB(B0, 1, 0); PG8_LDB(B1, 1, 1); PG8_SCHED; PG8_LDA(At, 1, 0); PG8_STAGE(PG8_SA(0, 1), a2 + hstep, voffA);
;             PG8_WAIT_V(8); PG8_WAIT_L(0); PG8_BAR; PG8_MMA(0, 0, At, B0); PG8_MMA(0, 1, At, B1); PG8_BAR; PG8_SCHED;
;             PG8_LDA(At, 1, 1); PG8_STAGE(PG8_SB(1, 0), b3, voffB); PG8_STAGE(PG8_SB(1, 1), b3 + hstep, voffB); PG8_STAGE(PG8_SA(1, 0), a3, voffA);
;             PG8_WAIT_V(8); PG8_WAIT_L(0); PG8_BAR; PG8_MMA(1, 0, At, B0); PG8_MMA(1, 1, At, B1); PG8_BAR; PG8_SCHED;
	s_add_i32 s57, 0, 0x18000
	v_add_u32_e32 v148, s57, v150
	s_add_i32 s58, 0, 0x1c000
	ds_read_b128 v[144:147], v148
	ds_read_b128 v[158:161], v148 offset:1024
	ds_read_b128 v[162:165], v148 offset:2048
	ds_read_b128 v[166:169], v148 offset:3072
	v_add_u32_e32 v148, s58, v150
	ds_read_b128 v[170:173], v148
	ds_read_b128 v[174:177], v148 offset:1024
	ds_read_b128 v[178:181], v148 offset:2048
	ds_read_b128 v[182:185], v148 offset:3072
	s_add_u32 s40, s40, 0x40000
	s_addc_u32 s41, s41, 0
	s_mov_b32 m0, s46
	v_lshl_add_u64 v[228:229], s[40:41], 0, v[128:129]
	ds_read_b128 v[186:189], v155 offset:32768
	ds_read_b128 v[190:193], v155 offset:33792
	ds_read_b128 v[194:197], v155 offset:34816
	ds_read_b128 v[198:201], v155 offset:35840
	ds_read_b128 v[202:205], v155 offset:36864
	ds_read_b128 v[206:209], v155 offset:37888
	ds_read_b128 v[214:217], v155 offset:38912
	ds_read_b128 v[218:221], v155 offset:39936
	global_load_lds_dwordx4 v[228:229], off
	v_lshl_add_u64 v[228:229], s[40:41], 0, v[132:133]
	s_mov_b32 m0, s47
	s_nop 0
	global_load_lds_dwordx4 v[228:229], off
	s_waitcnt vmcnt(8)
	s_waitcnt lgkmcnt(0)
	s_barrier
	s_setprio 1
	s_waitcnt lgkmcnt(0)
	v_mfma_f32_16x16x32_bf16 v[124:127], v[144:147], v[186:189], v[124:127]
	v_mfma_f32_16x16x32_bf16 v[120:123], v[162:165], v[186:189], v[120:123]
	v_mfma_f32_16x16x32_bf16 v[108:111], v[144:147], v[194:197], v[108:111]
	v_mfma_f32_16x16x32_bf16 v[104:107], v[162:165], v[194:197], v[104:107]
	v_mfma_f32_16x16x32_bf16 v[92:95], v[144:147], v[202:205], v[92:95]
	v_mfma_f32_16x16x32_bf16 v[88:91], v[162:165], v[202:205], v[88:91]
	v_mfma_f32_16x16x32_bf16 v[76:79], v[144:147], v[214:217], v[76:79]
	v_mfma_f32_16x16x32_bf16 v[72:75], v[162:165], v[214:217], v[72:75]
	v_mfma_f32_16x16x32_bf16 v[124:127], v[158:161], v[190:193], v[124:127]
	v_mfma_f32_16x16x32_bf16 v[120:123], v[166:169], v[190:193], v[120:123]
	v_mfma_f32_16x16x32_bf16 v[108:111], v[158:161], v[198:201], v[108:111]
	v_mfma_f32_16x16x32_bf16 v[104:107], v[166:169], v[198:201], v[104:107]
	v_mfma_f32_16x16x32_bf16 v[92:95], v[158:161], v[206:209], v[92:95]
	v_mfma_f32_16x16x32_bf16 v[88:91], v[166:169], v[206:209], v[88:91]
	v_mfma_f32_16x16x32_bf16 v[76:79], v[158:161], v[218:221], v[76:79]
	v_mfma_f32_16x16x32_bf16 v[72:75], v[166:169], v[218:221], v[72:75]
	s_setprio 0
	s_setprio 1
	v_mfma_f32_16x16x32_bf16 v[116:119], v[170:173], v[186:189], v[116:119]
	v_mfma_f32_16x16x32_bf16 v[112:115], v[178:181], v[186:189], v[112:115]
	v_mfma_f32_16x16x32_bf16 v[100:103], v[170:173], v[194:197], v[100:103]
	v_mfma_f32_16x16x32_bf16 v[96:99], v[178:181], v[194:197], v[96:99]
	v_mfma_f32_16x16x32_bf16 v[84:87], v[170:173], v[202:205], v[84:87]
	v_mfma_f32_16x16x32_bf16 v[80:83], v[178:181], v[202:205], v[80:83]
	v_mfma_f32_16x16x32_bf16 v[68:71], v[170:173], v[214:217], v[68:71]
	v_mfma_f32_16x16x32_bf16 v[64:67], v[178:181], v[214:217], v[64:67]
	v_mfma_f32_16x16x32_bf16 v[116:119], v[174:177], v[190:193], v[116:119]
	v_mfma_f32_16x16x32_bf16 v[112:115], v[182:185], v[190:193], v[112:115]
	v_mfma_f32_16x16x32_bf16 v[100:103], v[174:177], v[198:201], v[100:103]
	v_mfma_f32_16x16x32_bf16 v[96:99], v[182:185], v[198:201], v[96:99]
	v_mfma_f32_16x16x32_bf16 v[84:87], v[174:177], v[206:209], v[84:87]
	v_mfma_f32_16x16x32_bf16 v[80:83], v[182:185], v[206:209], v[80:83]
	v_mfma_f32_16x16x32_bf16 v[68:71], v[174:177], v[218:221], v[68:71]
	v_mfma_f32_16x16x32_bf16 v[64:67], v[182:185], v[218:221], v[64:67]
	s_setprio 0
	s_barrier
; #define PG8_STAGE(bufoff, gbase, voff) do { _Pragma("unroll") for (int _i = 0; _i < 2; ++_i) \
;         __builtin_amdgcn_global_load_lds((const unsigned*)((const char*)(gbase) + (voff)[_i]), (PG8_LAS unsigned*)(lds + (bufoff) + ldsw + _i * 8192), 16, 0, 0); } while (0)
; #define PG8_LDA(dst, b, h) do { _Pragma("unroll") for (int m = 0; m < 4; ++m) _Pragma("unroll") for (int k = 0; k < 2; ++k) dst[m][k] = *(const PG8_LAS bf16x8*)(lds + PG8_SA(b, h) + aoff + m * 2048 + k * 1024); } while (0)
; #define PG8_LDB(dst, b, h) do { _Pragma("unroll") for (int n = 0; n < 2; ++n) _Pragma("unroll") for (int k = 0; k < 2; ++k) dst[n][k] = *(const PG8_LAS bf16x8*)(lds + PG8_SB(b, h) + boff + n * 2048 + k * 1024); } while (0)
; #define PG8_MMA(ai, bj, At, Bt) do { __builtin_amdgcn_s_setprio(1); _Pragma("unroll") for (int m = 0; m < 4; ++m) _Pragma("unroll") for (int n = 0; n < 2; ++n) _Pragma("unroll") for (int k = 0; k < 2; ++k) \
;         acc[ai][bj][m][n] = __builtin_amdgcn_mfma_f32_16x16x32_bf16(Bt[n][k], At[m][k], acc[ai][bj][m][n], 0, 0, 0); __builtin_amdgcn_s_setprio(0); } while (0)
; #define PG8_BAR __builtin_amdgcn_s_barrier()
; template <class Epi, class Sched, bool ALIGN_EPI = false, bool SP2 = false>
; __device__ __forceinline__ void gemm_phase(PG8_LAS unsigned char* lds, const Gemm g, const Sched& S, const Epi& E, const int wv  ) {
;     ...
;             PG8_LDB(B0, 0, 0); PG8_LDB(B1, 0, 1); PG8_SCHED; PG8_LDA(At, 0, 0); PG8_STAGE(PG8_SA(1, 1), a1 + hstep, voffA);
;             PG8_WAIT_V(8); PG8_WAIT_L(0); PG8_BAR; PG8_MMA(0, 0, At, B0); PG8_MMA(0, 1, At, B1); PG8_BAR; PG8_SCHED;
;             PG8_LDA(At, 0, 1); PG8_STAGE(PG8_SB(0, 0), b2, voffB); PG8_STAGE(PG8_SB(0, 1), b2 + hstep, voffB); PG8_STAGE(PG8_SA(0, 0), a2, voffA);
;             PG8_WAIT_V(8); PG8_WAIT_L(0); PG8_BAR; PG8_MMA(1, 0, At, B0); PG8_MMA(1, 1, At, B1); PG8_BAR; PG8_SCHED;
;             PG8_LDB(B0, 1, 0); PG8_LDB(B1, 1, 1); PG8_SCHED; PG8_LDA(At, 1, 0); PG8_STAGE(PG8_SA(0, 1), a2 + hstep, voffA);
;             PG8_WAIT_V(8); PG8_WAIT_L(0); PG8_BAR; PG8_MMA(0, 0, At, B0); PG8_MMA(0, 1, At, B1); PG8_BAR; PG8_SCHED;
;             PG8_LDA(At, 1, 1); PG8_STAGE(PG8_SB(1, 0), b3, voffB); PG8_STAGE(PG8_SB(1, 1), b3 + hstep, voffB); PG8_STAGE(PG8_SA(1, 0), a3, voffA);
;             PG8_WAIT_V(8); PG8_WAIT_L(0); PG8_BAR; PG8_MMA(1, 0, At, B0); PG8_MMA(1, 1, At, B1); PG8_BAR; PG8_SCHED;
	s_add_i32 s40, s57, s20
	v_lshl_add_u64 v[210:211], v[210:211], 0, s[16:17]
	s_mov_b32 m0, s40
	ds_read_b128 v[186:189], v155 offset:49152
	ds_read_b128 v[190:193], v155 offset:50176
	ds_read_b128 v[194:197], v155 offset:51200
	ds_read_b128 v[198:201], v155 offset:52224
	ds_read_b128 v[202:205], v155 offset:53248
	ds_read_b128 v[206:209], v155 offset:54272
	ds_read_b128 v[214:217], v155 offset:55296
	ds_read_b128 v[218:221], v155 offset:56320
	global_load_lds_dwordx4 v[210:211], off
	s_add_i32 m0, s40, 0x2000
	s_add_u32 s38, s38, 0x40080
	v_lshl_add_u64 v[210:211], v[222:223], 0, s[16:17]
	s_addc_u32 s39, s39, 0
	s_add_i32 s40, s58, s20
	global_load_lds_dwordx4 v[210:211], off
	v_lshl_add_u64 v[210:211], s[38:39], 0, v[130:131]
	s_mov_b32 m0, s40
	s_nop 0
	global_load_lds_dwordx4 v[210:211], off
	v_lshl_add_u64 v[210:211], s[38:39], 0, v[134:135]
	s_add_i32 m0, s40, 0x2000
	s_nop 0
	global_load_lds_dwordx4 v[210:211], off
	v_lshl_add_u64 v[210:211], v[224:225], 0, s[16:17]
	s_mov_b32 m0, s49
	s_nop 0
	global_load_lds_dwordx4 v[210:211], off
	v_lshl_add_u64 v[210:211], v[226:227], 0, s[16:17]
	s_mov_b32 m0, s50
	s_nop 0
	global_load_lds_dwordx4 v[210:211], off
	s_waitcnt vmcnt(8)
	s_waitcnt lgkmcnt(0)
	s_barrier
	s_setprio 1
	s_waitcnt lgkmcnt(0)
	v_mfma_f32_16x16x32_bf16 v[60:63], v[144:147], v[186:189], v[60:63]
	v_mfma_f32_16x16x32_bf16 v[56:59], v[162:165], v[186:189], v[56:59]
	v_mfma_f32_16x16x32_bf16 v[44:47], v[144:147], v[194:197], v[44:47]
	v_mfma_f32_16x16x32_bf16 v[40:43], v[162:165], v[194:197], v[40:43]
	v_mfma_f32_16x16x32_bf16 v[28:31], v[144:147], v[202:205], v[28:31]
	v_mfma_f32_16x16x32_bf16 v[24:27], v[162:165], v[202:205], v[24:27]
	v_mfma_f32_16x16x32_bf16 v[12:15], v[144:147], v[214:217], v[12:15]
	v_mfma_f32_16x16x32_bf16 v[8:11], v[162:165], v[214:217], v[8:11]
	v_mfma_f32_16x16x32_bf16 v[60:63], v[158:161], v[190:193], v[60:63]
	v_mfma_f32_16x16x32_bf16 v[56:59], v[166:169], v[190:193], v[56:59]
	v_mfma_f32_16x16x32_bf16 v[44:47], v[158:161], v[198:201], v[44:47]
	v_mfma_f32_16x16x32_bf16 v[40:43], v[166:169], v[198:201], v[40:43]
	v_mfma_f32_16x16x32_bf16 v[28:31], v[158:161], v[206:209], v[28:31]
	v_mfma_f32_16x16x32_bf16 v[24:27], v[166:169], v[206:209], v[24:27]
	v_mfma_f32_16x16x32_bf16 v[12:15], v[158:161], v[218:221], v[12:15]
	v_mfma_f32_16x16x32_bf16 v[8:11], v[166:169], v[218:221], v[8:11]
	s_setprio 0
	s_setprio 1
	v_mfma_f32_16x16x32_bf16 v[52:55], v[170:173], v[186:189], v[52:55]
	v_mfma_f32_16x16x32_bf16 v[48:51], v[178:181], v[186:189], v[48:51]
	v_mfma_f32_16x16x32_bf16 v[36:39], v[170:173], v[194:197], v[36:39]
	v_mfma_f32_16x16x32_bf16 v[32:35], v[178:181], v[194:197], v[32:35]
	v_mfma_f32_16x16x32_bf16 v[20:23], v[170:173], v[202:205], v[20:23]
	v_mfma_f32_16x16x32_bf16 v[16:19], v[178:181], v[202:205], v[16:19]
	v_mfma_f32_16x16x32_bf16 v[4:7], v[170:173], v[214:217], v[4:7]
	v_mfma_f32_16x16x32_bf16 v[0:3], v[178:181], v[214:217], v[0:3]
	v_mfma_f32_16x16x32_bf16 v[52:55], v[174:177], v[190:193], v[52:55]
	v_mfma_f32_16x16x32_bf16 v[48:51], v[182:185], v[190:193], v[48:51]
	v_mfma_f32_16x16x32_bf16 v[36:39], v[174:177], v[198:201], v[36:39]
	v_mfma_f32_16x16x32_bf16 v[32:35], v[182:185], v[198:201], v[32:35]
	v_mfma_f32_16x16x32_bf16 v[20:23], v[174:177], v[206:209], v[20:23]
	v_mfma_f32_16x16x32_bf16 v[16:19], v[182:185], v[206:209], v[16:19]
	v_mfma_f32_16x16x32_bf16 v[4:7], v[174:177], v[218:221], v[4:7]
	v_mfma_f32_16x16x32_bf16 v[0:3], v[182:185], v[218:221], v[0:3]
	s_setprio 0
	s_barrier
	s_add_i32 s56, s56, 2
	s_add_u32 s0, s0, 0x100
	s_addc_u32 s1, s1, 0
	s_add_u32 s27, s27, 0x100
	s_addc_u32 s29, s29, 0
	s_cmp_gt_u32 s56, 13

; #define PG8_STAGE(bufoff, gbase, voff) do { _Pragma("unroll") for (int _i = 0; _i < 2; ++_i) \
;         __builtin_amdgcn_global_load_lds((const unsigned*)((const char*)(gbase) + (voff)[_i]), (PG8_LAS unsigned*)(lds + (bufoff) + ldsw + _i * 8192), 16, 0, 0); } while (0)
; #define PG8_LDA(dst, b, h) do { _Pragma("unroll") for (int m = 0; m < 4; ++m) _Pragma("unroll") for (int k = 0; k < 2; ++k) dst[m][k] = *(const PG8_LAS bf16x8*)(lds + PG8_SA(b, h) + aoff + m * 2048 + k * 1024); } while (0)
; #define PG8_LDB(dst, b, h) do { _Pragma("unroll") for (int n = 0; n < 2; ++n) _Pragma("unroll") for (int k = 0; k < 2; ++k) dst[n][k] = *(const PG8_LAS bf16x8*)(lds + PG8_SB(b, h) + boff + n * 2048 + k * 1024); } while (0)
; #define PG8_WAIT_V(n) asm volatile("s_waitcnt vmcnt(" #n ")" ::: "memory")
; #define PG8_WAIT_L(n) asm volatile("s_waitcnt lgkmcnt(" #n ")" ::: "memory")
; #define PG8_BAR __builtin_amdgcn_s_barrier()
; #define PG8_SCHED __builtin_amdgcn_sched_barrier(0)
; template <class Epi, class Sched, bool ALIGN_EPI = false, bool SP2 = false>
; __device__ __forceinline__ void gemm_phase(PG8_LAS unsigned char* lds, const Gemm g, const Sched& S, const Epi& E, const int wv  ) {
;     ...
;         const bool has_next = S.next(ui + 1, nxt);
;         const char* nA = has_next ? (const char*)g.A + (size_t)nxt.pm * tstep : cA; const char* nB = has_next ? (const char*)g.Bt + (size_t)nxt.pn * tstep : cB;
;         for (int t = 0; t < nt; t += 2) {
;             const bool last = (t == nt - 2);
;             const char* a1 = cA + (size_t)(t + 1) * kstep;
;             const char* a2 = last ? nA : cA + (size_t)(t + 2) * kstep; const char* b2 = last ? nB : cB + (size_t)(t + 2) * kstep;
;             const char* a3 = a2 + kstep; const char* b3 = b2 + kstep;
;             if (last && has_next) S.a_ready(nxt);
;             if constexpr (SP2) {
;             PG8_LDB(B0, 0, 0); PG8_LDB(B1, 0, 1); PG8_SCHED; PG8_LDA(At, 0, 0); PG8_STAGE(PG8_SA(1, 1), a1 + hstep, voffA);
;             PG8_WAIT_V(8); PG8_WAIT_L(0); PG8_BAR; PG8_MMA(0, 0, At, B0); PG8_MMA(0, 1, At, B1); PG8_BAR; PG8_SCHED;
;             PG8_LDA(At, 0, 1); PG8_STAGE(PG8_SB(0, 0), b2, voffB); PG8_STAGE(PG8_SB(0, 1), b2 + hstep, voffB); PG8_STAGE(PG8_SA(0, 0), a2, voffA);
;             PG8_WAIT_V(8); PG8_WAIT_L(0); PG8_BAR; PG8_MMA(1, 0, At, B0); PG8_MMA(1, 1, At, B1); PG8_BAR; PG8_SCHED;
.LBB0_1455:
	s_ashr_i32 s27, s26, 31
	s_lshl_b64 s[28:29], s[26:27], 21
	s_add_u32 s28, s2, s28
	s_addc_u32 s29, s3, s29
	s_and_b64 s[30:31], s[6:7], exec
	s_cselect_b32 s27, s29, s37
	s_cselect_b32 s35, s28, s36
	s_ashr_i32 s25, s24, 31
	s_lshl_b64 s[30:31], s[24:25], 21
	s_add_u32 s30, s20, s30
	s_addc_u32 s31, s21, s31
	s_and_b64 s[40:41], s[6:7], exec
	s_cselect_b32 s25, s31, s39
	s_cselect_b32 s54, s30, s38
	s_add_u32 s36, s36, 0x100080
	s_addc_u32 s37, s37, 0
	s_add_u32 s55, s38, 0x100
	s_addc_u32 s56, s39, 0
	s_mov_b32 s57, -2
	s_waitcnt lgkmcnt(0)
	s_cmp_eq_u32 s53, 1
	s_cbranch_scc1 .LpeelA_1456
	ds_read_b128 v[128:131], v191
	ds_read_b128 v[132:135], v191 offset:1024
	ds_read_b128 v[136:139], v191 offset:2048
	ds_read_b128 v[140:143], v191 offset:3072
	ds_read_b128 v[144:147], v192
	ds_read_b128 v[148:151], v192 offset:1024
	ds_read_b128 v[168:171], v192 offset:2048
	ds_read_b128 v[172:175], v192 offset:3072
	s_add_u32 s38, s36, 0xfff00080
	s_addc_u32 s39, s37, -1
	s_cmp_eq_u32 s57, 60
	s_cselect_b32 s41, s27, s39
	s_cselect_b32 s40, s35, s38
	s_cselect_b32 s39, s25, s56
	s_cselect_b32 s38, s54, s55
	ds_read_b128 v[176:179], v193
	ds_read_b128 v[180:183], v193 offset:1024
	ds_read_b128 v[194:197], v193 offset:2048
	ds_read_b128 v[198:201], v193 offset:3072
	ds_read_b128 v[202:205], v193 offset:4096
	ds_read_b128 v[206:209], v193 offset:5120
	ds_read_b128 v[214:217], v193 offset:6144
	ds_read_b128 v[218:221], v193 offset:7168
	s_waitcnt vmcnt(24)
	s_waitcnt lgkmcnt(0)
	s_barrier
	s_setprio 1
	s_waitcnt lgkmcnt(0)
	v_mfma_f32_16x16x32_bf16 v[124:127], v[128:131], v[176:179], 0
	v_mfma_f32_16x16x32_bf16 v[120:123], v[136:139], v[176:179], 0
	v_mfma_f32_16x16x32_bf16 v[108:111], v[128:131], v[194:197], 0
	v_mfma_f32_16x16x32_bf16 v[104:107], v[136:139], v[194:197], 0
	v_mfma_f32_16x16x32_bf16 v[92:95], v[128:131], v[202:205], 0
	v_mfma_f32_16x16x32_bf16 v[88:91], v[136:139], v[202:205], 0
	v_mfma_f32_16x16x32_bf16 v[76:79], v[128:131], v[214:217], 0
	v_mfma_f32_16x16x32_bf16 v[72:75], v[136:139], v[214:217], 0
	v_mfma_f32_16x16x32_bf16 v[124:127], v[132:135], v[180:183], v[124:127]
	v_mfma_f32_16x16x32_bf16 v[120:123], v[140:143], v[180:183], v[120:123]
	v_mfma_f32_16x16x32_bf16 v[108:111], v[132:135], v[198:201], v[108:111]
	v_mfma_f32_16x16x32_bf16 v[104:107], v[140:143], v[198:201], v[104:107]
	v_mfma_f32_16x16x32_bf16 v[92:95], v[132:135], v[206:209], v[92:95]
	v_mfma_f32_16x16x32_bf16 v[88:91], v[140:143], v[206:209], v[88:91]
	v_mfma_f32_16x16x32_bf16 v[76:79], v[132:135], v[218:221], v[76:79]
	v_mfma_f32_16x16x32_bf16 v[72:75], v[140:143], v[218:221], v[72:75]
	s_setprio 0
	s_setprio 1
	v_mfma_f32_16x16x32_bf16 v[116:119], v[144:147], v[176:179], 0
	v_mfma_f32_16x16x32_bf16 v[112:115], v[168:171], v[176:179], 0
	v_mfma_f32_16x16x32_bf16 v[100:103], v[144:147], v[194:197], 0
	v_mfma_f32_16x16x32_bf16 v[96:99], v[168:171], v[194:197], 0
	v_mfma_f32_16x16x32_bf16 v[84:87], v[144:147], v[202:205], 0
	v_mfma_f32_16x16x32_bf16 v[80:83], v[168:171], v[202:205], 0
	v_mfma_f32_16x16x32_bf16 v[68:71], v[144:147], v[214:217], 0
	v_mfma_f32_16x16x32_bf16 v[64:67], v[168:171], v[214:217], 0
	v_mfma_f32_16x16x32_bf16 v[116:119], v[148:151], v[180:183], v[116:119]
	v_mfma_f32_16x16x32_bf16 v[112:115], v[172:175], v[180:183], v[112:115]
	v_mfma_f32_16x16x32_bf16 v[100:103], v[148:151], v[198:201], v[100:103]
	v_mfma_f32_16x16x32_bf16 v[96:99], v[172:175], v[198:201], v[96:99]
	v_mfma_f32_16x16x32_bf16 v[84:87], v[148:151], v[206:209], v[84:87]
	v_mfma_f32_16x16x32_bf16 v[80:83], v[172:175], v[206:209], v[80:83]
	v_mfma_f32_16x16x32_bf16 v[68:71], v[148:151], v[218:221], v[68:71]
	v_mfma_f32_16x16x32_bf16 v[64:67], v[172:175], v[218:221], v[64:67]
	s_setprio 0
	s_barrier
	s_add_i32 s58, s51, s33
	v_lshl_add_u64 v[184:185], s[38:39], 0, v[154:155]
	s_mov_b32 m0, s58
	ds_read_b128 v[176:179], v193 offset:16384
	ds_read_b128 v[180:183], v193 offset:17408
	ds_read_b128 v[194:197], v193 offset:18432
	ds_read_b128 v[198:201], v193 offset:19456
	ds_read_b128 v[202:205], v193 offset:20480
	ds_read_b128 v[206:209], v193 offset:21504
	ds_read_b128 v[214:217], v193 offset:22528
	ds_read_b128 v[218:221], v193 offset:23552
	global_load_lds_dwordx4 v[184:185], off
	s_add_i32 m0, s58, 0x2000
	s_add_u32 s58, s38, 0x100000
	v_lshl_add_u64 v[210:211], s[38:39], 0, v[158:159]
	s_addc_u32 s59, s39, 0
	s_add_i32 s60, s52, s33
	global_load_lds_dwordx4 v[210:211], off
	v_lshl_add_u64 v[222:223], s[58:59], 0, v[154:155]
	s_mov_b32 m0, s60
	v_lshl_add_u64 v[224:225], s[40:41], 0, v[156:157]
	global_load_lds_dwordx4 v[222:223], off
	v_lshl_add_u64 v[222:223], s[58:59], 0, v[158:159]
	s_add_i32 m0, s60, 0x2000
	s_nop 0
	global_load_lds_dwordx4 v[222:223], off
	v_lshl_add_u64 v[222:223], s[40:41], 0, v[152:153]
	s_mov_b32 m0, s42
	s_nop 0
	global_load_lds_dwordx4 v[222:223], off
	s_mov_b32 m0, s43
	s_nop 0
	global_load_lds_dwordx4 v[224:225], off
	s_waitcnt vmcnt(24)
	s_waitcnt lgkmcnt(0)
	s_barrier
; #define PG8_STAGE(bufoff, gbase, voff) do { _Pragma("unroll") for (int _i = 0; _i < 2; ++_i) \
;         __builtin_amdgcn_global_load_lds((const unsigned*)((const char*)(gbase) + (voff)[_i]), (PG8_LAS unsigned*)(lds + (bufoff) + ldsw + _i * 8192), 16, 0, 0); } while (0)
; #define PG8_LDA(dst, b, h) do { _Pragma("unroll") for (int m = 0; m < 4; ++m) _Pragma("unroll") for (int k = 0; k < 2; ++k) dst[m][k] = *(const PG8_LAS bf16x8*)(lds + PG8_SA(b, h) + aoff + m * 2048 + k * 1024); } while (0)
; #define PG8_LDB(dst, b, h) do { _Pragma("unroll") for (int n = 0; n < 2; ++n) _Pragma("unroll") for (int k = 0; k < 2; ++k) dst[n][k] = *(const PG8_LAS bf16x8*)(lds + PG8_SB(b, h) + boff + n * 2048 + k * 1024); } while (0)
; #define PG8_MMA(ai, bj, At, Bt) do { __builtin_amdgcn_s_setprio(1); _Pragma("unroll") for (int m = 0; m < 4; ++m) _Pragma("unroll") for (int n = 0; n < 2; ++n) _Pragma("unroll") for (int k = 0; k < 2; ++k) \
;         acc[ai][bj][m][n] = __builtin_amdgcn_mfma_f32_16x16x32_bf16(Bt[n][k], At[m][k], acc[ai][bj][m][n], 0, 0, 0); __builtin_amdgcn_s_setprio(0); } while (0)
; #define PG8_WAIT_V(n) asm volatile("s_waitcnt vmcnt(" #n ")" ::: "memory")
; #define PG8_WAIT_L(n) asm volatile("s_waitcnt lgkmcnt(" #n ")" ::: "memory")
; #define PG8_BAR __builtin_amdgcn_s_barrier()
; #define PG8_SCHED __builtin_amdgcn_sched_barrier(0)
; template <class Epi, class Sched, bool ALIGN_EPI = false, bool SP2 = false>
; __device__ __forceinline__ void gemm_phase(PG8_LAS unsigned char* lds, const Gemm g, const Sched& S, const Epi& E, const int wv  ) {
;     ...
;             PG8_WAIT_V(8); PG8_WAIT_L(0); PG8_BAR; PG8_MMA(1, 0, At, B0); PG8_MMA(1, 1, At, B1); PG8_BAR; PG8_SCHED;
;             PG8_LDB(B0, 1, 0); PG8_LDB(B1, 1, 1); PG8_SCHED; PG8_LDA(At, 1, 0); PG8_STAGE(PG8_SA(0, 1), a2 + hstep, voffA);
;             PG8_WAIT_V(8); PG8_WAIT_L(0); PG8_BAR; PG8_MMA(0, 0, At, B0); PG8_MMA(0, 1, At, B1); PG8_BAR; PG8_SCHED;
	s_setprio 1
	s_waitcnt lgkmcnt(0)
	v_mfma_f32_16x16x32_bf16 v[60:63], v[128:131], v[176:179], 0
	v_mfma_f32_16x16x32_bf16 v[56:59], v[136:139], v[176:179], 0
	v_mfma_f32_16x16x32_bf16 v[44:47], v[128:131], v[194:197], 0
	v_mfma_f32_16x16x32_bf16 v[40:43], v[136:139], v[194:197], 0
	v_mfma_f32_16x16x32_bf16 v[28:31], v[128:131], v[202:205], 0
	v_mfma_f32_16x16x32_bf16 v[24:27], v[136:139], v[202:205], 0
	v_mfma_f32_16x16x32_bf16 v[12:15], v[128:131], v[214:217], 0
	v_mfma_f32_16x16x32_bf16 v[8:11], v[136:139], v[214:217], 0
	v_mfma_f32_16x16x32_bf16 v[60:63], v[132:135], v[180:183], v[60:63]
	v_mfma_f32_16x16x32_bf16 v[56:59], v[140:143], v[180:183], v[56:59]
	v_mfma_f32_16x16x32_bf16 v[44:47], v[132:135], v[198:201], v[44:47]
	v_mfma_f32_16x16x32_bf16 v[40:43], v[140:143], v[198:201], v[40:43]
	v_mfma_f32_16x16x32_bf16 v[28:31], v[132:135], v[206:209], v[28:31]
	v_mfma_f32_16x16x32_bf16 v[24:27], v[140:143], v[206:209], v[24:27]
	v_mfma_f32_16x16x32_bf16 v[12:15], v[132:135], v[218:221], v[12:15]
	v_mfma_f32_16x16x32_bf16 v[8:11], v[140:143], v[218:221], v[8:11]
	s_setprio 0
	s_setprio 1
	v_mfma_f32_16x16x32_bf16 v[52:55], v[144:147], v[176:179], 0
	v_mfma_f32_16x16x32_bf16 v[48:51], v[168:171], v[176:179], 0
	v_mfma_f32_16x16x32_bf16 v[36:39], v[144:147], v[194:197], 0
	v_mfma_f32_16x16x32_bf16 v[32:35], v[168:171], v[194:197], 0
	v_mfma_f32_16x16x32_bf16 v[20:23], v[144:147], v[202:205], 0
	v_mfma_f32_16x16x32_bf16 v[16:19], v[168:171], v[202:205], 0
	v_mfma_f32_16x16x32_bf16 v[4:7], v[144:147], v[214:217], 0
	v_mfma_f32_16x16x32_bf16 v[0:3], v[168:171], v[214:217], 0
	v_mfma_f32_16x16x32_bf16 v[52:55], v[148:151], v[180:183], v[52:55]
	v_mfma_f32_16x16x32_bf16 v[48:51], v[172:175], v[180:183], v[48:51]
	v_mfma_f32_16x16x32_bf16 v[36:39], v[148:151], v[198:201], v[36:39]
	v_mfma_f32_16x16x32_bf16 v[32:35], v[172:175], v[198:201], v[32:35]
	v_mfma_f32_16x16x32_bf16 v[20:23], v[148:151], v[206:209], v[20:23]
	v_mfma_f32_16x16x32_bf16 v[16:19], v[172:175], v[206:209], v[16:19]
	v_mfma_f32_16x16x32_bf16 v[4:7], v[148:151], v[218:221], v[4:7]
	v_mfma_f32_16x16x32_bf16 v[0:3], v[172:175], v[218:221], v[0:3]
	s_setprio 0
	s_barrier
	s_add_i32 s58, 0, 0x18000
	s_add_i32 s59, 0, 0x1c000
	v_add_u32_e32 v140, s58, v189
	v_add_u32_e32 v172, s59, v189
	ds_read_b128 v[128:131], v140
	ds_read_b128 v[132:135], v140 offset:1024
	ds_read_b128 v[136:139], v140 offset:2048
	ds_read_b128 v[140:143], v140 offset:3072
	ds_read_b128 v[144:147], v172
	ds_read_b128 v[148:151], v172 offset:1024
	ds_read_b128 v[168:171], v172 offset:2048
	ds_read_b128 v[172:175], v172 offset:3072
	s_add_u32 s40, s40, 0x100000
	s_addc_u32 s41, s41, 0
	s_mov_b32 m0, s44
	v_lshl_add_u64 v[226:227], s[40:41], 0, v[152:153]
	ds_read_b128 v[176:179], v193 offset:32768
	ds_read_b128 v[180:183], v193 offset:33792
	ds_read_b128 v[194:197], v193 offset:34816
	ds_read_b128 v[198:201], v193 offset:35840
	ds_read_b128 v[202:205], v193 offset:36864
	ds_read_b128 v[206:209], v193 offset:37888
	ds_read_b128 v[214:217], v193 offset:38912
	ds_read_b128 v[218:221], v193 offset:39936
	global_load_lds_dwordx4 v[226:227], off
	v_lshl_add_u64 v[226:227], s[40:41], 0, v[156:157]
	s_mov_b32 m0, s45
	s_nop 0
	global_load_lds_dwordx4 v[226:227], off
	s_waitcnt vmcnt(24)
	s_waitcnt lgkmcnt(0)
	s_barrier
	s_setprio 1
	s_waitcnt lgkmcnt(0)
	v_mfma_f32_16x16x32_bf16 v[124:127], v[128:131], v[176:179], v[124:127]
	v_mfma_f32_16x16x32_bf16 v[120:123], v[136:139], v[176:179], v[120:123]
	v_mfma_f32_16x16x32_bf16 v[108:111], v[128:131], v[194:197], v[108:111]
	v_mfma_f32_16x16x32_bf16 v[104:107], v[136:139], v[194:197], v[104:107]
	v_mfma_f32_16x16x32_bf16 v[92:95], v[128:131], v[202:205], v[92:95]
	v_mfma_f32_16x16x32_bf16 v[88:91], v[136:139], v[202:205], v[88:91]
	v_mfma_f32_16x16x32_bf16 v[76:79], v[128:131], v[214:217], v[76:79]
	v_mfma_f32_16x16x32_bf16 v[72:75], v[136:139], v[214:217], v[72:75]
	v_mfma_f32_16x16x32_bf16 v[124:127], v[132:135], v[180:183], v[124:127]
	v_mfma_f32_16x16x32_bf16 v[120:123], v[140:143], v[180:183], v[120:123]
	v_mfma_f32_16x16x32_bf16 v[108:111], v[132:135], v[198:201], v[108:111]
	v_mfma_f32_16x16x32_bf16 v[104:107], v[140:143], v[198:201], v[104:107]
	v_mfma_f32_16x16x32_bf16 v[92:95], v[132:135], v[206:209], v[92:95]
	v_mfma_f32_16x16x32_bf16 v[88:91], v[140:143], v[206:209], v[88:91]
	v_mfma_f32_16x16x32_bf16 v[76:79], v[132:135], v[218:221], v[76:79]
	v_mfma_f32_16x16x32_bf16 v[72:75], v[140:143], v[218:221], v[72:75]
	s_setprio 0
	s_setprio 1
	v_mfma_f32_16x16x32_bf16 v[116:119], v[144:147], v[176:179], v[116:119]
	v_mfma_f32_16x16x32_bf16 v[112:115], v[168:171], v[176:179], v[112:115]
	v_mfma_f32_16x16x32_bf16 v[100:103], v[144:147], v[194:197], v[100:103]
	v_mfma_f32_16x16x32_bf16 v[96:99], v[168:171], v[194:197], v[96:99]
	v_mfma_f32_16x16x32_bf16 v[84:87], v[144:147], v[202:205], v[84:87]
	v_mfma_f32_16x16x32_bf16 v[80:83], v[168:171], v[202:205], v[80:83]
	v_mfma_f32_16x16x32_bf16 v[68:71], v[144:147], v[214:217], v[68:71]
	v_mfma_f32_16x16x32_bf16 v[64:67], v[168:171], v[214:217], v[64:67]
	v_mfma_f32_16x16x32_bf16 v[116:119], v[148:151], v[180:183], v[116:119]
	v_mfma_f32_16x16x32_bf16 v[112:115], v[172:175], v[180:183], v[112:115]
	v_mfma_f32_16x16x32_bf16 v[100:103], v[148:151], v[198:201], v[100:103]
	v_mfma_f32_16x16x32_bf16 v[96:99], v[172:175], v[198:201], v[96:99]
	v_mfma_f32_16x16x32_bf16 v[84:87], v[148:151], v[206:209], v[84:87]
	v_mfma_f32_16x16x32_bf16 v[80:83], v[172:175], v[206:209], v[80:83]
	v_mfma_f32_16x16x32_bf16 v[68:71], v[148:151], v[218:221], v[68:71]
	v_mfma_f32_16x16x32_bf16 v[64:67], v[172:175], v[218:221], v[64:67]
	s_setprio 0
	s_barrier
; #define PG8_STAGE(bufoff, gbase, voff) do { _Pragma("unroll") for (int _i = 0; _i < 2; ++_i) \
;         __builtin_amdgcn_global_load_lds((const unsigned*)((const char*)(gbase) + (voff)[_i]), (PG8_LAS unsigned*)(lds + (bufoff) + ldsw + _i * 8192), 16, 0, 0); } while (0)
; #define PG8_LDA(dst, b, h) do { _Pragma("unroll") for (int m = 0; m < 4; ++m) _Pragma("unroll") for (int k = 0; k < 2; ++k) dst[m][k] = *(const PG8_LAS bf16x8*)(lds + PG8_SA(b, h) + aoff + m * 2048 + k * 1024); } while (0)
; #define PG8_LDB(dst, b, h) do { _Pragma("unroll") for (int n = 0; n < 2; ++n) _Pragma("unroll") for (int k = 0; k < 2; ++k) dst[n][k] = *(const PG8_LAS bf16x8*)(lds + PG8_SB(b, h) + boff + n * 2048 + k * 1024); } while (0)
; #define PG8_MMA(ai, bj, At, Bt) do { __builtin_amdgcn_s_setprio(1); _Pragma("unroll") for (int m = 0; m < 4; ++m) _Pragma("unroll") for (int n = 0; n < 2; ++n) _Pragma("unroll") for (int k = 0; k < 2; ++k) \
;         acc[ai][bj][m][n] = __builtin_amdgcn_mfma_f32_16x16x32_bf16(Bt[n][k], At[m][k], acc[ai][bj][m][n], 0, 0, 0); __builtin_amdgcn_s_setprio(0); } while (0)
; #define PG8_WAIT_V(n) asm volatile("s_waitcnt vmcnt(" #n ")" ::: "memory")
; #define PG8_WAIT_L(n) asm volatile("s_waitcnt lgkmcnt(" #n ")" ::: "memory")
; #define PG8_BAR __builtin_amdgcn_s_barrier()
; #define PG8_SCHED __builtin_amdgcn_sched_barrier(0)
; template <class Epi, class Sched, bool ALIGN_EPI = false, bool SP2 = false>
; __device__ __forceinline__ void gemm_phase(PG8_LAS unsigned char* lds, const Gemm g, const Sched& S, const Epi& E, const int wv  ) {
;     ...
;             PG8_LDB(B0, 0, 0); PG8_LDB(B1, 0, 1); PG8_SCHED; PG8_LDA(At, 0, 0); PG8_STAGE(PG8_SA(1, 1), a1 + hstep, voffA);
;             PG8_WAIT_V(8); PG8_WAIT_L(0); PG8_BAR; PG8_MMA(0, 0, At, B0); PG8_MMA(0, 1, At, B1); PG8_BAR; PG8_SCHED;
;             PG8_LDA(At, 0, 1); PG8_STAGE(PG8_SB(0, 0), b2, voffB); PG8_STAGE(PG8_SB(0, 1), b2 + hstep, voffB); PG8_STAGE(PG8_SA(0, 0), a2, voffA);
;     ...
;             PG8_LDA(At, 1, 1); PG8_STAGE(PG8_SB(1, 0), b3, voffB); PG8_STAGE(PG8_SB(1, 1), b3 + hstep, voffB); PG8_STAGE(PG8_SA(1, 0), a3, voffA);
;             PG8_WAIT_V(8); PG8_WAIT_L(0); PG8_BAR; PG8_MMA(1, 0, At, B0); PG8_MMA(1, 1, At, B1); PG8_BAR; PG8_SCHED;
	s_add_i32 s40, s58, s33
	v_lshl_add_u64 v[184:185], v[184:185], 0, s[18:19]
	s_mov_b32 m0, s40
	ds_read_b128 v[176:179], v193 offset:49152
	ds_read_b128 v[180:183], v193 offset:50176
	ds_read_b128 v[194:197], v193 offset:51200
	ds_read_b128 v[198:201], v193 offset:52224
	ds_read_b128 v[202:205], v193 offset:53248
	ds_read_b128 v[206:209], v193 offset:54272
	ds_read_b128 v[214:217], v193 offset:55296
	ds_read_b128 v[218:221], v193 offset:56320
	global_load_lds_dwordx4 v[184:185], off
	s_add_i32 m0, s40, 0x2000
	s_add_u32 s38, s38, 0x100080
	v_lshl_add_u64 v[184:185], v[210:211], 0, s[18:19]
	s_addc_u32 s39, s39, 0
	s_add_i32 s40, s59, s33
	global_load_lds_dwordx4 v[184:185], off
	v_lshl_add_u64 v[184:185], s[38:39], 0, v[154:155]
	s_mov_b32 m0, s40
	s_nop 0
	global_load_lds_dwordx4 v[184:185], off
	v_lshl_add_u64 v[184:185], s[38:39], 0, v[158:159]
	s_add_i32 m0, s40, 0x2000
	s_nop 0
	global_load_lds_dwordx4 v[184:185], off
	v_lshl_add_u64 v[184:185], v[222:223], 0, s[18:19]
	s_mov_b32 m0, s49
	s_nop 0
	global_load_lds_dwordx4 v[184:185], off
	v_lshl_add_u64 v[184:185], v[224:225], 0, s[18:19]
	s_mov_b32 m0, s50
	s_nop 0
	global_load_lds_dwordx4 v[184:185], off
	s_waitcnt vmcnt(8)
	s_waitcnt lgkmcnt(0)
	s_barrier
	s_setprio 1
	s_waitcnt lgkmcnt(0)
	v_mfma_f32_16x16x32_bf16 v[60:63], v[128:131], v[176:179], v[60:63]
	v_mfma_f32_16x16x32_bf16 v[56:59], v[136:139], v[176:179], v[56:59]
	v_mfma_f32_16x16x32_bf16 v[44:47], v[128:131], v[194:197], v[44:47]
	v_mfma_f32_16x16x32_bf16 v[40:43], v[136:139], v[194:197], v[40:43]
	v_mfma_f32_16x16x32_bf16 v[28:31], v[128:131], v[202:205], v[28:31]
	v_mfma_f32_16x16x32_bf16 v[24:27], v[136:139], v[202:205], v[24:27]
	v_mfma_f32_16x16x32_bf16 v[12:15], v[128:131], v[214:217], v[12:15]
	v_mfma_f32_16x16x32_bf16 v[8:11], v[136:139], v[214:217], v[8:11]
	v_mfma_f32_16x16x32_bf16 v[60:63], v[132:135], v[180:183], v[60:63]
	v_mfma_f32_16x16x32_bf16 v[56:59], v[140:143], v[180:183], v[56:59]
	v_mfma_f32_16x16x32_bf16 v[44:47], v[132:135], v[198:201], v[44:47]
	v_mfma_f32_16x16x32_bf16 v[40:43], v[140:143], v[198:201], v[40:43]
	v_mfma_f32_16x16x32_bf16 v[28:31], v[132:135], v[206:209], v[28:31]
	v_mfma_f32_16x16x32_bf16 v[24:27], v[140:143], v[206:209], v[24:27]
	v_mfma_f32_16x16x32_bf16 v[12:15], v[132:135], v[218:221], v[12:15]
	v_mfma_f32_16x16x32_bf16 v[8:11], v[140:143], v[218:221], v[8:11]
	s_setprio 0
	s_setprio 1
	v_mfma_f32_16x16x32_bf16 v[52:55], v[144:147], v[176:179], v[52:55]
	v_mfma_f32_16x16x32_bf16 v[48:51], v[168:171], v[176:179], v[48:51]
	v_mfma_f32_16x16x32_bf16 v[36:39], v[144:147], v[194:197], v[36:39]
	v_mfma_f32_16x16x32_bf16 v[32:35], v[168:171], v[194:197], v[32:35]
	v_mfma_f32_16x16x32_bf16 v[20:23], v[144:147], v[202:205], v[20:23]
	v_mfma_f32_16x16x32_bf16 v[16:19], v[168:171], v[202:205], v[16:19]
	v_mfma_f32_16x16x32_bf16 v[4:7], v[144:147], v[214:217], v[4:7]
	v_mfma_f32_16x16x32_bf16 v[0:3], v[168:171], v[214:217], v[0:3]
	v_mfma_f32_16x16x32_bf16 v[52:55], v[148:151], v[180:183], v[52:55]
	v_mfma_f32_16x16x32_bf16 v[48:51], v[172:175], v[180:183], v[48:51]
	v_mfma_f32_16x16x32_bf16 v[36:39], v[148:151], v[198:201], v[36:39]
	v_mfma_f32_16x16x32_bf16 v[32:35], v[172:175], v[198:201], v[32:35]
	v_mfma_f32_16x16x32_bf16 v[20:23], v[148:151], v[206:209], v[20:23]
	v_mfma_f32_16x16x32_bf16 v[16:19], v[172:175], v[206:209], v[16:19]
	v_mfma_f32_16x16x32_bf16 v[4:7], v[148:151], v[218:221], v[4:7]
	v_mfma_f32_16x16x32_bf16 v[0:3], v[172:175], v[218:221], v[0:3]
	s_setprio 0
	s_barrier
	s_add_i32 s57, s57, 2
	s_add_u32 s36, s36, 0x100
	s_addc_u32 s37, s37, 0
	s_add_u32 s55, s55, 0x100
	s_addc_u32 s56, s56, 0
	s_cmp_gt_u32 s57, 61
	s_branch .LBB0_1456
.LpeelA_1456:
	ds_read_b128 v[128:131], v191
	ds_read_b128 v[132:135], v191 offset:1024
	ds_read_b128 v[136:139], v191 offset:2048
	ds_read_b128 v[140:143], v191 offset:3072
	ds_read_b128 v[144:147], v192
	ds_read_b128 v[148:151], v192 offset:1024
	ds_read_b128 v[168:171], v192 offset:2048
	ds_read_b128 v[172:175], v192 offset:3072
	s_add_u32 s38, s36, 0xfff00080
	s_addc_u32 s39, s37, -1
	s_cmp_eq_u32 s57, 60
	s_cselect_b32 s41, s27, s39
	s_cselect_b32 s40, s35, s38
	s_cselect_b32 s39, s25, s56
	s_cselect_b32 s38, s54, s55
	v_lshl_add_u64 v[184:185], s[36:37], 0, v[160:161]
	s_add_i32 m0, s42, 0xc000
	ds_read_b128 v[176:179], v193
	ds_read_b128 v[180:183], v193 offset:1024
	ds_read_b128 v[194:197], v193 offset:2048
	ds_read_b128 v[198:201], v193 offset:3072
	ds_read_b128 v[202:205], v193 offset:4096
	ds_read_b128 v[206:209], v193 offset:5120
	ds_read_b128 v[214:217], v193 offset:6144
	ds_read_b128 v[218:221], v193 offset:7168
	global_load_lds_dwordx4 v[184:185], off
	v_lshl_add_u64 v[184:185], s[36:37], 0, v[162:163]
	s_add_i32 m0, s42, 0xe000
	s_nop 0
	global_load_lds_dwordx4 v[184:185], off
	s_waitcnt vmcnt(8)
	s_waitcnt lgkmcnt(0)
	s_barrier
; #define PG8_STAGE(bufoff, gbase, voff) do { _Pragma("unroll") for (int _i = 0; _i < 2; ++_i) \
;         __builtin_amdgcn_global_load_lds((const unsigned*)((const char*)(gbase) + (voff)[_i]), (PG8_LAS unsigned*)(lds + (bufoff) + ldsw + _i * 8192), 16, 0, 0); } while (0)
; #define PG8_LDA(dst, b, h) do { _Pragma("unroll") for (int m = 0; m < 4; ++m) _Pragma("unroll") for (int k = 0; k < 2; ++k) dst[m][k] = *(const PG8_LAS bf16x8*)(lds + PG8_SA(b, h) + aoff + m * 2048 + k * 1024); } while (0)
; #define PG8_MMA(ai, bj, At, Bt) do { __builtin_amdgcn_s_setprio(1); _Pragma("unroll") for (int m = 0; m < 4; ++m) _Pragma("unroll") for (int n = 0; n < 2; ++n) _Pragma("unroll") for (int k = 0; k < 2; ++k) \
;         acc[ai][bj][m][n] = __builtin_amdgcn_mfma_f32_16x16x32_bf16(Bt[n][k], At[m][k], acc[ai][bj][m][n], 0, 0, 0); __builtin_amdgcn_s_setprio(0); } while (0)
; #define PG8_WAIT_V(n) asm volatile("s_waitcnt vmcnt(" #n ")" ::: "memory")
; #define PG8_WAIT_L(n) asm volatile("s_waitcnt lgkmcnt(" #n ")" ::: "memory")
; #define PG8_BAR __builtin_amdgcn_s_barrier()
; #define PG8_SCHED __builtin_amdgcn_sched_barrier(0)
; template <class Epi, class Sched, bool ALIGN_EPI = false, bool SP2 = false>
; __device__ __forceinline__ void gemm_phase(PG8_LAS unsigned char* lds, const Gemm g, const Sched& S, const Epi& E, const int wv  ) {
;     ...
;             PG8_WAIT_V(8); PG8_WAIT_L(0); PG8_BAR; PG8_MMA(0, 0, At, B0); PG8_MMA(0, 1, At, B1); PG8_BAR; PG8_SCHED;
;             PG8_LDA(At, 0, 1); PG8_STAGE(PG8_SB(0, 0), b2, voffB); PG8_STAGE(PG8_SB(0, 1), b2 + hstep, voffB); PG8_STAGE(PG8_SA(0, 0), a2, voffA);
;             PG8_WAIT_V(8); PG8_WAIT_L(0); PG8_BAR; PG8_MMA(1, 0, At, B0); PG8_MMA(1, 1, At, B1); PG8_BAR; PG8_SCHED;
	s_setprio 1
	s_waitcnt lgkmcnt(0)
	v_mfma_f32_16x16x32_bf16 v[124:127], v[128:131], v[176:179], 0
	v_mfma_f32_16x16x32_bf16 v[120:123], v[136:139], v[176:179], 0
	v_mfma_f32_16x16x32_bf16 v[108:111], v[128:131], v[194:197], 0
	v_mfma_f32_16x16x32_bf16 v[104:107], v[136:139], v[194:197], 0
	v_mfma_f32_16x16x32_bf16 v[92:95], v[128:131], v[202:205], 0
	v_mfma_f32_16x16x32_bf16 v[88:91], v[136:139], v[202:205], 0
	v_mfma_f32_16x16x32_bf16 v[76:79], v[128:131], v[214:217], 0
	v_mfma_f32_16x16x32_bf16 v[72:75], v[136:139], v[214:217], 0
	v_mfma_f32_16x16x32_bf16 v[124:127], v[132:135], v[180:183], v[124:127]
	v_mfma_f32_16x16x32_bf16 v[120:123], v[140:143], v[180:183], v[120:123]
	v_mfma_f32_16x16x32_bf16 v[108:111], v[132:135], v[198:201], v[108:111]
	v_mfma_f32_16x16x32_bf16 v[104:107], v[140:143], v[198:201], v[104:107]
	v_mfma_f32_16x16x32_bf16 v[92:95], v[132:135], v[206:209], v[92:95]
	v_mfma_f32_16x16x32_bf16 v[88:91], v[140:143], v[206:209], v[88:91]
	v_mfma_f32_16x16x32_bf16 v[76:79], v[132:135], v[218:221], v[76:79]
	v_mfma_f32_16x16x32_bf16 v[72:75], v[140:143], v[218:221], v[72:75]
	s_setprio 0
	s_setprio 1
	v_mfma_f32_16x16x32_bf16 v[116:119], v[144:147], v[176:179], 0
	v_mfma_f32_16x16x32_bf16 v[112:115], v[168:171], v[176:179], 0
	v_mfma_f32_16x16x32_bf16 v[100:103], v[144:147], v[194:197], 0
	v_mfma_f32_16x16x32_bf16 v[96:99], v[168:171], v[194:197], 0
	v_mfma_f32_16x16x32_bf16 v[84:87], v[144:147], v[202:205], 0
	v_mfma_f32_16x16x32_bf16 v[80:83], v[168:171], v[202:205], 0
	v_mfma_f32_16x16x32_bf16 v[68:71], v[144:147], v[214:217], 0
	v_mfma_f32_16x16x32_bf16 v[64:67], v[168:171], v[214:217], 0
	v_mfma_f32_16x16x32_bf16 v[116:119], v[148:151], v[180:183], v[116:119]
	v_mfma_f32_16x16x32_bf16 v[112:115], v[172:175], v[180:183], v[112:115]
	v_mfma_f32_16x16x32_bf16 v[100:103], v[148:151], v[198:201], v[100:103]
	v_mfma_f32_16x16x32_bf16 v[96:99], v[172:175], v[198:201], v[96:99]
	v_mfma_f32_16x16x32_bf16 v[84:87], v[148:151], v[206:209], v[84:87]
	v_mfma_f32_16x16x32_bf16 v[80:83], v[172:175], v[206:209], v[80:83]
	v_mfma_f32_16x16x32_bf16 v[68:71], v[148:151], v[218:221], v[68:71]
	v_mfma_f32_16x16x32_bf16 v[64:67], v[172:175], v[218:221], v[64:67]
	s_setprio 0
	s_barrier
	s_add_i32 s58, s51, s33
	v_lshl_add_u64 v[184:185], s[38:39], 0, v[154:155]
	s_mov_b32 m0, s58
	ds_read_b128 v[176:179], v193 offset:16384
	ds_read_b128 v[180:183], v193 offset:17408
	ds_read_b128 v[194:197], v193 offset:18432
	ds_read_b128 v[198:201], v193 offset:19456
	ds_read_b128 v[202:205], v193 offset:20480
	ds_read_b128 v[206:209], v193 offset:21504
	ds_read_b128 v[214:217], v193 offset:22528
	ds_read_b128 v[218:221], v193 offset:23552
	global_load_lds_dwordx4 v[184:185], off
	s_add_i32 m0, s58, 0x2000
	s_add_u32 s58, s38, 0x100000
	v_lshl_add_u64 v[210:211], s[38:39], 0, v[158:159]
	s_addc_u32 s59, s39, 0
	s_add_i32 s60, s52, s33
	global_load_lds_dwordx4 v[210:211], off
	v_lshl_add_u64 v[222:223], s[58:59], 0, v[154:155]
	s_mov_b32 m0, s60
	v_lshl_add_u64 v[224:225], s[40:41], 0, v[156:157]
	global_load_lds_dwordx4 v[222:223], off
	v_lshl_add_u64 v[222:223], s[58:59], 0, v[158:159]
	s_add_i32 m0, s60, 0x2000
	s_nop 0
	global_load_lds_dwordx4 v[222:223], off
	v_lshl_add_u64 v[222:223], s[40:41], 0, v[152:153]
	s_mov_b32 m0, s42
	s_nop 0
	global_load_lds_dwordx4 v[222:223], off
	s_mov_b32 m0, s43
	s_nop 0
	global_load_lds_dwordx4 v[224:225], off
	s_waitcnt vmcnt(8)
	s_waitcnt lgkmcnt(0)
	s_barrier
	s_setprio 1
	s_waitcnt lgkmcnt(0)
	v_mfma_f32_16x16x32_bf16 v[60:63], v[128:131], v[176:179], 0
	v_mfma_f32_16x16x32_bf16 v[56:59], v[136:139], v[176:179], 0
	v_mfma_f32_16x16x32_bf16 v[44:47], v[128:131], v[194:197], 0
	v_mfma_f32_16x16x32_bf16 v[40:43], v[136:139], v[194:197], 0
	v_mfma_f32_16x16x32_bf16 v[28:31], v[128:131], v[202:205], 0
	v_mfma_f32_16x16x32_bf16 v[24:27], v[136:139], v[202:205], 0
	v_mfma_f32_16x16x32_bf16 v[12:15], v[128:131], v[214:217], 0
	v_mfma_f32_16x16x32_bf16 v[8:11], v[136:139], v[214:217], 0
	v_mfma_f32_16x16x32_bf16 v[60:63], v[132:135], v[180:183], v[60:63]
	v_mfma_f32_16x16x32_bf16 v[56:59], v[140:143], v[180:183], v[56:59]
	v_mfma_f32_16x16x32_bf16 v[44:47], v[132:135], v[198:201], v[44:47]
	v_mfma_f32_16x16x32_bf16 v[40:43], v[140:143], v[198:201], v[40:43]
	v_mfma_f32_16x16x32_bf16 v[28:31], v[132:135], v[206:209], v[28:31]
	v_mfma_f32_16x16x32_bf16 v[24:27], v[140:143], v[206:209], v[24:27]
	v_mfma_f32_16x16x32_bf16 v[12:15], v[132:135], v[218:221], v[12:15]
	v_mfma_f32_16x16x32_bf16 v[8:11], v[140:143], v[218:221], v[8:11]
	s_setprio 0
	s_setprio 1
	v_mfma_f32_16x16x32_bf16 v[52:55], v[144:147], v[176:179], 0
	v_mfma_f32_16x16x32_bf16 v[48:51], v[168:171], v[176:179], 0
	v_mfma_f32_16x16x32_bf16 v[36:39], v[144:147], v[194:197], 0
	v_mfma_f32_16x16x32_bf16 v[32:35], v[168:171], v[194:197], 0
	v_mfma_f32_16x16x32_bf16 v[20:23], v[144:147], v[202:205], 0
	v_mfma_f32_16x16x32_bf16 v[16:19], v[168:171], v[202:205], 0
	v_mfma_f32_16x16x32_bf16 v[4:7], v[144:147], v[214:217], 0
	v_mfma_f32_16x16x32_bf16 v[0:3], v[168:171], v[214:217], 0
	v_mfma_f32_16x16x32_bf16 v[52:55], v[148:151], v[180:183], v[52:55]
	v_mfma_f32_16x16x32_bf16 v[48:51], v[172:175], v[180:183], v[48:51]
	v_mfma_f32_16x16x32_bf16 v[36:39], v[148:151], v[198:201], v[36:39]
	v_mfma_f32_16x16x32_bf16 v[32:35], v[172:175], v[198:201], v[32:35]
	v_mfma_f32_16x16x32_bf16 v[20:23], v[148:151], v[206:209], v[20:23]
	v_mfma_f32_16x16x32_bf16 v[16:19], v[172:175], v[206:209], v[16:19]
	v_mfma_f32_16x16x32_bf16 v[4:7], v[148:151], v[218:221], v[4:7]
	v_mfma_f32_16x16x32_bf16 v[0:3], v[172:175], v[218:221], v[0:3]
	s_setprio 0
	s_barrier
; #define PG8_STAGE(bufoff, gbase, voff) do { _Pragma("unroll") for (int _i = 0; _i < 2; ++_i) \
;         __builtin_amdgcn_global_load_lds((const unsigned*)((const char*)(gbase) + (voff)[_i]), (PG8_LAS unsigned*)(lds + (bufoff) + ldsw + _i * 8192), 16, 0, 0); } while (0)
; #define PG8_LDA(dst, b, h) do { _Pragma("unroll") for (int m = 0; m < 4; ++m) _Pragma("unroll") for (int k = 0; k < 2; ++k) dst[m][k] = *(const PG8_LAS bf16x8*)(lds + PG8_SA(b, h) + aoff + m * 2048 + k * 1024); } while (0)
; #define PG8_LDB(dst, b, h) do { _Pragma("unroll") for (int n = 0; n < 2; ++n) _Pragma("unroll") for (int k = 0; k < 2; ++k) dst[n][k] = *(const PG8_LAS bf16x8*)(lds + PG8_SB(b, h) + boff + n * 2048 + k * 1024); } while (0)
; #define PG8_MMA(ai, bj, At, Bt) do { __builtin_amdgcn_s_setprio(1); _Pragma("unroll") for (int m = 0; m < 4; ++m) _Pragma("unroll") for (int n = 0; n < 2; ++n) _Pragma("unroll") for (int k = 0; k < 2; ++k) \
;         acc[ai][bj][m][n] = __builtin_amdgcn_mfma_f32_16x16x32_bf16(Bt[n][k], At[m][k], acc[ai][bj][m][n], 0, 0, 0); __builtin_amdgcn_s_setprio(0); } while (0)
; #define PG8_WAIT_V(n) asm volatile("s_waitcnt vmcnt(" #n ")" ::: "memory")
; #define PG8_WAIT_L(n) asm volatile("s_waitcnt lgkmcnt(" #n ")" ::: "memory")
; #define PG8_BAR __builtin_amdgcn_s_barrier()
; #define PG8_SCHED __builtin_amdgcn_sched_barrier(0)
; template <class Epi, class Sched, bool ALIGN_EPI = false, bool SP2 = false>
; __device__ __forceinline__ void gemm_phase(PG8_LAS unsigned char* lds, const Gemm g, const Sched& S, const Epi& E, const int wv  ) {
;     ...
;             PG8_LDB(B0, 1, 0); PG8_LDB(B1, 1, 1); PG8_SCHED; PG8_LDA(At, 1, 0); PG8_STAGE(PG8_SA(0, 1), a2 + hstep, voffA);
;             PG8_WAIT_V(8); PG8_WAIT_L(0); PG8_BAR; PG8_MMA(0, 0, At, B0); PG8_MMA(0, 1, At, B1); PG8_BAR; PG8_SCHED;
	s_add_i32 s58, 0, 0x18000
	s_add_i32 s59, 0, 0x1c000
	v_add_u32_e32 v140, s58, v189
	v_add_u32_e32 v172, s59, v189
	ds_read_b128 v[128:131], v140
	ds_read_b128 v[132:135], v140 offset:1024
	ds_read_b128 v[136:139], v140 offset:2048
	ds_read_b128 v[140:143], v140 offset:3072
	ds_read_b128 v[144:147], v172
	ds_read_b128 v[148:151], v172 offset:1024
	ds_read_b128 v[168:171], v172 offset:2048
	ds_read_b128 v[172:175], v172 offset:3072
	s_add_u32 s40, s40, 0x100000
	s_addc_u32 s41, s41, 0
	s_mov_b32 m0, s44
	v_lshl_add_u64 v[226:227], s[40:41], 0, v[152:153]
	ds_read_b128 v[176:179], v193 offset:32768
	ds_read_b128 v[180:183], v193 offset:33792
	ds_read_b128 v[194:197], v193 offset:34816
	ds_read_b128 v[198:201], v193 offset:35840
	ds_read_b128 v[202:205], v193 offset:36864
	ds_read_b128 v[206:209], v193 offset:37888
	ds_read_b128 v[214:217], v193 offset:38912
	ds_read_b128 v[218:221], v193 offset:39936
	global_load_lds_dwordx4 v[226:227], off
	v_lshl_add_u64 v[226:227], s[40:41], 0, v[156:157]
	s_mov_b32 m0, s45
	s_nop 0
	global_load_lds_dwordx4 v[226:227], off
	s_waitcnt vmcnt(8)
	s_waitcnt lgkmcnt(0)
	s_barrier
	s_setprio 1
	s_waitcnt lgkmcnt(0)
	v_mfma_f32_16x16x32_bf16 v[124:127], v[128:131], v[176:179], v[124:127]
	v_mfma_f32_16x16x32_bf16 v[120:123], v[136:139], v[176:179], v[120:123]
	v_mfma_f32_16x16x32_bf16 v[108:111], v[128:131], v[194:197], v[108:111]
	v_mfma_f32_16x16x32_bf16 v[104:107], v[136:139], v[194:197], v[104:107]
	v_mfma_f32_16x16x32_bf16 v[92:95], v[128:131], v[202:205], v[92:95]
	v_mfma_f32_16x16x32_bf16 v[88:91], v[136:139], v[202:205], v[88:91]
	v_mfma_f32_16x16x32_bf16 v[76:79], v[128:131], v[214:217], v[76:79]
	v_mfma_f32_16x16x32_bf16 v[72:75], v[136:139], v[214:217], v[72:75]
	v_mfma_f32_16x16x32_bf16 v[124:127], v[132:135], v[180:183], v[124:127]
	v_mfma_f32_16x16x32_bf16 v[120:123], v[140:143], v[180:183], v[120:123]
	v_mfma_f32_16x16x32_bf16 v[108:111], v[132:135], v[198:201], v[108:111]
	v_mfma_f32_16x16x32_bf16 v[104:107], v[140:143], v[198:201], v[104:107]
	v_mfma_f32_16x16x32_bf16 v[92:95], v[132:135], v[206:209], v[92:95]
	v_mfma_f32_16x16x32_bf16 v[88:91], v[140:143], v[206:209], v[88:91]
	v_mfma_f32_16x16x32_bf16 v[76:79], v[132:135], v[218:221], v[76:79]
	v_mfma_f32_16x16x32_bf16 v[72:75], v[140:143], v[218:221], v[72:75]
	s_setprio 0
	s_setprio 1
	v_mfma_f32_16x16x32_bf16 v[116:119], v[144:147], v[176:179], v[116:119]
	v_mfma_f32_16x16x32_bf16 v[112:115], v[168:171], v[176:179], v[112:115]
	v_mfma_f32_16x16x32_bf16 v[100:103], v[144:147], v[194:197], v[100:103]
	v_mfma_f32_16x16x32_bf16 v[96:99], v[168:171], v[194:197], v[96:99]
	v_mfma_f32_16x16x32_bf16 v[84:87], v[144:147], v[202:205], v[84:87]
	v_mfma_f32_16x16x32_bf16 v[80:83], v[168:171], v[202:205], v[80:83]
	v_mfma_f32_16x16x32_bf16 v[68:71], v[144:147], v[214:217], v[68:71]
	v_mfma_f32_16x16x32_bf16 v[64:67], v[168:171], v[214:217], v[64:67]
	v_mfma_f32_16x16x32_bf16 v[116:119], v[148:151], v[180:183], v[116:119]
	v_mfma_f32_16x16x32_bf16 v[112:115], v[172:175], v[180:183], v[112:115]
	v_mfma_f32_16x16x32_bf16 v[100:103], v[148:151], v[198:201], v[100:103]
	v_mfma_f32_16x16x32_bf16 v[96:99], v[172:175], v[198:201], v[96:99]
	v_mfma_f32_16x16x32_bf16 v[84:87], v[148:151], v[206:209], v[84:87]
	v_mfma_f32_16x16x32_bf16 v[80:83], v[172:175], v[206:209], v[80:83]
	v_mfma_f32_16x16x32_bf16 v[68:71], v[148:151], v[218:221], v[68:71]
	v_mfma_f32_16x16x32_bf16 v[64:67], v[172:175], v[218:221], v[64:67]
	s_setprio 0
	s_barrier
; #define PG8_STAGE(bufoff, gbase, voff) do { _Pragma("unroll") for (int _i = 0; _i < 2; ++_i) \
;         __builtin_amdgcn_global_load_lds((const unsigned*)((const char*)(gbase) + (voff)[_i]), (PG8_LAS unsigned*)(lds + (bufoff) + ldsw + _i * 8192), 16, 0, 0); } while (0)
; #define PG8_LDA(dst, b, h) do { _Pragma("unroll") for (int m = 0; m < 4; ++m) _Pragma("unroll") for (int k = 0; k < 2; ++k) dst[m][k] = *(const PG8_LAS bf16x8*)(lds + PG8_SA(b, h) + aoff + m * 2048 + k * 1024); } while (0)
; #define PG8_MMA(ai, bj, At, Bt) do { __builtin_amdgcn_s_setprio(1); _Pragma("unroll") for (int m = 0; m < 4; ++m) _Pragma("unroll") for (int n = 0; n < 2; ++n) _Pragma("unroll") for (int k = 0; k < 2; ++k) \
;         acc[ai][bj][m][n] = __builtin_amdgcn_mfma_f32_16x16x32_bf16(Bt[n][k], At[m][k], acc[ai][bj][m][n], 0, 0, 0); __builtin_amdgcn_s_setprio(0); } while (0)
; #define PG8_WAIT_V(n) asm volatile("s_waitcnt vmcnt(" #n ")" ::: "memory")
; #define PG8_WAIT_L(n) asm volatile("s_waitcnt lgkmcnt(" #n ")" ::: "memory")
; #define PG8_BAR __builtin_amdgcn_s_barrier()
; #define PG8_SCHED __builtin_amdgcn_sched_barrier(0)
; template <class Epi, class Sched, bool ALIGN_EPI = false, bool SP2 = false>
; __device__ __forceinline__ void gemm_phase(PG8_LAS unsigned char* lds, const Gemm g, const Sched& S, const Epi& E, const int wv  ) {
;     ...
;         for (int t = 0; t < nt; t += 2) {
;     ...
;             PG8_LDA(At, 1, 1); PG8_STAGE(PG8_SB(1, 0), b3, voffB); PG8_STAGE(PG8_SB(1, 1), b3 + hstep, voffB); PG8_STAGE(PG8_SA(1, 0), a3, voffA);
;             PG8_WAIT_V(8); PG8_WAIT_L(0); PG8_BAR; PG8_MMA(1, 0, At, B0); PG8_MMA(1, 1, At, B1); PG8_BAR; PG8_SCHED;
	s_add_i32 s40, s58, s33
	v_lshl_add_u64 v[184:185], v[184:185], 0, s[18:19]
	s_mov_b32 m0, s40
	ds_read_b128 v[176:179], v193 offset:49152
	ds_read_b128 v[180:183], v193 offset:50176
	ds_read_b128 v[194:197], v193 offset:51200
	ds_read_b128 v[198:201], v193 offset:52224
	ds_read_b128 v[202:205], v193 offset:53248
	ds_read_b128 v[206:209], v193 offset:54272
	ds_read_b128 v[214:217], v193 offset:55296
	ds_read_b128 v[218:221], v193 offset:56320
	global_load_lds_dwordx4 v[184:185], off
	s_add_i32 m0, s40, 0x2000
	s_add_u32 s38, s38, 0x100080
	v_lshl_add_u64 v[184:185], v[210:211], 0, s[18:19]
	s_addc_u32 s39, s39, 0
	s_add_i32 s40, s59, s33
	global_load_lds_dwordx4 v[184:185], off
	v_lshl_add_u64 v[184:185], s[38:39], 0, v[154:155]
	s_mov_b32 m0, s40
	s_nop 0
	global_load_lds_dwordx4 v[184:185], off
	v_lshl_add_u64 v[184:185], s[38:39], 0, v[158:159]
	s_add_i32 m0, s40, 0x2000
	s_nop 0
	global_load_lds_dwordx4 v[184:185], off
	v_lshl_add_u64 v[184:185], v[222:223], 0, s[18:19]
	s_mov_b32 m0, s49
	s_nop 0
	global_load_lds_dwordx4 v[184:185], off
	v_lshl_add_u64 v[184:185], v[224:225], 0, s[18:19]
	s_mov_b32 m0, s50
	s_nop 0
	global_load_lds_dwordx4 v[184:185], off
	s_waitcnt vmcnt(8)
	s_waitcnt lgkmcnt(0)
	s_barrier
	s_setprio 1
	s_waitcnt lgkmcnt(0)
	v_mfma_f32_16x16x32_bf16 v[60:63], v[128:131], v[176:179], v[60:63]
	v_mfma_f32_16x16x32_bf16 v[56:59], v[136:139], v[176:179], v[56:59]
	v_mfma_f32_16x16x32_bf16 v[44:47], v[128:131], v[194:197], v[44:47]
	v_mfma_f32_16x16x32_bf16 v[40:43], v[136:139], v[194:197], v[40:43]
	v_mfma_f32_16x16x32_bf16 v[28:31], v[128:131], v[202:205], v[28:31]
	v_mfma_f32_16x16x32_bf16 v[24:27], v[136:139], v[202:205], v[24:27]
	v_mfma_f32_16x16x32_bf16 v[12:15], v[128:131], v[214:217], v[12:15]
	v_mfma_f32_16x16x32_bf16 v[8:11], v[136:139], v[214:217], v[8:11]
	v_mfma_f32_16x16x32_bf16 v[60:63], v[132:135], v[180:183], v[60:63]
	v_mfma_f32_16x16x32_bf16 v[56:59], v[140:143], v[180:183], v[56:59]
	v_mfma_f32_16x16x32_bf16 v[44:47], v[132:135], v[198:201], v[44:47]
	v_mfma_f32_16x16x32_bf16 v[40:43], v[140:143], v[198:201], v[40:43]
	v_mfma_f32_16x16x32_bf16 v[28:31], v[132:135], v[206:209], v[28:31]
	v_mfma_f32_16x16x32_bf16 v[24:27], v[140:143], v[206:209], v[24:27]
	v_mfma_f32_16x16x32_bf16 v[12:15], v[132:135], v[218:221], v[12:15]
	v_mfma_f32_16x16x32_bf16 v[8:11], v[140:143], v[218:221], v[8:11]
	s_setprio 0
	s_setprio 1
	v_mfma_f32_16x16x32_bf16 v[52:55], v[144:147], v[176:179], v[52:55]
	v_mfma_f32_16x16x32_bf16 v[48:51], v[168:171], v[176:179], v[48:51]
	v_mfma_f32_16x16x32_bf16 v[36:39], v[144:147], v[194:197], v[36:39]
	v_mfma_f32_16x16x32_bf16 v[32:35], v[168:171], v[194:197], v[32:35]
	v_mfma_f32_16x16x32_bf16 v[20:23], v[144:147], v[202:205], v[20:23]
	v_mfma_f32_16x16x32_bf16 v[16:19], v[168:171], v[202:205], v[16:19]
	v_mfma_f32_16x16x32_bf16 v[4:7], v[144:147], v[214:217], v[4:7]
	v_mfma_f32_16x16x32_bf16 v[0:3], v[168:171], v[214:217], v[0:3]
	v_mfma_f32_16x16x32_bf16 v[52:55], v[148:151], v[180:183], v[52:55]
	v_mfma_f32_16x16x32_bf16 v[48:51], v[172:175], v[180:183], v[48:51]
	v_mfma_f32_16x16x32_bf16 v[36:39], v[148:151], v[198:201], v[36:39]
	v_mfma_f32_16x16x32_bf16 v[32:35], v[172:175], v[198:201], v[32:35]
	v_mfma_f32_16x16x32_bf16 v[20:23], v[148:151], v[206:209], v[20:23]
	v_mfma_f32_16x16x32_bf16 v[16:19], v[172:175], v[206:209], v[16:19]
	v_mfma_f32_16x16x32_bf16 v[4:7], v[148:151], v[218:221], v[4:7]
	v_mfma_f32_16x16x32_bf16 v[0:3], v[172:175], v[218:221], v[0:3]
	s_setprio 0
	s_barrier
	s_add_i32 s57, s57, 2
	s_add_u32 s36, s36, 0x100
	s_addc_u32 s37, s37, 0
	s_add_u32 s55, s55, 0x100
	s_addc_u32 s56, s56, 0
	s_cmp_gt_u32 s57, 61

;     __device__ __forceinline__ void operator()(const f32x4 (&acc)[2][2][4][2], const Unit& u, int wr, int wc, int fr, int fq) const {
;         const int row0 = u.pm * BM + wr * 64 + fr, col0 = u.pn * BM + wc * 32 + 8 * fq;
; #pragma unroll
;         for (int ai = 0; ai < 2; ++ai) {
;             u32x4 bw[4][2]; f32x4 bf[4][2][2];
; #pragma unroll
;             for (int m = 0; m < 4; ++m)
; #pragma unroll
;                 for (int bj = 0; bj < 2; ++bj) { const size_t off = (size_t)(row0 + ai * HALF + m * 16) * 1024 + col0 + bj * HALF;
;                     if (BASE_BF16) bw[m][bj] = *(const u32x4*)((const bf16_t*)base + off);
;                     else { bf[m][bj][0] = *(const f32x4*)((const float*)base + off); bf[m][bj][1] = *(const f32x4*)((const float*)base + off + 4); } }
; #pragma unroll
;             for (int m = 0; m < 4; ++m) {
;                 const int row = row0 + ai * HALF + m * 16; const size_t off = (size_t)row * 1024 + col0;
;                 float ss = 0.f;
; #pragma unroll
;                 for (int bj = 0; bj < 2; ++bj) {
;                     f32x4 b0, b1;
;                     if (BASE_BF16) { const u32x4 w = bw[m][bj];
;                         b0 = (f32x4){__builtin_bit_cast(float, w.x << 16), __builtin_bit_cast(float, w.x & 0xffff0000u), __builtin_bit_cast(float, w.y << 16), __builtin_bit_cast(float, w.y & 0xffff0000u)};
;                         b1 = (f32x4){__builtin_bit_cast(float, w.z << 16), __builtin_bit_cast(float, w.z & 0xffff0000u), __builtin_bit_cast(float, w.w << 16), __builtin_bit_cast(float, w.w & 0xffff0000u)}; }
;                     else { b0 = bf[m][bj][0]; b1 = bf[m][bj][1]; }
;                     const f32x4 v0 = acc[ai][bj][m][0] + b0, v1 = acc[ai][bj][m][1] + b1;
;                     ss += (v0[0] * v0[0] + v0[1] * v0[1]) + (v0[2] * v0[2] + v0[3] * v0[3]) + (v1[0] * v1[0] + v1[1] * v1[1]) + (v1[2] * v1[2] + v1[3] * v1[3]);
;                     if (OUT_BF16) { u32x4 w; w.x = cvt_pk_bf16(v0[0], v0[1]); w.y = cvt_pk_bf16(v0[2], v0[3]); w.z = cvt_pk_bf16(v1[0], v1[1]); w.w = cvt_pk_bf16(v1[2], v1[3]);
;                         *(u32x4*)((bf16_t*)out + off + bj * HALF) = w; }
;                     else { *(f32x4*)((float*)out + off + bj * HALF) = v0; *(f32x4*)((float*)out + off + bj * HALF + 4) = v1; }
;                 }
;                 ss += __shfl_xor(ss, 16); ss += __shfl_xor(ss, 32);
.LBB0_1459:
	s_add_u32 s60, s35, 0x100080
	s_addc_u32 s61, s27, 0
	v_lshl_add_u64 v[184:185], s[60:61], 0, v[160:161]
	s_add_i32 m0, s42, 0xc000
	s_nop 0
	global_load_lds_dwordx4 v[184:185], off
	v_lshl_add_u64 v[184:185], s[60:61], 0, v[162:163]
	s_add_i32 m0, s42, 0xe000
	s_nop 0
	global_load_lds_dwordx4 v[184:185], off
	v_lshl_or_b32 v168, s8, 8, v190
	v_lshl_add_u32 v172, s34, 8, v188
	v_ashrrev_i32_e32 v169, 31, v168
	v_lshlrev_b64 v[202:203], 1, v[168:169]
	v_ashrrev_i32_e32 v173, 31, v172
	v_lshl_add_u64 v[170:171], s[12:13], 0, v[202:203]
	v_lshlrev_b64 v[204:205], 11, v[172:173]
	v_lshl_add_u64 v[128:129], v[170:171], 0, v[204:205]
	global_load_dwordx4 v[194:197], v[128:129], off
	global_load_dwordx4 v[198:201], v[128:129], off offset:256
	v_or_b32_e32 v182, 16, v172
	v_or_b32_e32 v178, 32, v172
	v_or_b32_e32 v174, 48, v172
	v_ashrrev_i32_e32 v183, 31, v182
	v_ashrrev_i32_e32 v179, 31, v178
	v_ashrrev_i32_e32 v175, 31, v174
	v_lshlrev_b64 v[184:185], 11, v[182:183]
	v_lshlrev_b64 v[180:181], 11, v[178:179]
	v_lshlrev_b64 v[176:177], 11, v[174:175]
	v_lshl_add_u64 v[128:129], v[170:171], 0, v[184:185]
	v_lshl_add_u64 v[130:131], v[170:171], 0, v[180:181]
	v_lshl_add_u64 v[206:207], v[170:171], 0, v[176:177]
	global_load_dwordx4 v[148:151], v[128:129], off
	global_load_dwordx4 v[144:147], v[128:129], off offset:256
	global_load_dwordx4 v[140:143], v[130:131], off
	global_load_dwordx4 v[136:139], v[130:131], off offset:256
	global_load_dwordx4 v[132:135], v[206:207], off
	s_nop 0
	global_load_dwordx4 v[128:131], v[206:207], off offset:256
	s_lshl_b32 s34, s8, 2
	s_ashr_i32 s35, s34, 31
	s_waitcnt vmcnt(0)
	v_lshlrev_b32_e32 v206, 16, v194
	v_and_b32_e32 v207, 0xffff0000, v194
	v_lshlrev_b32_e32 v194, 16, v195
	v_and_b32_e32 v195, 0xffff0000, v195
	v_lshlrev_b32_e32 v208, 16, v196
	v_and_b32_e32 v209, 0xffff0000, v196
	v_lshlrev_b32_e32 v196, 16, v197
	v_and_b32_e32 v197, 0xffff0000, v197
	v_lshlrev_b32_e32 v210, 16, v198
	v_and_b32_e32 v211, 0xffff0000, v198
	v_lshlrev_b32_e32 v198, 16, v199
	v_and_b32_e32 v199, 0xffff0000, v199
	v_lshlrev_b32_e32 v214, 16, v200
	v_and_b32_e32 v215, 0xffff0000, v200
	v_lshlrev_b32_e32 v200, 16, v201
	v_and_b32_e32 v201, 0xffff0000, v201
	v_pk_add_f32 v[126:127], v[126:127], v[194:195]
	v_pk_add_f32 v[124:125], v[124:125], v[206:207]
	v_pk_add_f32 v[122:123], v[122:123], v[196:197]
	v_pk_add_f32 v[120:121], v[120:121], v[208:209]
	v_pk_add_f32 v[118:119], v[118:119], v[198:199]
	v_pk_add_f32 v[116:117], v[116:117], v[210:211]
	v_pk_add_f32 v[194:195], v[114:115], v[200:201]
	v_pk_add_f32 v[196:197], v[112:113], v[214:215]
	v_mul_f32_e32 v198, v125, v125
	v_mul_f32_e32 v199, v127, v127
	v_mul_f32_e32 v200, v121, v121
	v_mul_f32_e32 v201, v123, v123
	v_cvt_pk_bf16_f32 v112, v124, v125
	v_cvt_pk_bf16_f32 v113, v126, v127
	v_cvt_pk_bf16_f32 v114, v120, v121
	v_cvt_pk_bf16_f32 v115, v122, v123
	v_mul_f32_e32 v121, v117, v117
	v_mul_f32_e32 v123, v119, v119
	v_mul_f32_e32 v125, v197, v197
	v_fmac_f32_e32 v198, v124, v124
	v_fmac_f32_e32 v199, v126, v126
	v_fmac_f32_e32 v121, v116, v116
	v_fmac_f32_e32 v123, v118, v118
	v_mul_f32_e32 v127, v195, v195
	v_fmac_f32_e32 v200, v120, v120
	v_fmac_f32_e32 v125, v196, v196
	v_add_f32_e32 v120, v198, v199
	v_add_f32_e32 v121, v121, v123
	v_fmac_f32_e32 v201, v122, v122
	v_fmac_f32_e32 v127, v194, v194
	v_add_f32_e32 v120, v200, v120
	v_add_f32_e32 v121, v125, v121
	v_add_f32_e32 v120, v201, v120
	v_add_f32_e32 v121, v127, v121
	v_add_f32_e32 v122, v120, v121
	ds_bpermute_b32 v123, v186, v122
	v_lshl_add_u64 v[120:121], s[14:15], 0, v[204:205]
	v_lshl_add_u64 v[120:121], v[120:121], 0, v[202:203]
	ds_bpermute_b32 v240, v253, v112
	ds_bpermute_b32 v241, v253, v113
	ds_bpermute_b32 v242, v253, v114
	ds_bpermute_b32 v243, v253, v115
	v_lshl_add_u64 v[236:237], v[120:121], 0, v[250:251]
	s_waitcnt lgkmcnt(4)
	s_nop 0
	v_add_f32_e32 v112, v122, v123
	ds_bpermute_b32 v113, v187, v112
	v_cvt_pk_bf16_f32 v114, v116, v117
	v_cvt_pk_bf16_f32 v115, v118, v119
	v_cvt_pk_bf16_f32 v116, v196, v197
	v_cvt_pk_bf16_f32 v117, v194, v195
	ds_bpermute_b32 v244, v253, v114
	ds_bpermute_b32 v245, v253, v115
	ds_bpermute_b32 v246, v253, v116
	ds_bpermute_b32 v247, v253, v117
	v_lshl_add_u64 v[238:239], v[120:121], 0, v[250:251]
	s_waitcnt lgkmcnt(4)
	global_store_dwordx4 v[236:237], v[240:243], off
	s_and_saveexec_b64 s[36:37], s[4:5]
	s_cbranch_execz .LBB0_1461
	v_lshlrev_b64 v[114:115], 6, v[172:173]
	v_lshl_add_u64 v[114:115], s[16:17], 0, v[114:115]
	v_lshl_add_u64 v[114:115], s[34:35], 2, v[114:115]
	s_lshl_b32 s8, s48, 2
	v_lshl_add_u64 v[114:115], v[114:115], 0, s[8:9]
	s_waitcnt lgkmcnt(4)
	v_add_f32_e32 v112, v112, v113
	global_store_dword v[114:115], v112, off
